# v44 + GEMM K-loops: 67 LDS-DMA pieces issued in the SGPR-base + 32-bit lane-offset form (their 64-bit VALU address adds removed)
# speedup vs baseline: 1.0071x; 1.0071x over previous
; #define PG8_STAGE(bufoff, gbase, voff) do { _Pragma("unroll") for (int _i = 0; _i < 2; ++_i) \
;         __builtin_amdgcn_global_load_lds((const unsigned*)((const char*)(gbase) + (voff)[_i]), (PG8_LAS unsigned*)(lds + (bufoff) + ldsw + _i * 8192), 16, 0, 0); } while (0)
; #define PG8_LDA(dst, b, h) do { _Pragma("unroll") for (int m = 0; m < 4; ++m) _Pragma("unroll") for (int k = 0; k < 2; ++k) dst[m][k] = *(const PG8_LAS bf16x8*)(lds + PG8_SA(b, h) + aoff + m * 2048 + k * 1024); } while (0)
; #define PG8_LDB(dst, b, h) do { _Pragma("unroll") for (int n = 0; n < 2; ++n) _Pragma("unroll") for (int k = 0; k < 2; ++k) dst[n][k] = *(const PG8_LAS bf16x8*)(lds + PG8_SB(b, h) + boff + n * 2048 + k * 1024); } while (0)
; template <class Epi, class Sched, bool ALIGN_EPI = false, bool SP2 = false>
; __device__ __forceinline__ void gemm_phase(PG8_LAS unsigned char* lds, const Gemm g, const Sched& S, const Epi& E) {
;     ...
;         for (int t = 0; t < nt; t += 2) {
;             const bool last = (t == nt - 2);
;             const char* a1 = cA + (size_t)(t + 1) * kstep;
;             const char* a2 = last ? nA : cA + (size_t)(t + 2) * kstep; const char* b2 = last ? nB : cB + (size_t)(t + 2) * kstep;
;             const char* a3 = a2 + kstep; const char* b3 = b2 + kstep;
;             if (last && has_next) S.a_ready(nxt);
;             if constexpr (SP2) {
;             PG8_LDB(B0, 0, 0); PG8_LDB(B1, 0, 1); PG8_SCHED; PG8_LDA(At, 0, 0); PG8_STAGE(PG8_SA(1, 1), a1 + hstepA, voffA);
;             PG8_WAIT_V(8); PG8_WAIT_L(0); PG8_BAR; PG8_MMA(0, 0, At, B0); PG8_MMA(0, 1, At, B1); PG8_BAR; PG8_SCHED;
;             PG8_LDA(At, 0, 1); PG8_STAGE(PG8_SB(0, 0), b2, voffB); PG8_STAGE(PG8_SB(0, 1), b2 + hstepB, voffB); PG8_STAGE(PG8_SA(0, 0), a2, voffA);
;             PG8_WAIT_V(8); PG8_WAIT_L(0); PG8_BAR; PG8_MMA(1, 0, At, B0); PG8_MMA(1, 1, At, B1); PG8_BAR; PG8_SCHED;
;             PG8_LDB(B0, 1, 0); PG8_LDB(B1, 1, 1); PG8_SCHED; PG8_LDA(At, 1, 0); PG8_STAGE(PG8_SA(0, 1), a2 + hstepA, voffA);
;             PG8_WAIT_V(8); PG8_WAIT_L(0); PG8_BAR; PG8_MMA(0, 0, At, B0); PG8_MMA(0, 1, At, B1); PG8_BAR; PG8_SCHED;
;             PG8_LDA(At, 1, 1); PG8_STAGE(PG8_SB(1, 0), b3, voffB); PG8_STAGE(PG8_SB(1, 1), b3 + hstepB, voffB); PG8_STAGE(PG8_SA(1, 0), a3, voffA);
;             PG8_WAIT_V(8); PG8_WAIT_L(0); PG8_BAR; PG8_MMA(1, 0, At, B0); PG8_MMA(1, 1, At, B1); PG8_BAR; PG8_SCHED;
.LBB0_275:
	s_add_u32 s28, s26, 0xfffc0080
	s_addc_u32 s29, s27, -1
	s_add_i32 s51, 0, 0x10000
	s_cmp_eq_u32 s50, 12
	s_cselect_b32 s31, s9, s29
	s_cselect_b32 s30, s21, s28
	s_cselect_b32 s29, s19, s47
	s_cselect_b32 s28, s45, s46
	s_add_i32 s56, 0, 0x14000
	v_add_u32_e32 v44, s51, v163
	v_add_u32_e32 v158, s56, v163
	ds_read_b128 v[24:27], v44
	ds_read_b128 v[28:31], v44 offset:1024
	ds_read_b128 v[36:39], v44 offset:2048
	ds_read_b128 v[44:47], v44 offset:3072
	ds_read_b128 v[154:157], v158
	ds_read_b128 v[166:169], v158 offset:1024
	ds_read_b128 v[174:177], v158 offset:2048
	ds_read_b128 v[178:181], v158 offset:3072
	s_add_i32 m0, s3, 0xc000
	ds_read_b128 v[182:185], v165
	ds_read_b128 v[192:195], v165 offset:1024
	ds_read_b128 v[196:199], v165 offset:2048
	ds_read_b128 v[200:203], v165 offset:3072
	ds_read_b128 v[204:207], v165 offset:4096
	ds_read_b128 v[208:211], v165 offset:5120
	ds_read_b128 v[212:215], v165 offset:6144
	ds_read_b128 v[216:219], v165 offset:7168
	global_load_lds_dwordx4 v150, s[26:27]
	s_add_i32 m0, s3, 0xe000
	s_nop 0
	global_load_lds_dwordx4 v152, s[26:27]
	s_waitcnt vmcnt(8)
	s_waitcnt lgkmcnt(0)
	s_barrier
	s_setprio 1
	s_waitcnt lgkmcnt(0)
	v_mfma_f32_16x16x32_bf16 v[140:143], v[24:27], v[182:185], v[140:143]
	v_mfma_f32_16x16x32_bf16 v[136:139], v[36:39], v[182:185], v[136:139]
	v_mfma_f32_16x16x32_bf16 v[124:127], v[24:27], v[196:199], v[124:127]
	v_mfma_f32_16x16x32_bf16 v[120:123], v[36:39], v[196:199], v[120:123]
	v_mfma_f32_16x16x32_bf16 v[108:111], v[24:27], v[204:207], v[108:111]
	v_mfma_f32_16x16x32_bf16 v[104:107], v[36:39], v[204:207], v[104:107]
	v_mfma_f32_16x16x32_bf16 v[92:95], v[24:27], v[212:215], v[92:95]
	v_mfma_f32_16x16x32_bf16 v[88:91], v[36:39], v[212:215], v[88:91]
	v_mfma_f32_16x16x32_bf16 v[140:143], v[28:31], v[192:195], v[140:143]
	v_mfma_f32_16x16x32_bf16 v[136:139], v[44:47], v[192:195], v[136:139]
	v_mfma_f32_16x16x32_bf16 v[124:127], v[28:31], v[200:203], v[124:127]
	v_mfma_f32_16x16x32_bf16 v[120:123], v[44:47], v[200:203], v[120:123]
	v_mfma_f32_16x16x32_bf16 v[108:111], v[28:31], v[208:211], v[108:111]
	v_mfma_f32_16x16x32_bf16 v[104:107], v[44:47], v[208:211], v[104:107]
	v_mfma_f32_16x16x32_bf16 v[92:95], v[28:31], v[216:219], v[92:95]
	v_mfma_f32_16x16x32_bf16 v[88:91], v[44:47], v[216:219], v[88:91]
	s_setprio 0
	s_setprio 1
	v_mfma_f32_16x16x32_bf16 v[132:135], v[154:157], v[182:185], v[132:135]
	v_mfma_f32_16x16x32_bf16 v[128:131], v[174:177], v[182:185], v[128:131]
	v_mfma_f32_16x16x32_bf16 v[116:119], v[154:157], v[196:199], v[116:119]
	v_mfma_f32_16x16x32_bf16 v[112:115], v[174:177], v[196:199], v[112:115]
	v_mfma_f32_16x16x32_bf16 v[100:103], v[154:157], v[204:207], v[100:103]
	v_mfma_f32_16x16x32_bf16 v[96:99], v[174:177], v[204:207], v[96:99]
	v_mfma_f32_16x16x32_bf16 v[84:87], v[154:157], v[212:215], v[84:87]
	v_mfma_f32_16x16x32_bf16 v[80:83], v[174:177], v[212:215], v[80:83]
	v_mfma_f32_16x16x32_bf16 v[132:135], v[166:169], v[192:195], v[132:135]
	v_mfma_f32_16x16x32_bf16 v[128:131], v[178:181], v[192:195], v[128:131]
	v_mfma_f32_16x16x32_bf16 v[116:119], v[166:169], v[200:203], v[116:119]
	v_mfma_f32_16x16x32_bf16 v[112:115], v[178:181], v[200:203], v[112:115]
	v_mfma_f32_16x16x32_bf16 v[100:103], v[166:169], v[208:211], v[100:103]
	v_mfma_f32_16x16x32_bf16 v[96:99], v[178:181], v[208:211], v[96:99]
	v_mfma_f32_16x16x32_bf16 v[84:87], v[166:169], v[216:219], v[84:87]
	v_mfma_f32_16x16x32_bf16 v[80:83], v[178:181], v[216:219], v[80:83]
	s_setprio 0
	s_barrier
	s_add_i32 s51, s51, s2
	v_lshl_add_u64 v[160:161], s[28:29], 0, v[172:173]
	s_mov_b32 m0, s51
	ds_read_b128 v[182:185], v165 offset:16384
	ds_read_b128 v[192:195], v165 offset:17408
	ds_read_b128 v[196:199], v165 offset:18432
	ds_read_b128 v[200:203], v165 offset:19456
	ds_read_b128 v[204:207], v165 offset:20480
	ds_read_b128 v[208:211], v165 offset:21504
	ds_read_b128 v[212:215], v165 offset:22528
	ds_read_b128 v[216:219], v165 offset:23552
	global_load_lds_dwordx4 v[160:161], off
	s_add_i32 m0, s51, 0x2000
	s_add_u32 s52, s28, 0x10000
	v_lshl_add_u64 v[170:171], s[28:29], 0, v[148:149]
	s_addc_u32 s53, s29, 0
	s_add_i32 s51, s56, s2
	global_load_lds_dwordx4 v[170:171], off
	s_mov_b32 m0, s51
	v_lshl_add_u64 v[220:221], s[30:31], 0, v[146:147]
	global_load_lds_dwordx4 v172, s[52:53]
	s_add_i32 m0, s51, 0x2000
	s_nop 0
	global_load_lds_dwordx4 v148, s[52:53]
	v_lshl_add_u64 v[186:187], s[30:31], 0, v[144:145]
	s_mov_b32 m0, s3
	s_nop 0
	global_load_lds_dwordx4 v[186:187], off
	s_mov_b32 m0, s25
	s_nop 0
	global_load_lds_dwordx4 v[220:221], off
	s_waitcnt vmcnt(8)
	s_waitcnt lgkmcnt(0)
	s_barrier
; #define PG8_STAGE(bufoff, gbase, voff) do { _Pragma("unroll") for (int _i = 0; _i < 2; ++_i) \
;         __builtin_amdgcn_global_load_lds((const unsigned*)((const char*)(gbase) + (voff)[_i]), (PG8_LAS unsigned*)(lds + (bufoff) + ldsw + _i * 8192), 16, 0, 0); } while (0)
; #define PG8_LDA(dst, b, h) do { _Pragma("unroll") for (int m = 0; m < 4; ++m) _Pragma("unroll") for (int k = 0; k < 2; ++k) dst[m][k] = *(const PG8_LAS bf16x8*)(lds + PG8_SA(b, h) + aoff + m * 2048 + k * 1024); } while (0)
; #define PG8_LDB(dst, b, h) do { _Pragma("unroll") for (int n = 0; n < 2; ++n) _Pragma("unroll") for (int k = 0; k < 2; ++k) dst[n][k] = *(const PG8_LAS bf16x8*)(lds + PG8_SB(b, h) + boff + n * 2048 + k * 1024); } while (0)
; #define PG8_MMA(ai, bj, At, Bt) do { __builtin_amdgcn_s_setprio(1); _Pragma("unroll") for (int m = 0; m < 4; ++m) _Pragma("unroll") for (int n = 0; n < 2; ++n) _Pragma("unroll") for (int k = 0; k < 2; ++k) \
;         acc[ai][bj][m][n] = __builtin_amdgcn_mfma_f32_16x16x32_bf16(Bt[n][k], At[m][k], acc[ai][bj][m][n], 0, 0, 0); __builtin_amdgcn_s_setprio(0); } while (0)
; template <class Epi, class Sched, bool ALIGN_EPI = false, bool SP2 = false>
; __device__ __forceinline__ void gemm_phase(PG8_LAS unsigned char* lds, const Gemm g, const Sched& S, const Epi& E) {
;     ...
;             if constexpr (SP2) {
;             PG8_LDB(B0, 0, 0); PG8_LDB(B1, 0, 1); PG8_SCHED; PG8_LDA(At, 0, 0); PG8_STAGE(PG8_SA(1, 1), a1 + hstepA, voffA);
;             PG8_WAIT_V(8); PG8_WAIT_L(0); PG8_BAR; PG8_MMA(0, 0, At, B0); PG8_MMA(0, 1, At, B1); PG8_BAR; PG8_SCHED;
;             PG8_LDA(At, 0, 1); PG8_STAGE(PG8_SB(0, 0), b2, voffB); PG8_STAGE(PG8_SB(0, 1), b2 + hstepB, voffB); PG8_STAGE(PG8_SA(0, 0), a2, voffA);
;             PG8_WAIT_V(8); PG8_WAIT_L(0); PG8_BAR; PG8_MMA(1, 0, At, B0); PG8_MMA(1, 1, At, B1); PG8_BAR; PG8_SCHED;
;             PG8_LDB(B0, 1, 0); PG8_LDB(B1, 1, 1); PG8_SCHED; PG8_LDA(At, 1, 0); PG8_STAGE(PG8_SA(0, 1), a2 + hstepA, voffA);
;             PG8_WAIT_V(8); PG8_WAIT_L(0); PG8_BAR; PG8_MMA(0, 0, At, B0); PG8_MMA(0, 1, At, B1); PG8_BAR; PG8_SCHED;
;             PG8_LDA(At, 1, 1); PG8_STAGE(PG8_SB(1, 0), b3, voffB); PG8_STAGE(PG8_SB(1, 1), b3 + hstepB, voffB); PG8_STAGE(PG8_SA(1, 0), a3, voffA);
;             PG8_WAIT_V(8); PG8_WAIT_L(0); PG8_BAR; PG8_MMA(1, 0, At, B0); PG8_MMA(1, 1, At, B1); PG8_BAR; PG8_SCHED;
	s_setprio 1
	s_waitcnt lgkmcnt(0)
	v_mfma_f32_16x16x32_bf16 v[76:79], v[24:27], v[182:185], v[76:79]
	v_mfma_f32_16x16x32_bf16 v[72:75], v[36:39], v[182:185], v[72:75]
	v_mfma_f32_16x16x32_bf16 v[60:63], v[24:27], v[196:199], v[60:63]
	v_mfma_f32_16x16x32_bf16 v[56:59], v[36:39], v[196:199], v[56:59]
	v_mfma_f32_16x16x32_bf16 v[40:43], v[24:27], v[204:207], v[40:43]
	v_mfma_f32_16x16x32_bf16 v[32:35], v[36:39], v[204:207], v[32:35]
	v_mfma_f32_16x16x32_bf16 v[12:15], v[24:27], v[212:215], v[12:15]
	v_mfma_f32_16x16x32_bf16 v[8:11], v[36:39], v[212:215], v[8:11]
	v_mfma_f32_16x16x32_bf16 v[76:79], v[28:31], v[192:195], v[76:79]
	v_mfma_f32_16x16x32_bf16 v[72:75], v[44:47], v[192:195], v[72:75]
	v_mfma_f32_16x16x32_bf16 v[60:63], v[28:31], v[200:203], v[60:63]
	v_mfma_f32_16x16x32_bf16 v[56:59], v[44:47], v[200:203], v[56:59]
	v_mfma_f32_16x16x32_bf16 v[40:43], v[28:31], v[208:211], v[40:43]
	v_mfma_f32_16x16x32_bf16 v[32:35], v[44:47], v[208:211], v[32:35]
	v_mfma_f32_16x16x32_bf16 v[12:15], v[28:31], v[216:219], v[12:15]
	v_mfma_f32_16x16x32_bf16 v[8:11], v[44:47], v[216:219], v[8:11]
	s_setprio 0
	s_setprio 1
	v_mfma_f32_16x16x32_bf16 v[20:23], v[154:157], v[204:207], v[20:23]
	v_mfma_f32_16x16x32_bf16 v[16:19], v[174:177], v[204:207], v[16:19]
	v_mfma_f32_16x16x32_bf16 v[4:7], v[154:157], v[212:215], v[4:7]
	v_mfma_f32_16x16x32_bf16 v[0:3], v[174:177], v[212:215], v[0:3]
	v_mfma_f32_16x16x32_bf16 v[24:27], v[154:157], v[182:185], v[68:71]
	v_mfma_f32_16x16x32_bf16 v[28:31], v[174:177], v[182:185], v[64:67]
	v_mfma_f32_16x16x32_bf16 v[36:39], v[154:157], v[196:199], v[52:55]
	v_mfma_f32_16x16x32_bf16 v[44:47], v[174:177], v[196:199], v[48:51]
	v_mfma_f32_16x16x32_bf16 v[20:23], v[166:169], v[208:211], v[20:23]
	v_mfma_f32_16x16x32_bf16 v[16:19], v[178:181], v[208:211], v[16:19]
	v_mfma_f32_16x16x32_bf16 v[4:7], v[166:169], v[216:219], v[4:7]
	v_mfma_f32_16x16x32_bf16 v[0:3], v[178:181], v[216:219], v[0:3]
	v_mfma_f32_16x16x32_bf16 v[24:27], v[166:169], v[192:195], v[24:27]
	v_mfma_f32_16x16x32_bf16 v[28:31], v[178:181], v[192:195], v[28:31]
	v_mfma_f32_16x16x32_bf16 v[36:39], v[166:169], v[200:203], v[36:39]
	v_mfma_f32_16x16x32_bf16 v[44:47], v[178:181], v[200:203], v[44:47]
	s_setprio 0
	s_barrier
	s_add_i32 s51, 0, 0x18000
	s_add_i32 s52, 0, 0x1c000
	v_add_u32_e32 v68, s51, v163
	v_add_u32_e32 v158, s52, v163
	ds_read_b128 v[48:51], v68
	ds_read_b128 v[52:55], v68 offset:1024
	ds_read_b128 v[64:67], v68 offset:2048
	ds_read_b128 v[68:71], v68 offset:3072
	ds_read_b128 v[154:157], v158
	ds_read_b128 v[166:169], v158 offset:1024
	ds_read_b128 v[174:177], v158 offset:2048
	ds_read_b128 v[178:181], v158 offset:3072
	s_add_u32 s30, s30, 0x40000
	s_addc_u32 s31, s31, 0
	s_mov_b32 m0, s40
	ds_read_b128 v[182:185], v165 offset:32768
	ds_read_b128 v[192:195], v165 offset:33792
	ds_read_b128 v[196:199], v165 offset:34816
	ds_read_b128 v[200:203], v165 offset:35840
	ds_read_b128 v[204:207], v165 offset:36864
	ds_read_b128 v[208:211], v165 offset:37888
	ds_read_b128 v[212:215], v165 offset:38912
	ds_read_b128 v[216:219], v165 offset:39936
	global_load_lds_dwordx4 v144, s[30:31]
	v_lshl_add_u64 v[222:223], s[30:31], 0, v[146:147]
	s_mov_b32 m0, s41
	s_nop 0
	global_load_lds_dwordx4 v[222:223], off
	s_waitcnt vmcnt(8)
	s_waitcnt lgkmcnt(0)
	s_barrier
	s_setprio 1
	s_waitcnt lgkmcnt(0)
	v_mfma_f32_16x16x32_bf16 v[140:143], v[48:51], v[182:185], v[140:143]
	v_mfma_f32_16x16x32_bf16 v[136:139], v[64:67], v[182:185], v[136:139]
	v_mfma_f32_16x16x32_bf16 v[124:127], v[48:51], v[196:199], v[124:127]
	v_mfma_f32_16x16x32_bf16 v[120:123], v[64:67], v[196:199], v[120:123]
	v_mfma_f32_16x16x32_bf16 v[108:111], v[48:51], v[204:207], v[108:111]
	v_mfma_f32_16x16x32_bf16 v[104:107], v[64:67], v[204:207], v[104:107]
	v_mfma_f32_16x16x32_bf16 v[92:95], v[48:51], v[212:215], v[92:95]
	v_mfma_f32_16x16x32_bf16 v[88:91], v[64:67], v[212:215], v[88:91]
	v_mfma_f32_16x16x32_bf16 v[140:143], v[52:55], v[192:195], v[140:143]
	v_mfma_f32_16x16x32_bf16 v[136:139], v[68:71], v[192:195], v[136:139]
	v_mfma_f32_16x16x32_bf16 v[124:127], v[52:55], v[200:203], v[124:127]
	v_mfma_f32_16x16x32_bf16 v[120:123], v[68:71], v[200:203], v[120:123]
	v_mfma_f32_16x16x32_bf16 v[108:111], v[52:55], v[208:211], v[108:111]
	v_mfma_f32_16x16x32_bf16 v[104:107], v[68:71], v[208:211], v[104:107]
	v_mfma_f32_16x16x32_bf16 v[92:95], v[52:55], v[216:219], v[92:95]
	v_mfma_f32_16x16x32_bf16 v[88:91], v[68:71], v[216:219], v[88:91]
	s_setprio 0
	s_setprio 1
	v_mfma_f32_16x16x32_bf16 v[132:135], v[154:157], v[182:185], v[132:135]
	v_mfma_f32_16x16x32_bf16 v[128:131], v[174:177], v[182:185], v[128:131]
	v_mfma_f32_16x16x32_bf16 v[116:119], v[154:157], v[196:199], v[116:119]
	v_mfma_f32_16x16x32_bf16 v[112:115], v[174:177], v[196:199], v[112:115]
	v_mfma_f32_16x16x32_bf16 v[100:103], v[154:157], v[204:207], v[100:103]
	v_mfma_f32_16x16x32_bf16 v[96:99], v[174:177], v[204:207], v[96:99]
	v_mfma_f32_16x16x32_bf16 v[84:87], v[154:157], v[212:215], v[84:87]
	v_mfma_f32_16x16x32_bf16 v[80:83], v[174:177], v[212:215], v[80:83]
	v_mfma_f32_16x16x32_bf16 v[132:135], v[166:169], v[192:195], v[132:135]
	v_mfma_f32_16x16x32_bf16 v[128:131], v[178:181], v[192:195], v[128:131]
	v_mfma_f32_16x16x32_bf16 v[116:119], v[166:169], v[200:203], v[116:119]
	v_mfma_f32_16x16x32_bf16 v[112:115], v[178:181], v[200:203], v[112:115]
	v_mfma_f32_16x16x32_bf16 v[100:103], v[166:169], v[208:211], v[100:103]
	v_mfma_f32_16x16x32_bf16 v[96:99], v[178:181], v[208:211], v[96:99]
	v_mfma_f32_16x16x32_bf16 v[84:87], v[166:169], v[216:219], v[84:87]
	v_mfma_f32_16x16x32_bf16 v[80:83], v[178:181], v[216:219], v[80:83]
	s_setprio 0
	s_barrier
; #define PG8_STAGE(bufoff, gbase, voff) do { _Pragma("unroll") for (int _i = 0; _i < 2; ++_i) \
;         __builtin_amdgcn_global_load_lds((const unsigned*)((const char*)(gbase) + (voff)[_i]), (PG8_LAS unsigned*)(lds + (bufoff) + ldsw + _i * 8192), 16, 0, 0); } while (0)
; #define PG8_LDA(dst, b, h) do { _Pragma("unroll") for (int m = 0; m < 4; ++m) _Pragma("unroll") for (int k = 0; k < 2; ++k) dst[m][k] = *(const PG8_LAS bf16x8*)(lds + PG8_SA(b, h) + aoff + m * 2048 + k * 1024); } while (0)
; #define PG8_LDB(dst, b, h) do { _Pragma("unroll") for (int n = 0; n < 2; ++n) _Pragma("unroll") for (int k = 0; k < 2; ++k) dst[n][k] = *(const PG8_LAS bf16x8*)(lds + PG8_SB(b, h) + boff + n * 2048 + k * 1024); } while (0)
; #define PG8_MMA(ai, bj, At, Bt) do { __builtin_amdgcn_s_setprio(1); _Pragma("unroll") for (int m = 0; m < 4; ++m) _Pragma("unroll") for (int n = 0; n < 2; ++n) _Pragma("unroll") for (int k = 0; k < 2; ++k) \
;         acc[ai][bj][m][n] = __builtin_amdgcn_mfma_f32_16x16x32_bf16(Bt[n][k], At[m][k], acc[ai][bj][m][n], 0, 0, 0); __builtin_amdgcn_s_setprio(0); } while (0)
; template <class Epi, class Sched, bool ALIGN_EPI = false, bool SP2 = false>
; __device__ __forceinline__ void gemm_phase(PG8_LAS unsigned char* lds, const Gemm g, const Sched& S, const Epi& E) {
;     ...
;             if constexpr (SP2) {
;             PG8_LDB(B0, 0, 0); PG8_LDB(B1, 0, 1); PG8_SCHED; PG8_LDA(At, 0, 0); PG8_STAGE(PG8_SA(1, 1), a1 + hstepA, voffA);
;             PG8_WAIT_V(8); PG8_WAIT_L(0); PG8_BAR; PG8_MMA(0, 0, At, B0); PG8_MMA(0, 1, At, B1); PG8_BAR; PG8_SCHED;
;             PG8_LDA(At, 0, 1); PG8_STAGE(PG8_SB(0, 0), b2, voffB); PG8_STAGE(PG8_SB(0, 1), b2 + hstepB, voffB); PG8_STAGE(PG8_SA(0, 0), a2, voffA);
;             PG8_WAIT_V(8); PG8_WAIT_L(0); PG8_BAR; PG8_MMA(1, 0, At, B0); PG8_MMA(1, 1, At, B1); PG8_BAR; PG8_SCHED;
;             PG8_LDB(B0, 1, 0); PG8_LDB(B1, 1, 1); PG8_SCHED; PG8_LDA(At, 1, 0); PG8_STAGE(PG8_SA(0, 1), a2 + hstepA, voffA);
;             PG8_WAIT_V(8); PG8_WAIT_L(0); PG8_BAR; PG8_MMA(0, 0, At, B0); PG8_MMA(0, 1, At, B1); PG8_BAR; PG8_SCHED;
;             PG8_LDA(At, 1, 1); PG8_STAGE(PG8_SB(1, 0), b3, voffB); PG8_STAGE(PG8_SB(1, 1), b3 + hstepB, voffB); PG8_STAGE(PG8_SA(1, 0), a3, voffA);
;             PG8_WAIT_V(8); PG8_WAIT_L(0); PG8_BAR; PG8_MMA(1, 0, At, B0); PG8_MMA(1, 1, At, B1); PG8_BAR; PG8_SCHED;
	s_add_i32 s30, s51, s2
	v_lshl_add_u64 v[160:161], v[160:161], 0, s[80:81]
	s_mov_b32 m0, s30
	ds_read_b128 v[182:185], v165 offset:49152
	ds_read_b128 v[192:195], v165 offset:50176
	ds_read_b128 v[196:199], v165 offset:51200
	ds_read_b128 v[200:203], v165 offset:52224
	ds_read_b128 v[204:207], v165 offset:53248
	ds_read_b128 v[208:211], v165 offset:54272
	ds_read_b128 v[212:215], v165 offset:55296
	ds_read_b128 v[216:219], v165 offset:56320
	global_load_lds_dwordx4 v[160:161], off
	s_add_i32 m0, s30, 0x2000
	s_add_u32 s28, s28, 0x10080
	v_lshl_add_u64 v[160:161], v[170:171], 0, s[80:81]
	s_addc_u32 s29, s29, 0
	s_add_i32 s30, s52, s2
	global_load_lds_dwordx4 v[160:161], off
	s_mov_b32 m0, s30
	s_nop 0
	global_load_lds_dwordx4 v172, s[28:29]
	s_add_i32 m0, s30, 0x2000
	s_nop 0
	global_load_lds_dwordx4 v148, s[28:29]
	v_lshl_add_u64 v[160:161], v[186:187], 0, s[80:81]
	s_mov_b32 m0, s42
	s_nop 0
	global_load_lds_dwordx4 v[160:161], off
	v_lshl_add_u64 v[160:161], v[220:221], 0, s[80:81]
	s_mov_b32 m0, s43
	s_nop 0
	global_load_lds_dwordx4 v[160:161], off
	s_waitcnt vmcnt(8)
	s_waitcnt lgkmcnt(0)
	s_barrier
	s_setprio 1
	s_waitcnt lgkmcnt(0)
	v_mfma_f32_16x16x32_bf16 v[76:79], v[48:51], v[182:185], v[76:79]
	v_mfma_f32_16x16x32_bf16 v[72:75], v[64:67], v[182:185], v[72:75]
	v_mfma_f32_16x16x32_bf16 v[60:63], v[48:51], v[196:199], v[60:63]
	v_mfma_f32_16x16x32_bf16 v[56:59], v[64:67], v[196:199], v[56:59]
	v_mfma_f32_16x16x32_bf16 v[40:43], v[48:51], v[204:207], v[40:43]
	v_mfma_f32_16x16x32_bf16 v[32:35], v[64:67], v[204:207], v[32:35]
	v_mfma_f32_16x16x32_bf16 v[12:15], v[48:51], v[212:215], v[12:15]
	v_mfma_f32_16x16x32_bf16 v[8:11], v[64:67], v[212:215], v[8:11]
	v_mfma_f32_16x16x32_bf16 v[76:79], v[52:55], v[192:195], v[76:79]
	v_mfma_f32_16x16x32_bf16 v[72:75], v[68:71], v[192:195], v[72:75]
	v_mfma_f32_16x16x32_bf16 v[60:63], v[52:55], v[200:203], v[60:63]
	v_mfma_f32_16x16x32_bf16 v[56:59], v[68:71], v[200:203], v[56:59]
	v_mfma_f32_16x16x32_bf16 v[40:43], v[52:55], v[208:211], v[40:43]
	v_mfma_f32_16x16x32_bf16 v[32:35], v[68:71], v[208:211], v[32:35]
	v_mfma_f32_16x16x32_bf16 v[12:15], v[52:55], v[216:219], v[12:15]
	v_mfma_f32_16x16x32_bf16 v[8:11], v[68:71], v[216:219], v[8:11]
	s_setprio 0
	s_setprio 1
	v_mfma_f32_16x16x32_bf16 v[24:27], v[154:157], v[182:185], v[24:27]
	v_mfma_f32_16x16x32_bf16 v[68:71], v[166:169], v[192:195], v[24:27]
	v_mfma_f32_16x16x32_bf16 v[24:27], v[174:177], v[182:185], v[28:31]
	v_mfma_f32_16x16x32_bf16 v[64:67], v[178:181], v[192:195], v[24:27]
	v_mfma_f32_16x16x32_bf16 v[24:27], v[154:157], v[196:199], v[36:39]
	v_mfma_f32_16x16x32_bf16 v[52:55], v[166:169], v[200:203], v[24:27]
	v_mfma_f32_16x16x32_bf16 v[24:27], v[174:177], v[196:199], v[44:47]
	v_mfma_f32_16x16x32_bf16 v[20:23], v[154:157], v[204:207], v[20:23]
	v_mfma_f32_16x16x32_bf16 v[16:19], v[174:177], v[204:207], v[16:19]
	v_mfma_f32_16x16x32_bf16 v[4:7], v[154:157], v[212:215], v[4:7]
	v_mfma_f32_16x16x32_bf16 v[0:3], v[174:177], v[212:215], v[0:3]
	v_mfma_f32_16x16x32_bf16 v[48:51], v[178:181], v[200:203], v[24:27]
	v_mfma_f32_16x16x32_bf16 v[20:23], v[166:169], v[208:211], v[20:23]
	v_mfma_f32_16x16x32_bf16 v[16:19], v[178:181], v[208:211], v[16:19]
	v_mfma_f32_16x16x32_bf16 v[4:7], v[166:169], v[216:219], v[4:7]
	v_mfma_f32_16x16x32_bf16 v[0:3], v[178:181], v[216:219], v[0:3]
	s_setprio 0
	s_barrier
	s_add_i32 s50, s50, 2
	s_add_u32 s26, s26, 0x100
	s_addc_u32 s27, s27, 0
	s_add_u32 s46, s46, 0x100
	s_addc_u32 s47, s47, 0
	s_cmp_gt_u32 s50, 13
	s_cbranch_scc0 .LBB0_275
	s_and_b64 vcc, exec, s[16:17]
	s_cbranch_vccz .LBB0_278
	s_barrier

; #define PG8_STAGE(bufoff, gbase, voff) do { _Pragma("unroll") for (int _i = 0; _i < 2; ++_i) \
;         __builtin_amdgcn_global_load_lds((const unsigned*)((const char*)(gbase) + (voff)[_i]), (PG8_LAS unsigned*)(lds + (bufoff) + ldsw + _i * 8192), 16, 0, 0); } while (0)
; #define PG8_LDA(dst, b, h) do { _Pragma("unroll") for (int m = 0; m < 4; ++m) _Pragma("unroll") for (int k = 0; k < 2; ++k) dst[m][k] = *(const PG8_LAS bf16x8*)(lds + PG8_SA(b, h) + aoff + m * 2048 + k * 1024); } while (0)
; #define PG8_LDB(dst, b, h) do { _Pragma("unroll") for (int n = 0; n < 2; ++n) _Pragma("unroll") for (int k = 0; k < 2; ++k) dst[n][k] = *(const PG8_LAS bf16x8*)(lds + PG8_SB(b, h) + boff + n * 2048 + k * 1024); } while (0)
; template <class Epi, class Sched, bool ALIGN_EPI = false, bool SP2 = false>
; __device__ __forceinline__ void gemm_phase(PG8_LAS unsigned char* lds, const Gemm g, const Sched& S, const Epi& E) {
;     ...
;         for (int t = 0; t < nt; t += 2) {
;             const bool last = (t == nt - 2);
;             const char* a1 = cA + (size_t)(t + 1) * kstep;
;             const char* a2 = last ? nA : cA + (size_t)(t + 2) * kstep; const char* b2 = last ? nB : cB + (size_t)(t + 2) * kstep;
;             const char* a3 = a2 + kstep; const char* b3 = b2 + kstep;
;             if (last && has_next) S.a_ready(nxt);
;             if constexpr (SP2) {
;             PG8_LDB(B0, 0, 0); PG8_LDB(B1, 0, 1); PG8_SCHED; PG8_LDA(At, 0, 0); PG8_STAGE(PG8_SA(1, 1), a1 + hstepA, voffA);
;             PG8_WAIT_V(8); PG8_WAIT_L(0); PG8_BAR; PG8_MMA(0, 0, At, B0); PG8_MMA(0, 1, At, B1); PG8_BAR; PG8_SCHED;
;             PG8_LDA(At, 0, 1); PG8_STAGE(PG8_SB(0, 0), b2, voffB); PG8_STAGE(PG8_SB(0, 1), b2 + hstepB, voffB); PG8_STAGE(PG8_SA(0, 0), a2, voffA);
;             PG8_WAIT_V(8); PG8_WAIT_L(0); PG8_BAR; PG8_MMA(1, 0, At, B0); PG8_MMA(1, 1, At, B1); PG8_BAR; PG8_SCHED;
;             PG8_LDB(B0, 1, 0); PG8_LDB(B1, 1, 1); PG8_SCHED; PG8_LDA(At, 1, 0); PG8_STAGE(PG8_SA(0, 1), a2 + hstepA, voffA);
;             PG8_WAIT_V(8); PG8_WAIT_L(0); PG8_BAR; PG8_MMA(0, 0, At, B0); PG8_MMA(0, 1, At, B1); PG8_BAR; PG8_SCHED;
;             PG8_LDA(At, 1, 1); PG8_STAGE(PG8_SB(1, 0), b3, voffB); PG8_STAGE(PG8_SB(1, 1), b3 + hstepB, voffB); PG8_STAGE(PG8_SA(1, 0), a3, voffA);
;             PG8_WAIT_V(8); PG8_WAIT_L(0); PG8_BAR; PG8_MMA(1, 0, At, B0); PG8_MMA(1, 1, At, B1); PG8_BAR; PG8_SCHED;
.LBB0_330:
	s_add_u32 s56, s42, 0xfffc0080
	s_addc_u32 s57, s43, -1
	s_add_i32 s64, 0, 0x10000
	s_cmp_eq_u32 s87, 12
	s_cselect_b32 vcc_hi, s73, s57
	s_cselect_b32 vcc_lo, s75, s56
	s_cselect_b32 s71, s47, s89
	s_cselect_b32 s70, s86, s85
	s_add_i32 s52, 0, 0x14000
	v_add_u32_e32 v150, s64, v171
	v_add_u32_e32 v166, s52, v171
	ds_read_b128 v[138:141], v150
	ds_read_b128 v[142:145], v150 offset:1024
	ds_read_b128 v[146:149], v150 offset:2048
	ds_read_b128 v[150:153], v150 offset:3072
	ds_read_b128 v[154:157], v166
	ds_read_b128 v[158:161], v166 offset:1024
	ds_read_b128 v[162:165], v166 offset:2048
	ds_read_b128 v[166:169], v166 offset:3072
	s_add_i32 m0, s45, 0xc000
	ds_read_b128 v[174:177], v180
	ds_read_b128 v[182:185], v180 offset:1024
	ds_read_b128 v[192:195], v180 offset:2048
	ds_read_b128 v[196:199], v180 offset:3072
	ds_read_b128 v[200:203], v180 offset:4096
	ds_read_b128 v[204:207], v180 offset:5120
	ds_read_b128 v[208:211], v180 offset:6144
	ds_read_b128 v[212:215], v180 offset:7168
	global_load_lds_dwordx4 v134, s[42:43]
	s_add_i32 m0, s45, 0xe000
	s_nop 0
	global_load_lds_dwordx4 v136, s[42:43]
	s_waitcnt vmcnt(8)
	s_waitcnt lgkmcnt(0)
	s_barrier
	s_setprio 1
	s_waitcnt lgkmcnt(0)
	v_mfma_f32_16x16x32_bf16 v[124:127], v[138:141], v[174:177], v[124:127]
	v_mfma_f32_16x16x32_bf16 v[120:123], v[146:149], v[174:177], v[120:123]
	v_mfma_f32_16x16x32_bf16 v[108:111], v[138:141], v[192:195], v[108:111]
	v_mfma_f32_16x16x32_bf16 v[104:107], v[146:149], v[192:195], v[104:107]
	v_mfma_f32_16x16x32_bf16 v[92:95], v[138:141], v[200:203], v[92:95]
	v_mfma_f32_16x16x32_bf16 v[88:91], v[146:149], v[200:203], v[88:91]
	v_mfma_f32_16x16x32_bf16 v[76:79], v[138:141], v[208:211], v[76:79]
	v_mfma_f32_16x16x32_bf16 v[72:75], v[146:149], v[208:211], v[72:75]
	v_mfma_f32_16x16x32_bf16 v[124:127], v[142:145], v[182:185], v[124:127]
	v_mfma_f32_16x16x32_bf16 v[120:123], v[150:153], v[182:185], v[120:123]
	v_mfma_f32_16x16x32_bf16 v[108:111], v[142:145], v[196:199], v[108:111]
	v_mfma_f32_16x16x32_bf16 v[104:107], v[150:153], v[196:199], v[104:107]
	v_mfma_f32_16x16x32_bf16 v[92:95], v[142:145], v[204:207], v[92:95]
	v_mfma_f32_16x16x32_bf16 v[88:91], v[150:153], v[204:207], v[88:91]
	v_mfma_f32_16x16x32_bf16 v[76:79], v[142:145], v[212:215], v[76:79]
	v_mfma_f32_16x16x32_bf16 v[72:75], v[150:153], v[212:215], v[72:75]
	s_setprio 0
	s_setprio 1
	v_mfma_f32_16x16x32_bf16 v[116:119], v[154:157], v[174:177], v[116:119]
	v_mfma_f32_16x16x32_bf16 v[112:115], v[162:165], v[174:177], v[112:115]
	v_mfma_f32_16x16x32_bf16 v[100:103], v[154:157], v[192:195], v[100:103]
	v_mfma_f32_16x16x32_bf16 v[96:99], v[162:165], v[192:195], v[96:99]
	v_mfma_f32_16x16x32_bf16 v[84:87], v[154:157], v[200:203], v[84:87]
	v_mfma_f32_16x16x32_bf16 v[80:83], v[162:165], v[200:203], v[80:83]
	v_mfma_f32_16x16x32_bf16 v[68:71], v[154:157], v[208:211], v[68:71]
	v_mfma_f32_16x16x32_bf16 v[64:67], v[162:165], v[208:211], v[64:67]
	v_mfma_f32_16x16x32_bf16 v[116:119], v[158:161], v[182:185], v[116:119]
	v_mfma_f32_16x16x32_bf16 v[112:115], v[166:169], v[182:185], v[112:115]
	v_mfma_f32_16x16x32_bf16 v[100:103], v[158:161], v[196:199], v[100:103]
	v_mfma_f32_16x16x32_bf16 v[96:99], v[166:169], v[196:199], v[96:99]
	v_mfma_f32_16x16x32_bf16 v[84:87], v[158:161], v[204:207], v[84:87]
	v_mfma_f32_16x16x32_bf16 v[80:83], v[166:169], v[204:207], v[80:83]
	v_mfma_f32_16x16x32_bf16 v[68:71], v[158:161], v[212:215], v[68:71]
	v_mfma_f32_16x16x32_bf16 v[64:67], v[166:169], v[212:215], v[64:67]
	s_setprio 0
	s_barrier
	s_add_i32 s56, s64, s66
	v_lshl_add_u64 v[186:187], s[70:71], 0, v[172:173]
	s_mov_b32 m0, s56
	ds_read_b128 v[174:177], v180 offset:16384
	ds_read_b128 v[182:185], v180 offset:17408
	ds_read_b128 v[192:195], v180 offset:18432
	ds_read_b128 v[196:199], v180 offset:19456
	ds_read_b128 v[200:203], v180 offset:20480
	ds_read_b128 v[204:207], v180 offset:21504
	ds_read_b128 v[208:211], v180 offset:22528
	ds_read_b128 v[212:215], v180 offset:23552
	global_load_lds_dwordx4 v[186:187], off
	s_add_i32 m0, s56, 0x2000
	s_add_u32 s56, s70, 0x40000
	v_lshl_add_u64 v[216:217], s[70:71], 0, v[132:133]
	s_addc_u32 s57, s71, 0
	s_add_i32 s52, s52, s66
	global_load_lds_dwordx4 v[216:217], off
	s_mov_b32 m0, s52
	v_lshl_add_u64 v[220:221], vcc, 0, v[130:131]
	global_load_lds_dwordx4 v172, s[56:57]
	s_add_i32 m0, s52, 0x2000
	s_nop 0
	global_load_lds_dwordx4 v132, s[56:57]
	v_lshl_add_u64 v[218:219], vcc, 0, v[128:129]
	s_mov_b32 m0, s45
	s_nop 0
	global_load_lds_dwordx4 v[218:219], off
	s_mov_b32 m0, s93
	s_nop 0
	global_load_lds_dwordx4 v[220:221], off
	s_waitcnt vmcnt(8)
	s_waitcnt lgkmcnt(0)
	s_barrier
; #define PG8_STAGE(bufoff, gbase, voff) do { _Pragma("unroll") for (int _i = 0; _i < 2; ++_i) \
;         __builtin_amdgcn_global_load_lds((const unsigned*)((const char*)(gbase) + (voff)[_i]), (PG8_LAS unsigned*)(lds + (bufoff) + ldsw + _i * 8192), 16, 0, 0); } while (0)
; #define PG8_LDA(dst, b, h) do { _Pragma("unroll") for (int m = 0; m < 4; ++m) _Pragma("unroll") for (int k = 0; k < 2; ++k) dst[m][k] = *(const PG8_LAS bf16x8*)(lds + PG8_SA(b, h) + aoff + m * 2048 + k * 1024); } while (0)
; #define PG8_LDB(dst, b, h) do { _Pragma("unroll") for (int n = 0; n < 2; ++n) _Pragma("unroll") for (int k = 0; k < 2; ++k) dst[n][k] = *(const PG8_LAS bf16x8*)(lds + PG8_SB(b, h) + boff + n * 2048 + k * 1024); } while (0)
; #define PG8_MMA(ai, bj, At, Bt) do { __builtin_amdgcn_s_setprio(1); _Pragma("unroll") for (int m = 0; m < 4; ++m) _Pragma("unroll") for (int n = 0; n < 2; ++n) _Pragma("unroll") for (int k = 0; k < 2; ++k) \
;         acc[ai][bj][m][n] = __builtin_amdgcn_mfma_f32_16x16x32_bf16(Bt[n][k], At[m][k], acc[ai][bj][m][n], 0, 0, 0); __builtin_amdgcn_s_setprio(0); } while (0)
; template <class Epi, class Sched, bool ALIGN_EPI = false, bool SP2 = false>
; __device__ __forceinline__ void gemm_phase(PG8_LAS unsigned char* lds, const Gemm g, const Sched& S, const Epi& E) {
;     ...
;             if constexpr (SP2) {
;             PG8_LDB(B0, 0, 0); PG8_LDB(B1, 0, 1); PG8_SCHED; PG8_LDA(At, 0, 0); PG8_STAGE(PG8_SA(1, 1), a1 + hstepA, voffA);
;             PG8_WAIT_V(8); PG8_WAIT_L(0); PG8_BAR; PG8_MMA(0, 0, At, B0); PG8_MMA(0, 1, At, B1); PG8_BAR; PG8_SCHED;
;             PG8_LDA(At, 0, 1); PG8_STAGE(PG8_SB(0, 0), b2, voffB); PG8_STAGE(PG8_SB(0, 1), b2 + hstepB, voffB); PG8_STAGE(PG8_SA(0, 0), a2, voffA);
;             PG8_WAIT_V(8); PG8_WAIT_L(0); PG8_BAR; PG8_MMA(1, 0, At, B0); PG8_MMA(1, 1, At, B1); PG8_BAR; PG8_SCHED;
;             PG8_LDB(B0, 1, 0); PG8_LDB(B1, 1, 1); PG8_SCHED; PG8_LDA(At, 1, 0); PG8_STAGE(PG8_SA(0, 1), a2 + hstepA, voffA);
;             PG8_WAIT_V(8); PG8_WAIT_L(0); PG8_BAR; PG8_MMA(0, 0, At, B0); PG8_MMA(0, 1, At, B1); PG8_BAR; PG8_SCHED;
;             PG8_LDA(At, 1, 1); PG8_STAGE(PG8_SB(1, 0), b3, voffB); PG8_STAGE(PG8_SB(1, 1), b3 + hstepB, voffB); PG8_STAGE(PG8_SA(1, 0), a3, voffA);
;             PG8_WAIT_V(8); PG8_WAIT_L(0); PG8_BAR; PG8_MMA(1, 0, At, B0); PG8_MMA(1, 1, At, B1); PG8_BAR; PG8_SCHED;
	s_setprio 1
	s_waitcnt lgkmcnt(0)
	v_mfma_f32_16x16x32_bf16 v[60:63], v[138:141], v[174:177], v[60:63]
	v_mfma_f32_16x16x32_bf16 v[56:59], v[146:149], v[174:177], v[56:59]
	v_mfma_f32_16x16x32_bf16 v[44:47], v[138:141], v[192:195], v[44:47]
	v_mfma_f32_16x16x32_bf16 v[40:43], v[146:149], v[192:195], v[40:43]
	v_mfma_f32_16x16x32_bf16 v[28:31], v[138:141], v[200:203], v[28:31]
	v_mfma_f32_16x16x32_bf16 v[24:27], v[146:149], v[200:203], v[24:27]
	v_mfma_f32_16x16x32_bf16 v[12:15], v[138:141], v[208:211], v[12:15]
	v_mfma_f32_16x16x32_bf16 v[8:11], v[146:149], v[208:211], v[8:11]
	v_mfma_f32_16x16x32_bf16 v[60:63], v[142:145], v[182:185], v[60:63]
	v_mfma_f32_16x16x32_bf16 v[56:59], v[150:153], v[182:185], v[56:59]
	v_mfma_f32_16x16x32_bf16 v[44:47], v[142:145], v[196:199], v[44:47]
	v_mfma_f32_16x16x32_bf16 v[40:43], v[150:153], v[196:199], v[40:43]
	v_mfma_f32_16x16x32_bf16 v[28:31], v[142:145], v[204:207], v[28:31]
	v_mfma_f32_16x16x32_bf16 v[24:27], v[150:153], v[204:207], v[24:27]
	v_mfma_f32_16x16x32_bf16 v[12:15], v[142:145], v[212:215], v[12:15]
	v_mfma_f32_16x16x32_bf16 v[8:11], v[150:153], v[212:215], v[8:11]
	s_setprio 0
	s_setprio 1
	v_mfma_f32_16x16x32_bf16 v[52:55], v[154:157], v[174:177], v[52:55]
	v_mfma_f32_16x16x32_bf16 v[48:51], v[162:165], v[174:177], v[48:51]
	v_mfma_f32_16x16x32_bf16 v[36:39], v[154:157], v[192:195], v[36:39]
	v_mfma_f32_16x16x32_bf16 v[32:35], v[162:165], v[192:195], v[32:35]
	v_mfma_f32_16x16x32_bf16 v[20:23], v[154:157], v[200:203], v[20:23]
	v_mfma_f32_16x16x32_bf16 v[16:19], v[162:165], v[200:203], v[16:19]
	v_mfma_f32_16x16x32_bf16 v[4:7], v[154:157], v[208:211], v[4:7]
	v_mfma_f32_16x16x32_bf16 v[0:3], v[162:165], v[208:211], v[0:3]
	v_mfma_f32_16x16x32_bf16 v[52:55], v[158:161], v[182:185], v[52:55]
	v_mfma_f32_16x16x32_bf16 v[48:51], v[166:169], v[182:185], v[48:51]
	v_mfma_f32_16x16x32_bf16 v[36:39], v[158:161], v[196:199], v[36:39]
	v_mfma_f32_16x16x32_bf16 v[32:35], v[166:169], v[196:199], v[32:35]
	v_mfma_f32_16x16x32_bf16 v[20:23], v[158:161], v[204:207], v[20:23]
	v_mfma_f32_16x16x32_bf16 v[16:19], v[166:169], v[204:207], v[16:19]
	v_mfma_f32_16x16x32_bf16 v[4:7], v[158:161], v[212:215], v[4:7]
	v_mfma_f32_16x16x32_bf16 v[0:3], v[166:169], v[212:215], v[0:3]
	s_setprio 0
	s_barrier
	s_add_i32 s52, 0, 0x18000
	s_add_i32 s64, 0, 0x1c000
	v_add_u32_e32 v150, s52, v171
	v_add_u32_e32 v166, s64, v171
	ds_read_b128 v[138:141], v150
	ds_read_b128 v[142:145], v150 offset:1024
	ds_read_b128 v[146:149], v150 offset:2048
	ds_read_b128 v[150:153], v150 offset:3072
	ds_read_b128 v[154:157], v166
	ds_read_b128 v[158:161], v166 offset:1024
	ds_read_b128 v[162:165], v166 offset:2048
	ds_read_b128 v[166:169], v166 offset:3072
	s_add_u32 s56, vcc_lo, 0x40000
	s_addc_u32 s57, vcc_hi, 0
	s_mov_b32 m0, s95
	ds_read_b128 v[174:177], v180 offset:32768
	ds_read_b128 v[182:185], v180 offset:33792
	ds_read_b128 v[192:195], v180 offset:34816
	ds_read_b128 v[196:199], v180 offset:35840
	ds_read_b128 v[200:203], v180 offset:36864
	ds_read_b128 v[204:207], v180 offset:37888
	ds_read_b128 v[208:211], v180 offset:38912
	ds_read_b128 v[212:215], v180 offset:39936
	global_load_lds_dwordx4 v128, s[56:57]
	v_lshl_add_u64 v[222:223], s[56:57], 0, v[130:131]
	s_mov_b32 m0, s96
	s_nop 0
	global_load_lds_dwordx4 v[222:223], off
	s_waitcnt vmcnt(8)
	s_waitcnt lgkmcnt(0)
	s_barrier
	s_setprio 1
	s_waitcnt lgkmcnt(0)
	v_mfma_f32_16x16x32_bf16 v[124:127], v[138:141], v[174:177], v[124:127]
	v_mfma_f32_16x16x32_bf16 v[120:123], v[146:149], v[174:177], v[120:123]
	v_mfma_f32_16x16x32_bf16 v[108:111], v[138:141], v[192:195], v[108:111]
	v_mfma_f32_16x16x32_bf16 v[104:107], v[146:149], v[192:195], v[104:107]
	v_mfma_f32_16x16x32_bf16 v[92:95], v[138:141], v[200:203], v[92:95]
	v_mfma_f32_16x16x32_bf16 v[88:91], v[146:149], v[200:203], v[88:91]
	v_mfma_f32_16x16x32_bf16 v[76:79], v[138:141], v[208:211], v[76:79]
	v_mfma_f32_16x16x32_bf16 v[72:75], v[146:149], v[208:211], v[72:75]
	v_mfma_f32_16x16x32_bf16 v[124:127], v[142:145], v[182:185], v[124:127]
	v_mfma_f32_16x16x32_bf16 v[120:123], v[150:153], v[182:185], v[120:123]
	v_mfma_f32_16x16x32_bf16 v[108:111], v[142:145], v[196:199], v[108:111]
	v_mfma_f32_16x16x32_bf16 v[104:107], v[150:153], v[196:199], v[104:107]
	v_mfma_f32_16x16x32_bf16 v[92:95], v[142:145], v[204:207], v[92:95]
	v_mfma_f32_16x16x32_bf16 v[88:91], v[150:153], v[204:207], v[88:91]
	v_mfma_f32_16x16x32_bf16 v[76:79], v[142:145], v[212:215], v[76:79]
	v_mfma_f32_16x16x32_bf16 v[72:75], v[150:153], v[212:215], v[72:75]
	s_setprio 0
	s_setprio 1
	v_mfma_f32_16x16x32_bf16 v[116:119], v[154:157], v[174:177], v[116:119]
	v_mfma_f32_16x16x32_bf16 v[112:115], v[162:165], v[174:177], v[112:115]
	v_mfma_f32_16x16x32_bf16 v[100:103], v[154:157], v[192:195], v[100:103]
	v_mfma_f32_16x16x32_bf16 v[96:99], v[162:165], v[192:195], v[96:99]
	v_mfma_f32_16x16x32_bf16 v[84:87], v[154:157], v[200:203], v[84:87]
	v_mfma_f32_16x16x32_bf16 v[80:83], v[162:165], v[200:203], v[80:83]
	v_mfma_f32_16x16x32_bf16 v[68:71], v[154:157], v[208:211], v[68:71]
	v_mfma_f32_16x16x32_bf16 v[64:67], v[162:165], v[208:211], v[64:67]
	v_mfma_f32_16x16x32_bf16 v[116:119], v[158:161], v[182:185], v[116:119]
	v_mfma_f32_16x16x32_bf16 v[112:115], v[166:169], v[182:185], v[112:115]
	v_mfma_f32_16x16x32_bf16 v[100:103], v[158:161], v[196:199], v[100:103]
	v_mfma_f32_16x16x32_bf16 v[96:99], v[166:169], v[196:199], v[96:99]
	v_mfma_f32_16x16x32_bf16 v[84:87], v[158:161], v[204:207], v[84:87]
	v_mfma_f32_16x16x32_bf16 v[80:83], v[166:169], v[204:207], v[80:83]
	v_mfma_f32_16x16x32_bf16 v[68:71], v[158:161], v[212:215], v[68:71]
	v_mfma_f32_16x16x32_bf16 v[64:67], v[166:169], v[212:215], v[64:67]
	s_setprio 0
	s_barrier
; #define PG8_STAGE(bufoff, gbase, voff) do { _Pragma("unroll") for (int _i = 0; _i < 2; ++_i) \
;         __builtin_amdgcn_global_load_lds((const unsigned*)((const char*)(gbase) + (voff)[_i]), (PG8_LAS unsigned*)(lds + (bufoff) + ldsw + _i * 8192), 16, 0, 0); } while (0)
; #define PG8_LDA(dst, b, h) do { _Pragma("unroll") for (int m = 0; m < 4; ++m) _Pragma("unroll") for (int k = 0; k < 2; ++k) dst[m][k] = *(const PG8_LAS bf16x8*)(lds + PG8_SA(b, h) + aoff + m * 2048 + k * 1024); } while (0)
; #define PG8_LDB(dst, b, h) do { _Pragma("unroll") for (int n = 0; n < 2; ++n) _Pragma("unroll") for (int k = 0; k < 2; ++k) dst[n][k] = *(const PG8_LAS bf16x8*)(lds + PG8_SB(b, h) + boff + n * 2048 + k * 1024); } while (0)
; #define PG8_MMA(ai, bj, At, Bt) do { __builtin_amdgcn_s_setprio(1); _Pragma("unroll") for (int m = 0; m < 4; ++m) _Pragma("unroll") for (int n = 0; n < 2; ++n) _Pragma("unroll") for (int k = 0; k < 2; ++k) \
;         acc[ai][bj][m][n] = __builtin_amdgcn_mfma_f32_16x16x32_bf16(Bt[n][k], At[m][k], acc[ai][bj][m][n], 0, 0, 0); __builtin_amdgcn_s_setprio(0); } while (0)
; template <class Epi, class Sched, bool ALIGN_EPI = false, bool SP2 = false>
; __device__ __forceinline__ void gemm_phase(PG8_LAS unsigned char* lds, const Gemm g, const Sched& S, const Epi& E) {
;     ...
;             if constexpr (SP2) {
;             PG8_LDB(B0, 0, 0); PG8_LDB(B1, 0, 1); PG8_SCHED; PG8_LDA(At, 0, 0); PG8_STAGE(PG8_SA(1, 1), a1 + hstepA, voffA);
;             PG8_WAIT_V(8); PG8_WAIT_L(0); PG8_BAR; PG8_MMA(0, 0, At, B0); PG8_MMA(0, 1, At, B1); PG8_BAR; PG8_SCHED;
;             PG8_LDA(At, 0, 1); PG8_STAGE(PG8_SB(0, 0), b2, voffB); PG8_STAGE(PG8_SB(0, 1), b2 + hstepB, voffB); PG8_STAGE(PG8_SA(0, 0), a2, voffA);
;             PG8_WAIT_V(8); PG8_WAIT_L(0); PG8_BAR; PG8_MMA(1, 0, At, B0); PG8_MMA(1, 1, At, B1); PG8_BAR; PG8_SCHED;
;             PG8_LDB(B0, 1, 0); PG8_LDB(B1, 1, 1); PG8_SCHED; PG8_LDA(At, 1, 0); PG8_STAGE(PG8_SA(0, 1), a2 + hstepA, voffA);
;             PG8_WAIT_V(8); PG8_WAIT_L(0); PG8_BAR; PG8_MMA(0, 0, At, B0); PG8_MMA(0, 1, At, B1); PG8_BAR; PG8_SCHED;
;             PG8_LDA(At, 1, 1); PG8_STAGE(PG8_SB(1, 0), b3, voffB); PG8_STAGE(PG8_SB(1, 1), b3 + hstepB, voffB); PG8_STAGE(PG8_SA(1, 0), a3, voffA);
;             PG8_WAIT_V(8); PG8_WAIT_L(0); PG8_BAR; PG8_MMA(1, 0, At, B0); PG8_MMA(1, 1, At, B1); PG8_BAR; PG8_SCHED;
	s_add_i32 s52, s52, s66
	v_lshl_add_u64 v[186:187], v[186:187], 0, s[80:81]
	s_mov_b32 m0, s52
	ds_read_b128 v[174:177], v180 offset:49152
	ds_read_b128 v[182:185], v180 offset:50176
	ds_read_b128 v[192:195], v180 offset:51200
	ds_read_b128 v[196:199], v180 offset:52224
	ds_read_b128 v[200:203], v180 offset:53248
	ds_read_b128 v[204:207], v180 offset:54272
	ds_read_b128 v[208:211], v180 offset:55296
	ds_read_b128 v[212:215], v180 offset:56320
	global_load_lds_dwordx4 v[186:187], off
	s_add_i32 m0, s52, 0x2000
	s_add_u32 s56, s70, 0x40080
	v_lshl_add_u64 v[186:187], v[216:217], 0, s[80:81]
	s_addc_u32 s57, s71, 0
	s_add_i32 s52, s64, s66
	global_load_lds_dwordx4 v[186:187], off
	s_mov_b32 m0, s52
	s_nop 0
	global_load_lds_dwordx4 v172, s[56:57]
	s_add_i32 m0, s52, 0x2000
	s_nop 0
	global_load_lds_dwordx4 v132, s[56:57]
	v_lshl_add_u64 v[186:187], v[218:219], 0, s[80:81]
	s_mov_b32 m0, s53
	s_nop 0
	global_load_lds_dwordx4 v[186:187], off
	v_lshl_add_u64 v[186:187], v[220:221], 0, s[80:81]
	s_mov_b32 m0, s58
	s_nop 0
	global_load_lds_dwordx4 v[186:187], off
	s_waitcnt vmcnt(8)
	s_waitcnt lgkmcnt(0)
	s_barrier
	s_setprio 1
	s_waitcnt lgkmcnt(0)
	v_mfma_f32_16x16x32_bf16 v[60:63], v[138:141], v[174:177], v[60:63]
	v_mfma_f32_16x16x32_bf16 v[56:59], v[146:149], v[174:177], v[56:59]
	v_mfma_f32_16x16x32_bf16 v[44:47], v[138:141], v[192:195], v[44:47]
	v_mfma_f32_16x16x32_bf16 v[40:43], v[146:149], v[192:195], v[40:43]
	v_mfma_f32_16x16x32_bf16 v[28:31], v[138:141], v[200:203], v[28:31]
	v_mfma_f32_16x16x32_bf16 v[24:27], v[146:149], v[200:203], v[24:27]
	v_mfma_f32_16x16x32_bf16 v[12:15], v[138:141], v[208:211], v[12:15]
	v_mfma_f32_16x16x32_bf16 v[8:11], v[146:149], v[208:211], v[8:11]
	v_mfma_f32_16x16x32_bf16 v[60:63], v[142:145], v[182:185], v[60:63]
	v_mfma_f32_16x16x32_bf16 v[56:59], v[150:153], v[182:185], v[56:59]
	v_mfma_f32_16x16x32_bf16 v[44:47], v[142:145], v[196:199], v[44:47]
	v_mfma_f32_16x16x32_bf16 v[40:43], v[150:153], v[196:199], v[40:43]
	v_mfma_f32_16x16x32_bf16 v[28:31], v[142:145], v[204:207], v[28:31]
	v_mfma_f32_16x16x32_bf16 v[24:27], v[150:153], v[204:207], v[24:27]
	v_mfma_f32_16x16x32_bf16 v[12:15], v[142:145], v[212:215], v[12:15]
	v_mfma_f32_16x16x32_bf16 v[8:11], v[150:153], v[212:215], v[8:11]
	s_setprio 0
	s_setprio 1
	v_mfma_f32_16x16x32_bf16 v[52:55], v[154:157], v[174:177], v[52:55]
	v_mfma_f32_16x16x32_bf16 v[48:51], v[162:165], v[174:177], v[48:51]
	v_mfma_f32_16x16x32_bf16 v[36:39], v[154:157], v[192:195], v[36:39]
	v_mfma_f32_16x16x32_bf16 v[32:35], v[162:165], v[192:195], v[32:35]
	v_mfma_f32_16x16x32_bf16 v[20:23], v[154:157], v[200:203], v[20:23]
	v_mfma_f32_16x16x32_bf16 v[16:19], v[162:165], v[200:203], v[16:19]
	v_mfma_f32_16x16x32_bf16 v[4:7], v[154:157], v[208:211], v[4:7]
	v_mfma_f32_16x16x32_bf16 v[0:3], v[162:165], v[208:211], v[0:3]
	v_mfma_f32_16x16x32_bf16 v[52:55], v[158:161], v[182:185], v[52:55]
	v_mfma_f32_16x16x32_bf16 v[48:51], v[166:169], v[182:185], v[48:51]
	v_mfma_f32_16x16x32_bf16 v[36:39], v[158:161], v[196:199], v[36:39]
	v_mfma_f32_16x16x32_bf16 v[32:35], v[166:169], v[196:199], v[32:35]
	v_mfma_f32_16x16x32_bf16 v[20:23], v[158:161], v[204:207], v[20:23]
	v_mfma_f32_16x16x32_bf16 v[16:19], v[166:169], v[204:207], v[16:19]
	v_mfma_f32_16x16x32_bf16 v[4:7], v[158:161], v[212:215], v[4:7]
	v_mfma_f32_16x16x32_bf16 v[0:3], v[166:169], v[212:215], v[0:3]
	s_setprio 0
	s_barrier
	s_add_i32 s87, s87, 2
	s_add_u32 s42, s42, 0x100
	s_addc_u32 s43, s43, 0
	s_add_u32 s85, s85, 0x100
	s_addc_u32 s89, s89, 0
	s_cmp_gt_u32 s87, 13
	s_cbranch_scc0 .LBB0_330
	s_and_b64 vcc, exec, s[76:77]
	s_cbranch_vccz .LBB0_333
	s_barrier

; #define PG8_STAGE(bufoff, gbase, voff) do { _Pragma("unroll") for (int _i = 0; _i < 2; ++_i) \
;         __builtin_amdgcn_global_load_lds((const unsigned*)((const char*)(gbase) + (voff)[_i]), (PG8_LAS unsigned*)(lds + (bufoff) + ldsw + _i * 8192), 16, 0, 0); } while (0)
; #define PG8_LDA(dst, b, h) do { _Pragma("unroll") for (int m = 0; m < 4; ++m) _Pragma("unroll") for (int k = 0; k < 2; ++k) dst[m][k] = *(const PG8_LAS bf16x8*)(lds + PG8_SA(b, h) + aoff + m * 2048 + k * 1024); } while (0)
; #define PG8_LDB(dst, b, h) do { _Pragma("unroll") for (int n = 0; n < 2; ++n) _Pragma("unroll") for (int k = 0; k < 2; ++k) dst[n][k] = *(const PG8_LAS bf16x8*)(lds + PG8_SB(b, h) + boff + n * 2048 + k * 1024); } while (0)
; template <class Epi, class Sched, bool ALIGN_EPI = false, bool SP2 = false>
; __device__ __forceinline__ void gemm_phase(PG8_LAS unsigned char* lds, const Gemm g, const Sched& S, const Epi& E) {
;     ...
;         for (int t = 0; t < nt; t += 2) {
;             const bool last = (t == nt - 2);
;             const char* a1 = cA + (size_t)(t + 1) * kstep;
;             const char* a2 = last ? nA : cA + (size_t)(t + 2) * kstep; const char* b2 = last ? nB : cB + (size_t)(t + 2) * kstep;
;             const char* a3 = a2 + kstep; const char* b3 = b2 + kstep;
;             if (last && has_next) S.a_ready(nxt);
;             if constexpr (SP2) {
;             PG8_LDB(B0, 0, 0); PG8_LDB(B1, 0, 1); PG8_SCHED; PG8_LDA(At, 0, 0); PG8_STAGE(PG8_SA(1, 1), a1 + hstepA, voffA);
;             PG8_WAIT_V(8); PG8_WAIT_L(0); PG8_BAR; PG8_MMA(0, 0, At, B0); PG8_MMA(0, 1, At, B1); PG8_BAR; PG8_SCHED;
;             PG8_LDA(At, 0, 1); PG8_STAGE(PG8_SB(0, 0), b2, voffB); PG8_STAGE(PG8_SB(0, 1), b2 + hstepB, voffB); PG8_STAGE(PG8_SA(0, 0), a2, voffA);
;             PG8_WAIT_V(8); PG8_WAIT_L(0); PG8_BAR; PG8_MMA(1, 0, At, B0); PG8_MMA(1, 1, At, B1); PG8_BAR; PG8_SCHED;
;             PG8_LDB(B0, 1, 0); PG8_LDB(B1, 1, 1); PG8_SCHED; PG8_LDA(At, 1, 0); PG8_STAGE(PG8_SA(0, 1), a2 + hstepA, voffA);
;             PG8_WAIT_V(8); PG8_WAIT_L(0); PG8_BAR; PG8_MMA(0, 0, At, B0); PG8_MMA(0, 1, At, B1); PG8_BAR; PG8_SCHED;
;             PG8_LDA(At, 1, 1); PG8_STAGE(PG8_SB(1, 0), b3, voffB); PG8_STAGE(PG8_SB(1, 1), b3 + hstepB, voffB); PG8_STAGE(PG8_SA(1, 0), a3, voffA);
;             PG8_WAIT_V(8); PG8_WAIT_L(0); PG8_BAR; PG8_MMA(1, 0, At, B0); PG8_MMA(1, 1, At, B1); PG8_BAR; PG8_SCHED;
.LBB0_533:
	s_add_u32 s40, s38, 0xfff80080
	s_addc_u32 s41, s39, -1
	s_add_i32 s70, 0, 0x10000
	s_cmp_eq_u32 s68, 28
	s_cselect_b32 s43, s27, s41
	s_cselect_b32 s42, s35, s40
	s_cselect_b32 s41, s25, s67
	s_cselect_b32 s40, s37, s66
	s_add_i32 s72, 0, 0x14000
	v_add_u32_e32 v92, s70, v181
	v_add_u32_e32 v164, s72, v181
	ds_read_b128 v[72:75], v92
	ds_read_b128 v[76:79], v92 offset:1024
	ds_read_b128 v[88:91], v92 offset:2048
	ds_read_b128 v[92:95], v92 offset:3072
	ds_read_b128 v[152:155], v164
	ds_read_b128 v[156:159], v164 offset:1024
	ds_read_b128 v[160:163], v164 offset:2048
	ds_read_b128 v[164:167], v164 offset:3072
	s_add_i32 m0, s51, 0xc000
	ds_read_b128 v[168:171], v186
	ds_read_b128 v[174:177], v186 offset:1024
	ds_read_b128 v[192:195], v186 offset:2048
	ds_read_b128 v[196:199], v186 offset:3072
	ds_read_b128 v[200:203], v186 offset:4096
	ds_read_b128 v[204:207], v186 offset:5120
	ds_read_b128 v[208:211], v186 offset:6144
	ds_read_b128 v[212:215], v186 offset:7168
	global_load_lds_dwordx4 v148, s[38:39]
	s_add_i32 m0, s51, 0xe000
	s_nop 0
	global_load_lds_dwordx4 v150, s[38:39]
	s_waitcnt vmcnt(8)
	s_waitcnt lgkmcnt(0)
	s_barrier
	s_setprio 1
	s_waitcnt lgkmcnt(0)
	v_mfma_f32_16x16x32_bf16 v[140:143], v[72:75], v[168:171], v[140:143]
	v_mfma_f32_16x16x32_bf16 v[136:139], v[88:91], v[168:171], v[136:139]
	v_mfma_f32_16x16x32_bf16 v[124:127], v[72:75], v[192:195], v[124:127]
	v_mfma_f32_16x16x32_bf16 v[120:123], v[88:91], v[192:195], v[120:123]
	v_mfma_f32_16x16x32_bf16 v[108:111], v[72:75], v[200:203], v[108:111]
	v_mfma_f32_16x16x32_bf16 v[104:107], v[88:91], v[200:203], v[104:107]
	v_mfma_f32_16x16x32_bf16 v[84:87], v[72:75], v[208:211], v[84:87]
	v_mfma_f32_16x16x32_bf16 v[80:83], v[88:91], v[208:211], v[80:83]
	v_mfma_f32_16x16x32_bf16 v[140:143], v[76:79], v[174:177], v[140:143]
	v_mfma_f32_16x16x32_bf16 v[136:139], v[92:95], v[174:177], v[136:139]
	v_mfma_f32_16x16x32_bf16 v[124:127], v[76:79], v[196:199], v[124:127]
	v_mfma_f32_16x16x32_bf16 v[120:123], v[92:95], v[196:199], v[120:123]
	v_mfma_f32_16x16x32_bf16 v[108:111], v[76:79], v[204:207], v[108:111]
	v_mfma_f32_16x16x32_bf16 v[104:107], v[92:95], v[204:207], v[104:107]
	v_mfma_f32_16x16x32_bf16 v[84:87], v[76:79], v[212:215], v[84:87]
	v_mfma_f32_16x16x32_bf16 v[80:83], v[92:95], v[212:215], v[80:83]
	s_setprio 0
	s_setprio 1
	v_mfma_f32_16x16x32_bf16 v[132:135], v[152:155], v[168:171], v[132:135]
	v_mfma_f32_16x16x32_bf16 v[128:131], v[160:163], v[168:171], v[128:131]
	v_mfma_f32_16x16x32_bf16 v[116:119], v[152:155], v[192:195], v[116:119]
	v_mfma_f32_16x16x32_bf16 v[112:115], v[160:163], v[192:195], v[112:115]
	v_mfma_f32_16x16x32_bf16 v[100:103], v[152:155], v[200:203], v[100:103]
	v_mfma_f32_16x16x32_bf16 v[96:99], v[160:163], v[200:203], v[96:99]
	v_mfma_f32_16x16x32_bf16 v[68:71], v[152:155], v[208:211], v[68:71]
	v_mfma_f32_16x16x32_bf16 v[64:67], v[160:163], v[208:211], v[64:67]
	v_mfma_f32_16x16x32_bf16 v[132:135], v[156:159], v[174:177], v[132:135]
	v_mfma_f32_16x16x32_bf16 v[128:131], v[164:167], v[174:177], v[128:131]
	v_mfma_f32_16x16x32_bf16 v[116:119], v[156:159], v[196:199], v[116:119]
	v_mfma_f32_16x16x32_bf16 v[112:115], v[164:167], v[196:199], v[112:115]
	v_mfma_f32_16x16x32_bf16 v[100:103], v[156:159], v[204:207], v[100:103]
	v_mfma_f32_16x16x32_bf16 v[96:99], v[164:167], v[204:207], v[96:99]
	v_mfma_f32_16x16x32_bf16 v[68:71], v[156:159], v[212:215], v[68:71]
	v_mfma_f32_16x16x32_bf16 v[64:67], v[164:167], v[212:215], v[64:67]
	s_setprio 0
	s_barrier
	s_add_i32 s70, s70, s50
	v_lshl_add_u64 v[178:179], s[40:41], 0, v[172:173]
	s_mov_b32 m0, s70
	ds_read_b128 v[168:171], v186 offset:16384
	ds_read_b128 v[174:177], v186 offset:17408
	ds_read_b128 v[192:195], v186 offset:18432
	ds_read_b128 v[196:199], v186 offset:19456
	ds_read_b128 v[200:203], v186 offset:20480
	ds_read_b128 v[204:207], v186 offset:21504
	ds_read_b128 v[208:211], v186 offset:22528
	ds_read_b128 v[212:215], v186 offset:23552
	global_load_lds_dwordx4 v[178:179], off
	s_add_i32 m0, s70, 0x2000
	s_add_u32 s70, s40, 0x80000
	v_lshl_add_u64 v[216:217], s[40:41], 0, v[144:145]
	s_addc_u32 s71, s41, 0
	s_add_i32 s72, s72, s50
	global_load_lds_dwordx4 v[216:217], off
	s_mov_b32 m0, s72
	v_lshl_add_u64 v[220:221], s[42:43], 0, v[144:145]
	global_load_lds_dwordx4 v172, s[70:71]
	s_add_i32 m0, s72, 0x2000
	s_nop 0
	global_load_lds_dwordx4 v144, s[70:71]
	v_lshl_add_u64 v[218:219], s[42:43], 0, v[172:173]
	s_mov_b32 m0, s51
	s_nop 0
	global_load_lds_dwordx4 v[218:219], off
	s_mov_b32 m0, s52
	s_nop 0
	global_load_lds_dwordx4 v[220:221], off
	s_waitcnt vmcnt(8)
	s_waitcnt lgkmcnt(0)
	s_barrier
; #define PG8_STAGE(bufoff, gbase, voff) do { _Pragma("unroll") for (int _i = 0; _i < 2; ++_i) \
;         __builtin_amdgcn_global_load_lds((const unsigned*)((const char*)(gbase) + (voff)[_i]), (PG8_LAS unsigned*)(lds + (bufoff) + ldsw + _i * 8192), 16, 0, 0); } while (0)
; #define PG8_LDA(dst, b, h) do { _Pragma("unroll") for (int m = 0; m < 4; ++m) _Pragma("unroll") for (int k = 0; k < 2; ++k) dst[m][k] = *(const PG8_LAS bf16x8*)(lds + PG8_SA(b, h) + aoff + m * 2048 + k * 1024); } while (0)
; #define PG8_LDB(dst, b, h) do { _Pragma("unroll") for (int n = 0; n < 2; ++n) _Pragma("unroll") for (int k = 0; k < 2; ++k) dst[n][k] = *(const PG8_LAS bf16x8*)(lds + PG8_SB(b, h) + boff + n * 2048 + k * 1024); } while (0)
; #define PG8_MMA(ai, bj, At, Bt) do { __builtin_amdgcn_s_setprio(1); _Pragma("unroll") for (int m = 0; m < 4; ++m) _Pragma("unroll") for (int n = 0; n < 2; ++n) _Pragma("unroll") for (int k = 0; k < 2; ++k) \
;         acc[ai][bj][m][n] = __builtin_amdgcn_mfma_f32_16x16x32_bf16(Bt[n][k], At[m][k], acc[ai][bj][m][n], 0, 0, 0); __builtin_amdgcn_s_setprio(0); } while (0)
; template <class Epi, class Sched, bool ALIGN_EPI = false, bool SP2 = false>
; __device__ __forceinline__ void gemm_phase(PG8_LAS unsigned char* lds, const Gemm g, const Sched& S, const Epi& E) {
;     ...
;             if constexpr (SP2) {
;             PG8_LDB(B0, 0, 0); PG8_LDB(B1, 0, 1); PG8_SCHED; PG8_LDA(At, 0, 0); PG8_STAGE(PG8_SA(1, 1), a1 + hstepA, voffA);
;             PG8_WAIT_V(8); PG8_WAIT_L(0); PG8_BAR; PG8_MMA(0, 0, At, B0); PG8_MMA(0, 1, At, B1); PG8_BAR; PG8_SCHED;
;             PG8_LDA(At, 0, 1); PG8_STAGE(PG8_SB(0, 0), b2, voffB); PG8_STAGE(PG8_SB(0, 1), b2 + hstepB, voffB); PG8_STAGE(PG8_SA(0, 0), a2, voffA);
;             PG8_WAIT_V(8); PG8_WAIT_L(0); PG8_BAR; PG8_MMA(1, 0, At, B0); PG8_MMA(1, 1, At, B1); PG8_BAR; PG8_SCHED;
;             PG8_LDB(B0, 1, 0); PG8_LDB(B1, 1, 1); PG8_SCHED; PG8_LDA(At, 1, 0); PG8_STAGE(PG8_SA(0, 1), a2 + hstepA, voffA);
;             PG8_WAIT_V(8); PG8_WAIT_L(0); PG8_BAR; PG8_MMA(0, 0, At, B0); PG8_MMA(0, 1, At, B1); PG8_BAR; PG8_SCHED;
;             PG8_LDA(At, 1, 1); PG8_STAGE(PG8_SB(1, 0), b3, voffB); PG8_STAGE(PG8_SB(1, 1), b3 + hstepB, voffB); PG8_STAGE(PG8_SA(1, 0), a3, voffA);
;             PG8_WAIT_V(8); PG8_WAIT_L(0); PG8_BAR; PG8_MMA(1, 0, At, B0); PG8_MMA(1, 1, At, B1); PG8_BAR; PG8_SCHED;
	s_setprio 1
	s_waitcnt lgkmcnt(0)
	v_mfma_f32_16x16x32_bf16 v[60:63], v[72:75], v[168:171], v[60:63]
	v_mfma_f32_16x16x32_bf16 v[56:59], v[88:91], v[168:171], v[56:59]
	v_mfma_f32_16x16x32_bf16 v[44:47], v[72:75], v[192:195], v[44:47]
	v_mfma_f32_16x16x32_bf16 v[40:43], v[88:91], v[192:195], v[40:43]
	v_mfma_f32_16x16x32_bf16 v[28:31], v[72:75], v[200:203], v[28:31]
	v_mfma_f32_16x16x32_bf16 v[24:27], v[88:91], v[200:203], v[24:27]
	v_mfma_f32_16x16x32_bf16 v[12:15], v[72:75], v[208:211], v[12:15]
	v_mfma_f32_16x16x32_bf16 v[8:11], v[88:91], v[208:211], v[8:11]
	v_mfma_f32_16x16x32_bf16 v[60:63], v[76:79], v[174:177], v[60:63]
	v_mfma_f32_16x16x32_bf16 v[56:59], v[92:95], v[174:177], v[56:59]
	v_mfma_f32_16x16x32_bf16 v[44:47], v[76:79], v[196:199], v[44:47]
	v_mfma_f32_16x16x32_bf16 v[40:43], v[92:95], v[196:199], v[40:43]
	v_mfma_f32_16x16x32_bf16 v[28:31], v[76:79], v[204:207], v[28:31]
	v_mfma_f32_16x16x32_bf16 v[24:27], v[92:95], v[204:207], v[24:27]
	v_mfma_f32_16x16x32_bf16 v[12:15], v[76:79], v[212:215], v[12:15]
	v_mfma_f32_16x16x32_bf16 v[8:11], v[92:95], v[212:215], v[8:11]
	s_setprio 0
	s_setprio 1
	v_mfma_f32_16x16x32_bf16 v[52:55], v[152:155], v[168:171], v[52:55]
	v_mfma_f32_16x16x32_bf16 v[48:51], v[160:163], v[168:171], v[48:51]
	v_mfma_f32_16x16x32_bf16 v[36:39], v[152:155], v[192:195], v[36:39]
	v_mfma_f32_16x16x32_bf16 v[32:35], v[160:163], v[192:195], v[32:35]
	v_mfma_f32_16x16x32_bf16 v[20:23], v[152:155], v[200:203], v[20:23]
	v_mfma_f32_16x16x32_bf16 v[16:19], v[160:163], v[200:203], v[16:19]
	v_mfma_f32_16x16x32_bf16 v[4:7], v[152:155], v[208:211], v[4:7]
	v_mfma_f32_16x16x32_bf16 v[0:3], v[160:163], v[208:211], v[0:3]
	v_mfma_f32_16x16x32_bf16 v[52:55], v[156:159], v[174:177], v[52:55]
	v_mfma_f32_16x16x32_bf16 v[48:51], v[164:167], v[174:177], v[48:51]
	v_mfma_f32_16x16x32_bf16 v[36:39], v[156:159], v[196:199], v[36:39]
	v_mfma_f32_16x16x32_bf16 v[32:35], v[164:167], v[196:199], v[32:35]
	v_mfma_f32_16x16x32_bf16 v[20:23], v[156:159], v[204:207], v[20:23]
	v_mfma_f32_16x16x32_bf16 v[16:19], v[164:167], v[204:207], v[16:19]
	v_mfma_f32_16x16x32_bf16 v[4:7], v[156:159], v[212:215], v[4:7]
	v_mfma_f32_16x16x32_bf16 v[0:3], v[164:167], v[212:215], v[0:3]
	s_setprio 0
	s_barrier
	s_add_i32 s70, 0, 0x18000
	s_add_i32 s71, 0, 0x1c000
	v_add_u32_e32 v92, s70, v181
	v_add_u32_e32 v164, s71, v181
	ds_read_b128 v[72:75], v92
	ds_read_b128 v[76:79], v92 offset:1024
	ds_read_b128 v[88:91], v92 offset:2048
	ds_read_b128 v[92:95], v92 offset:3072
	ds_read_b128 v[152:155], v164
	ds_read_b128 v[156:159], v164 offset:1024
	ds_read_b128 v[160:163], v164 offset:2048
	ds_read_b128 v[164:167], v164 offset:3072
	s_add_u32 s42, s42, 0x80000
	s_addc_u32 s43, s43, 0
	s_mov_b32 m0, s53
	ds_read_b128 v[168:171], v186 offset:32768
	ds_read_b128 v[174:177], v186 offset:33792
	ds_read_b128 v[192:195], v186 offset:34816
	ds_read_b128 v[196:199], v186 offset:35840
	ds_read_b128 v[200:203], v186 offset:36864
	ds_read_b128 v[204:207], v186 offset:37888
	ds_read_b128 v[208:211], v186 offset:38912
	ds_read_b128 v[212:215], v186 offset:39936
	global_load_lds_dwordx4 v172, s[42:43]
	v_lshl_add_u64 v[222:223], s[42:43], 0, v[144:145]
	s_mov_b32 m0, s56
	s_nop 0
	global_load_lds_dwordx4 v[222:223], off
	s_waitcnt vmcnt(8)
	s_waitcnt lgkmcnt(0)
	s_barrier
	s_setprio 1
	s_waitcnt lgkmcnt(0)
	v_mfma_f32_16x16x32_bf16 v[140:143], v[72:75], v[168:171], v[140:143]
	v_mfma_f32_16x16x32_bf16 v[136:139], v[88:91], v[168:171], v[136:139]
	v_mfma_f32_16x16x32_bf16 v[124:127], v[72:75], v[192:195], v[124:127]
	v_mfma_f32_16x16x32_bf16 v[120:123], v[88:91], v[192:195], v[120:123]
	v_mfma_f32_16x16x32_bf16 v[108:111], v[72:75], v[200:203], v[108:111]
	v_mfma_f32_16x16x32_bf16 v[104:107], v[88:91], v[200:203], v[104:107]
	v_mfma_f32_16x16x32_bf16 v[84:87], v[72:75], v[208:211], v[84:87]
	v_mfma_f32_16x16x32_bf16 v[80:83], v[88:91], v[208:211], v[80:83]
	v_mfma_f32_16x16x32_bf16 v[140:143], v[76:79], v[174:177], v[140:143]
	v_mfma_f32_16x16x32_bf16 v[136:139], v[92:95], v[174:177], v[136:139]
	v_mfma_f32_16x16x32_bf16 v[124:127], v[76:79], v[196:199], v[124:127]
	v_mfma_f32_16x16x32_bf16 v[120:123], v[92:95], v[196:199], v[120:123]
	v_mfma_f32_16x16x32_bf16 v[108:111], v[76:79], v[204:207], v[108:111]
	v_mfma_f32_16x16x32_bf16 v[104:107], v[92:95], v[204:207], v[104:107]
	v_mfma_f32_16x16x32_bf16 v[84:87], v[76:79], v[212:215], v[84:87]
	v_mfma_f32_16x16x32_bf16 v[80:83], v[92:95], v[212:215], v[80:83]
	s_setprio 0
	s_setprio 1
	v_mfma_f32_16x16x32_bf16 v[132:135], v[152:155], v[168:171], v[132:135]
	v_mfma_f32_16x16x32_bf16 v[128:131], v[160:163], v[168:171], v[128:131]
	v_mfma_f32_16x16x32_bf16 v[116:119], v[152:155], v[192:195], v[116:119]
	v_mfma_f32_16x16x32_bf16 v[112:115], v[160:163], v[192:195], v[112:115]
	v_mfma_f32_16x16x32_bf16 v[100:103], v[152:155], v[200:203], v[100:103]
	v_mfma_f32_16x16x32_bf16 v[96:99], v[160:163], v[200:203], v[96:99]
	v_mfma_f32_16x16x32_bf16 v[68:71], v[152:155], v[208:211], v[68:71]
	v_mfma_f32_16x16x32_bf16 v[64:67], v[160:163], v[208:211], v[64:67]
	v_mfma_f32_16x16x32_bf16 v[132:135], v[156:159], v[174:177], v[132:135]
	v_mfma_f32_16x16x32_bf16 v[128:131], v[164:167], v[174:177], v[128:131]
	v_mfma_f32_16x16x32_bf16 v[116:119], v[156:159], v[196:199], v[116:119]
	v_mfma_f32_16x16x32_bf16 v[112:115], v[164:167], v[196:199], v[112:115]
	v_mfma_f32_16x16x32_bf16 v[100:103], v[156:159], v[204:207], v[100:103]
	v_mfma_f32_16x16x32_bf16 v[96:99], v[164:167], v[204:207], v[96:99]
	v_mfma_f32_16x16x32_bf16 v[68:71], v[156:159], v[212:215], v[68:71]
	v_mfma_f32_16x16x32_bf16 v[64:67], v[164:167], v[212:215], v[64:67]
	s_setprio 0
	s_barrier
; #define PG8_STAGE(bufoff, gbase, voff) do { _Pragma("unroll") for (int _i = 0; _i < 2; ++_i) \
;         __builtin_amdgcn_global_load_lds((const unsigned*)((const char*)(gbase) + (voff)[_i]), (PG8_LAS unsigned*)(lds + (bufoff) + ldsw + _i * 8192), 16, 0, 0); } while (0)
; #define PG8_LDA(dst, b, h) do { _Pragma("unroll") for (int m = 0; m < 4; ++m) _Pragma("unroll") for (int k = 0; k < 2; ++k) dst[m][k] = *(const PG8_LAS bf16x8*)(lds + PG8_SA(b, h) + aoff + m * 2048 + k * 1024); } while (0)
; #define PG8_LDB(dst, b, h) do { _Pragma("unroll") for (int n = 0; n < 2; ++n) _Pragma("unroll") for (int k = 0; k < 2; ++k) dst[n][k] = *(const PG8_LAS bf16x8*)(lds + PG8_SB(b, h) + boff + n * 2048 + k * 1024); } while (0)
; #define PG8_MMA(ai, bj, At, Bt) do { __builtin_amdgcn_s_setprio(1); _Pragma("unroll") for (int m = 0; m < 4; ++m) _Pragma("unroll") for (int n = 0; n < 2; ++n) _Pragma("unroll") for (int k = 0; k < 2; ++k) \
;         acc[ai][bj][m][n] = __builtin_amdgcn_mfma_f32_16x16x32_bf16(Bt[n][k], At[m][k], acc[ai][bj][m][n], 0, 0, 0); __builtin_amdgcn_s_setprio(0); } while (0)
; template <class Epi, class Sched, bool ALIGN_EPI = false, bool SP2 = false>
; __device__ __forceinline__ void gemm_phase(PG8_LAS unsigned char* lds, const Gemm g, const Sched& S, const Epi& E) {
;     ...
;             if constexpr (SP2) {
;             PG8_LDB(B0, 0, 0); PG8_LDB(B1, 0, 1); PG8_SCHED; PG8_LDA(At, 0, 0); PG8_STAGE(PG8_SA(1, 1), a1 + hstepA, voffA);
;             PG8_WAIT_V(8); PG8_WAIT_L(0); PG8_BAR; PG8_MMA(0, 0, At, B0); PG8_MMA(0, 1, At, B1); PG8_BAR; PG8_SCHED;
;             PG8_LDA(At, 0, 1); PG8_STAGE(PG8_SB(0, 0), b2, voffB); PG8_STAGE(PG8_SB(0, 1), b2 + hstepB, voffB); PG8_STAGE(PG8_SA(0, 0), a2, voffA);
;             PG8_WAIT_V(8); PG8_WAIT_L(0); PG8_BAR; PG8_MMA(1, 0, At, B0); PG8_MMA(1, 1, At, B1); PG8_BAR; PG8_SCHED;
;             PG8_LDB(B0, 1, 0); PG8_LDB(B1, 1, 1); PG8_SCHED; PG8_LDA(At, 1, 0); PG8_STAGE(PG8_SA(0, 1), a2 + hstepA, voffA);
;             PG8_WAIT_V(8); PG8_WAIT_L(0); PG8_BAR; PG8_MMA(0, 0, At, B0); PG8_MMA(0, 1, At, B1); PG8_BAR; PG8_SCHED;
;             PG8_LDA(At, 1, 1); PG8_STAGE(PG8_SB(1, 0), b3, voffB); PG8_STAGE(PG8_SB(1, 1), b3 + hstepB, voffB); PG8_STAGE(PG8_SA(1, 0), a3, voffA);
;             PG8_WAIT_V(8); PG8_WAIT_L(0); PG8_BAR; PG8_MMA(1, 0, At, B0); PG8_MMA(1, 1, At, B1); PG8_BAR; PG8_SCHED;
	s_add_i32 s42, s70, s50
	v_lshl_add_u64 v[178:179], v[178:179], 0, s[80:81]
	s_mov_b32 m0, s42
	ds_read_b128 v[168:171], v186 offset:49152
	ds_read_b128 v[174:177], v186 offset:50176
	ds_read_b128 v[192:195], v186 offset:51200
	ds_read_b128 v[196:199], v186 offset:52224
	ds_read_b128 v[200:203], v186 offset:53248
	ds_read_b128 v[204:207], v186 offset:54272
	ds_read_b128 v[208:211], v186 offset:55296
	ds_read_b128 v[212:215], v186 offset:56320
	global_load_lds_dwordx4 v[178:179], off
	s_add_i32 m0, s42, 0x2000
	s_add_u32 s40, s40, 0x80080
	v_lshl_add_u64 v[178:179], v[216:217], 0, s[80:81]
	s_addc_u32 s41, s41, 0
	s_add_i32 s42, s71, s50
	global_load_lds_dwordx4 v[178:179], off
	s_mov_b32 m0, s42
	s_nop 0
	global_load_lds_dwordx4 v172, s[40:41]
	s_add_i32 m0, s42, 0x2000
	s_nop 0
	global_load_lds_dwordx4 v144, s[40:41]
	v_lshl_add_u64 v[178:179], v[218:219], 0, s[80:81]
	s_mov_b32 m0, s61
	s_nop 0
	global_load_lds_dwordx4 v[178:179], off
	v_lshl_add_u64 v[178:179], v[220:221], 0, s[80:81]
	s_mov_b32 m0, s62
	s_nop 0
	global_load_lds_dwordx4 v[178:179], off
	s_waitcnt vmcnt(8)
	s_waitcnt lgkmcnt(0)
	s_barrier
	s_setprio 1
	s_waitcnt lgkmcnt(0)
	v_mfma_f32_16x16x32_bf16 v[60:63], v[72:75], v[168:171], v[60:63]
	v_mfma_f32_16x16x32_bf16 v[56:59], v[88:91], v[168:171], v[56:59]
	v_mfma_f32_16x16x32_bf16 v[44:47], v[72:75], v[192:195], v[44:47]
	v_mfma_f32_16x16x32_bf16 v[40:43], v[88:91], v[192:195], v[40:43]
	v_mfma_f32_16x16x32_bf16 v[28:31], v[72:75], v[200:203], v[28:31]
	v_mfma_f32_16x16x32_bf16 v[24:27], v[88:91], v[200:203], v[24:27]
	v_mfma_f32_16x16x32_bf16 v[12:15], v[72:75], v[208:211], v[12:15]
	v_mfma_f32_16x16x32_bf16 v[8:11], v[88:91], v[208:211], v[8:11]
	v_mfma_f32_16x16x32_bf16 v[60:63], v[76:79], v[174:177], v[60:63]
	v_mfma_f32_16x16x32_bf16 v[56:59], v[92:95], v[174:177], v[56:59]
	v_mfma_f32_16x16x32_bf16 v[44:47], v[76:79], v[196:199], v[44:47]
	v_mfma_f32_16x16x32_bf16 v[40:43], v[92:95], v[196:199], v[40:43]
	v_mfma_f32_16x16x32_bf16 v[28:31], v[76:79], v[204:207], v[28:31]
	v_mfma_f32_16x16x32_bf16 v[24:27], v[92:95], v[204:207], v[24:27]
	v_mfma_f32_16x16x32_bf16 v[12:15], v[76:79], v[212:215], v[12:15]
	v_mfma_f32_16x16x32_bf16 v[8:11], v[92:95], v[212:215], v[8:11]
	s_setprio 0
	s_setprio 1
	v_mfma_f32_16x16x32_bf16 v[52:55], v[152:155], v[168:171], v[52:55]
	v_mfma_f32_16x16x32_bf16 v[48:51], v[160:163], v[168:171], v[48:51]
	v_mfma_f32_16x16x32_bf16 v[36:39], v[152:155], v[192:195], v[36:39]
	v_mfma_f32_16x16x32_bf16 v[32:35], v[160:163], v[192:195], v[32:35]
	v_mfma_f32_16x16x32_bf16 v[20:23], v[152:155], v[200:203], v[20:23]
	v_mfma_f32_16x16x32_bf16 v[16:19], v[160:163], v[200:203], v[16:19]
	v_mfma_f32_16x16x32_bf16 v[4:7], v[152:155], v[208:211], v[4:7]
	v_mfma_f32_16x16x32_bf16 v[0:3], v[160:163], v[208:211], v[0:3]
	v_mfma_f32_16x16x32_bf16 v[52:55], v[156:159], v[174:177], v[52:55]
	v_mfma_f32_16x16x32_bf16 v[48:51], v[164:167], v[174:177], v[48:51]
	v_mfma_f32_16x16x32_bf16 v[36:39], v[156:159], v[196:199], v[36:39]
	v_mfma_f32_16x16x32_bf16 v[32:35], v[164:167], v[196:199], v[32:35]
	v_mfma_f32_16x16x32_bf16 v[20:23], v[156:159], v[204:207], v[20:23]
	v_mfma_f32_16x16x32_bf16 v[16:19], v[164:167], v[204:207], v[16:19]
	v_mfma_f32_16x16x32_bf16 v[4:7], v[156:159], v[212:215], v[4:7]
	v_mfma_f32_16x16x32_bf16 v[0:3], v[164:167], v[212:215], v[0:3]
	s_setprio 0
	s_barrier
	s_add_i32 s68, s68, 2
	s_add_u32 s38, s38, 0x100
	s_addc_u32 s39, s39, 0
	s_add_u32 s66, s66, 0x100
	s_addc_u32 s67, s67, 0
	s_cmp_gt_u32 s68, 29
	s_cbranch_scc0 .LBB0_533
	s_and_b64 vcc, exec, s[22:23]
	s_cbranch_vccz .LBB0_536
	s_barrier

; #define PG8_STAGE(bufoff, gbase, voff) do { _Pragma("unroll") for (int _i = 0; _i < 2; ++_i) \
;         __builtin_amdgcn_global_load_lds((const unsigned*)((const char*)(gbase) + (voff)[_i]), (PG8_LAS unsigned*)(lds + (bufoff) + ldsw + _i * 8192), 16, 0, 0); } while (0)
; #define PG8_LDA(dst, b, h) do { _Pragma("unroll") for (int m = 0; m < 4; ++m) _Pragma("unroll") for (int k = 0; k < 2; ++k) dst[m][k] = *(const PG8_LAS bf16x8*)(lds + PG8_SA(b, h) + aoff + m * 2048 + k * 1024); } while (0)
; #define PG8_LDB(dst, b, h) do { _Pragma("unroll") for (int n = 0; n < 2; ++n) _Pragma("unroll") for (int k = 0; k < 2; ++k) dst[n][k] = *(const PG8_LAS bf16x8*)(lds + PG8_SB(b, h) + boff + n * 2048 + k * 1024); } while (0)
; template <class Epi, class Sched, bool ALIGN_EPI = false, bool SP2 = false>
; __device__ __forceinline__ void gemm_phase(PG8_LAS unsigned char* lds, const Gemm g, const Sched& S, const Epi& E) {
;     ...
;         for (int t = 0; t < nt; t += 2) {
;             const bool last = (t == nt - 2);
;             const char* a1 = cA + (size_t)(t + 1) * kstep;
;             const char* a2 = last ? nA : cA + (size_t)(t + 2) * kstep; const char* b2 = last ? nB : cB + (size_t)(t + 2) * kstep;
;             const char* a3 = a2 + kstep; const char* b3 = b2 + kstep;
;             if (last && has_next) S.a_ready(nxt);
;             if constexpr (SP2) {
;             PG8_LDB(B0, 0, 0); PG8_LDB(B1, 0, 1); PG8_SCHED; PG8_LDA(At, 0, 0); PG8_STAGE(PG8_SA(1, 1), a1 + hstepA, voffA);
;             PG8_WAIT_V(8); PG8_WAIT_L(0); PG8_BAR; PG8_MMA(0, 0, At, B0); PG8_MMA(0, 1, At, B1); PG8_BAR; PG8_SCHED;
;             PG8_LDA(At, 0, 1); PG8_STAGE(PG8_SB(0, 0), b2, voffB); PG8_STAGE(PG8_SB(0, 1), b2 + hstepB, voffB); PG8_STAGE(PG8_SA(0, 0), a2, voffA);
;             PG8_WAIT_V(8); PG8_WAIT_L(0); PG8_BAR; PG8_MMA(1, 0, At, B0); PG8_MMA(1, 1, At, B1); PG8_BAR; PG8_SCHED;
;             PG8_LDB(B0, 1, 0); PG8_LDB(B1, 1, 1); PG8_SCHED; PG8_LDA(At, 1, 0); PG8_STAGE(PG8_SA(0, 1), a2 + hstepA, voffA);
;             PG8_WAIT_V(8); PG8_WAIT_L(0); PG8_BAR; PG8_MMA(0, 0, At, B0); PG8_MMA(0, 1, At, B1); PG8_BAR; PG8_SCHED;
;             PG8_LDA(At, 1, 1); PG8_STAGE(PG8_SB(1, 0), b3, voffB); PG8_STAGE(PG8_SB(1, 1), b3 + hstepB, voffB); PG8_STAGE(PG8_SA(1, 0), a3, voffA);
;             PG8_WAIT_V(8); PG8_WAIT_L(0); PG8_BAR; PG8_MMA(1, 0, At, B0); PG8_MMA(1, 1, At, B1); PG8_BAR; PG8_SCHED;
.LBB0_780:
	s_add_u32 s12, s10, 0xfffc0080
	s_addc_u32 s13, s11, -1
	s_add_i32 s61, 0, 0x10000
	s_cmp_eq_u32 s21, 12
	s_cselect_b32 s15, s5, s13
	s_cselect_b32 s14, s16, s12
	s_cselect_b32 s13, s17, s20
	s_cselect_b32 s12, s18, s19
	s_add_i32 s63, 0, 0x14000
	v_add_u32_e32 v44, s61, v197
	v_add_u32_e32 v60, s63, v197
	ds_read_b128 v[32:35], v44
	ds_read_b128 v[36:39], v44 offset:1024
	ds_read_b128 v[40:43], v44 offset:2048
	ds_read_b128 v[44:47], v44 offset:3072
	ds_read_b128 v[48:51], v60
	ds_read_b128 v[52:55], v60 offset:1024
	ds_read_b128 v[56:59], v60 offset:2048
	ds_read_b128 v[60:63], v60 offset:3072
	s_add_i32 m0, s27, 0xc000
	ds_read_b128 v[168:171], v201
	ds_read_b128 v[178:181], v201 offset:1024
	ds_read_b128 v[182:185], v201 offset:2048
	ds_read_b128 v[202:205], v201 offset:3072
	ds_read_b128 v[206:209], v201 offset:4096
	ds_read_b128 v[210:213], v201 offset:5120
	ds_read_b128 v[214:217], v201 offset:6144
	ds_read_b128 v[218:221], v201 offset:7168
	global_load_lds_dwordx4 v164, s[10:11]
	s_add_i32 m0, s27, 0xe000
	s_nop 0
	global_load_lds_dwordx4 v166, s[10:11]
	s_waitcnt vmcnt(8)
	s_waitcnt lgkmcnt(0)
	s_barrier
	s_setprio 1
	s_waitcnt lgkmcnt(0)
	v_mfma_f32_16x16x32_bf16 v[156:159], v[32:35], v[168:171], v[156:159]
	v_mfma_f32_16x16x32_bf16 v[152:155], v[40:43], v[168:171], v[152:155]
	v_mfma_f32_16x16x32_bf16 v[140:143], v[32:35], v[182:185], v[140:143]
	v_mfma_f32_16x16x32_bf16 v[136:139], v[40:43], v[182:185], v[136:139]
	v_mfma_f32_16x16x32_bf16 v[124:127], v[32:35], v[206:209], v[124:127]
	v_mfma_f32_16x16x32_bf16 v[120:123], v[40:43], v[206:209], v[120:123]
	v_mfma_f32_16x16x32_bf16 v[108:111], v[32:35], v[214:217], v[108:111]
	v_mfma_f32_16x16x32_bf16 v[104:107], v[40:43], v[214:217], v[104:107]
	v_mfma_f32_16x16x32_bf16 v[156:159], v[36:39], v[178:181], v[156:159]
	v_mfma_f32_16x16x32_bf16 v[152:155], v[44:47], v[178:181], v[152:155]
	v_mfma_f32_16x16x32_bf16 v[140:143], v[36:39], v[202:205], v[140:143]
	v_mfma_f32_16x16x32_bf16 v[136:139], v[44:47], v[202:205], v[136:139]
	v_mfma_f32_16x16x32_bf16 v[124:127], v[36:39], v[210:213], v[124:127]
	v_mfma_f32_16x16x32_bf16 v[120:123], v[44:47], v[210:213], v[120:123]
	v_mfma_f32_16x16x32_bf16 v[108:111], v[36:39], v[218:221], v[108:111]
	v_mfma_f32_16x16x32_bf16 v[104:107], v[44:47], v[218:221], v[104:107]
	s_setprio 0
	s_setprio 1
	v_mfma_f32_16x16x32_bf16 v[148:151], v[48:51], v[168:171], v[148:151]
	v_mfma_f32_16x16x32_bf16 v[144:147], v[56:59], v[168:171], v[144:147]
	v_mfma_f32_16x16x32_bf16 v[132:135], v[48:51], v[182:185], v[132:135]
	v_mfma_f32_16x16x32_bf16 v[128:131], v[56:59], v[182:185], v[128:131]
	v_mfma_f32_16x16x32_bf16 v[116:119], v[48:51], v[206:209], v[116:119]
	v_mfma_f32_16x16x32_bf16 v[112:115], v[56:59], v[206:209], v[112:115]
	v_mfma_f32_16x16x32_bf16 v[100:103], v[48:51], v[214:217], v[100:103]
	v_mfma_f32_16x16x32_bf16 v[96:99], v[56:59], v[214:217], v[96:99]
	v_mfma_f32_16x16x32_bf16 v[148:151], v[52:55], v[178:181], v[148:151]
	v_mfma_f32_16x16x32_bf16 v[144:147], v[60:63], v[178:181], v[144:147]
	v_mfma_f32_16x16x32_bf16 v[132:135], v[52:55], v[202:205], v[132:135]
	v_mfma_f32_16x16x32_bf16 v[128:131], v[60:63], v[202:205], v[128:131]
	v_mfma_f32_16x16x32_bf16 v[116:119], v[52:55], v[210:213], v[116:119]
	v_mfma_f32_16x16x32_bf16 v[112:115], v[60:63], v[210:213], v[112:115]
	v_mfma_f32_16x16x32_bf16 v[100:103], v[52:55], v[218:221], v[100:103]
	v_mfma_f32_16x16x32_bf16 v[96:99], v[60:63], v[218:221], v[96:99]
	s_setprio 0
	s_barrier
	s_add_i32 s61, s61, s91
	v_lshl_add_u64 v[174:175], s[12:13], 0, v[160:161]
	s_mov_b32 m0, s61
	ds_read_b128 v[168:171], v201 offset:16384
	ds_read_b128 v[178:181], v201 offset:17408
	ds_read_b128 v[182:185], v201 offset:18432
	ds_read_b128 v[202:205], v201 offset:19456
	ds_read_b128 v[206:209], v201 offset:20480
	ds_read_b128 v[210:213], v201 offset:21504
	ds_read_b128 v[214:217], v201 offset:22528
	ds_read_b128 v[218:221], v201 offset:23552
	global_load_lds_dwordx4 v[174:175], off
	s_add_i32 m0, s61, 0x2000
	s_add_u32 s70, s12, 0x40000
	v_lshl_add_u64 v[176:177], s[12:13], 0, v[162:163]
	s_addc_u32 s71, s13, 0
	s_add_i32 s61, s63, s91
	global_load_lds_dwordx4 v[176:177], off
	s_mov_b32 m0, s61
	v_lshl_add_u64 v[192:193], s[14:15], 0, v[162:163]
	global_load_lds_dwordx4 v160, s[70:71]
	s_add_i32 m0, s61, 0x2000
	s_nop 0
	global_load_lds_dwordx4 v162, s[70:71]
	v_lshl_add_u64 v[186:187], s[14:15], 0, v[160:161]
	s_mov_b32 m0, s27
	s_nop 0
	global_load_lds_dwordx4 v[186:187], off
	s_mov_b32 m0, s93
	s_nop 0
	global_load_lds_dwordx4 v[192:193], off
	s_waitcnt vmcnt(8)
	s_waitcnt lgkmcnt(0)
	s_barrier
; #define PG8_STAGE(bufoff, gbase, voff) do { _Pragma("unroll") for (int _i = 0; _i < 2; ++_i) \
;         __builtin_amdgcn_global_load_lds((const unsigned*)((const char*)(gbase) + (voff)[_i]), (PG8_LAS unsigned*)(lds + (bufoff) + ldsw + _i * 8192), 16, 0, 0); } while (0)
; #define PG8_LDA(dst, b, h) do { _Pragma("unroll") for (int m = 0; m < 4; ++m) _Pragma("unroll") for (int k = 0; k < 2; ++k) dst[m][k] = *(const PG8_LAS bf16x8*)(lds + PG8_SA(b, h) + aoff + m * 2048 + k * 1024); } while (0)
; #define PG8_LDB(dst, b, h) do { _Pragma("unroll") for (int n = 0; n < 2; ++n) _Pragma("unroll") for (int k = 0; k < 2; ++k) dst[n][k] = *(const PG8_LAS bf16x8*)(lds + PG8_SB(b, h) + boff + n * 2048 + k * 1024); } while (0)
; #define PG8_MMA(ai, bj, At, Bt) do { __builtin_amdgcn_s_setprio(1); _Pragma("unroll") for (int m = 0; m < 4; ++m) _Pragma("unroll") for (int n = 0; n < 2; ++n) _Pragma("unroll") for (int k = 0; k < 2; ++k) \
;         acc[ai][bj][m][n] = __builtin_amdgcn_mfma_f32_16x16x32_bf16(Bt[n][k], At[m][k], acc[ai][bj][m][n], 0, 0, 0); __builtin_amdgcn_s_setprio(0); } while (0)
; template <class Epi, class Sched, bool ALIGN_EPI = false, bool SP2 = false>
; __device__ __forceinline__ void gemm_phase(PG8_LAS unsigned char* lds, const Gemm g, const Sched& S, const Epi& E) {
;     ...
;             if constexpr (SP2) {
;             PG8_LDB(B0, 0, 0); PG8_LDB(B1, 0, 1); PG8_SCHED; PG8_LDA(At, 0, 0); PG8_STAGE(PG8_SA(1, 1), a1 + hstepA, voffA);
;             PG8_WAIT_V(8); PG8_WAIT_L(0); PG8_BAR; PG8_MMA(0, 0, At, B0); PG8_MMA(0, 1, At, B1); PG8_BAR; PG8_SCHED;
;             PG8_LDA(At, 0, 1); PG8_STAGE(PG8_SB(0, 0), b2, voffB); PG8_STAGE(PG8_SB(0, 1), b2 + hstepB, voffB); PG8_STAGE(PG8_SA(0, 0), a2, voffA);
;             PG8_WAIT_V(8); PG8_WAIT_L(0); PG8_BAR; PG8_MMA(1, 0, At, B0); PG8_MMA(1, 1, At, B1); PG8_BAR; PG8_SCHED;
;             PG8_LDB(B0, 1, 0); PG8_LDB(B1, 1, 1); PG8_SCHED; PG8_LDA(At, 1, 0); PG8_STAGE(PG8_SA(0, 1), a2 + hstepA, voffA);
;             PG8_WAIT_V(8); PG8_WAIT_L(0); PG8_BAR; PG8_MMA(0, 0, At, B0); PG8_MMA(0, 1, At, B1); PG8_BAR; PG8_SCHED;
;             PG8_LDA(At, 1, 1); PG8_STAGE(PG8_SB(1, 0), b3, voffB); PG8_STAGE(PG8_SB(1, 1), b3 + hstepB, voffB); PG8_STAGE(PG8_SA(1, 0), a3, voffA);
;             PG8_WAIT_V(8); PG8_WAIT_L(0); PG8_BAR; PG8_MMA(1, 0, At, B0); PG8_MMA(1, 1, At, B1); PG8_BAR; PG8_SCHED;
	s_setprio 1
	s_waitcnt lgkmcnt(0)
	v_mfma_f32_16x16x32_bf16 v[92:95], v[32:35], v[168:171], v[92:95]
	v_mfma_f32_16x16x32_bf16 v[88:91], v[40:43], v[168:171], v[88:91]
	v_mfma_f32_16x16x32_bf16 v[76:79], v[32:35], v[182:185], v[76:79]
	v_mfma_f32_16x16x32_bf16 v[72:75], v[40:43], v[182:185], v[72:75]
	v_mfma_f32_16x16x32_bf16 v[28:31], v[32:35], v[206:209], v[28:31]
	v_mfma_f32_16x16x32_bf16 v[24:27], v[40:43], v[206:209], v[24:27]
	v_mfma_f32_16x16x32_bf16 v[12:15], v[32:35], v[214:217], v[12:15]
	v_mfma_f32_16x16x32_bf16 v[8:11], v[40:43], v[214:217], v[8:11]
	v_mfma_f32_16x16x32_bf16 v[92:95], v[36:39], v[178:181], v[92:95]
	v_mfma_f32_16x16x32_bf16 v[88:91], v[44:47], v[178:181], v[88:91]
	v_mfma_f32_16x16x32_bf16 v[76:79], v[36:39], v[202:205], v[76:79]
	v_mfma_f32_16x16x32_bf16 v[72:75], v[44:47], v[202:205], v[72:75]
	v_mfma_f32_16x16x32_bf16 v[28:31], v[36:39], v[210:213], v[28:31]
	v_mfma_f32_16x16x32_bf16 v[24:27], v[44:47], v[210:213], v[24:27]
	v_mfma_f32_16x16x32_bf16 v[12:15], v[36:39], v[218:221], v[12:15]
	v_mfma_f32_16x16x32_bf16 v[8:11], v[44:47], v[218:221], v[8:11]
	s_setprio 0
	s_setprio 1
	v_mfma_f32_16x16x32_bf16 v[20:23], v[48:51], v[206:209], v[20:23]
	v_mfma_f32_16x16x32_bf16 v[16:19], v[56:59], v[206:209], v[16:19]
	v_mfma_f32_16x16x32_bf16 v[4:7], v[48:51], v[214:217], v[4:7]
	v_mfma_f32_16x16x32_bf16 v[0:3], v[56:59], v[214:217], v[0:3]
	v_mfma_f32_16x16x32_bf16 v[32:35], v[48:51], v[168:171], v[84:87]
	v_mfma_f32_16x16x32_bf16 v[36:39], v[56:59], v[168:171], v[80:83]
	v_mfma_f32_16x16x32_bf16 v[40:43], v[48:51], v[182:185], v[68:71]
	v_mfma_f32_16x16x32_bf16 v[44:47], v[56:59], v[182:185], v[64:67]
	v_mfma_f32_16x16x32_bf16 v[20:23], v[52:55], v[210:213], v[20:23]
	v_mfma_f32_16x16x32_bf16 v[16:19], v[60:63], v[210:213], v[16:19]
	v_mfma_f32_16x16x32_bf16 v[4:7], v[52:55], v[218:221], v[4:7]
	v_mfma_f32_16x16x32_bf16 v[0:3], v[60:63], v[218:221], v[0:3]
	v_mfma_f32_16x16x32_bf16 v[32:35], v[52:55], v[178:181], v[32:35]
	v_mfma_f32_16x16x32_bf16 v[36:39], v[60:63], v[178:181], v[36:39]
	v_mfma_f32_16x16x32_bf16 v[40:43], v[52:55], v[202:205], v[40:43]
	v_mfma_f32_16x16x32_bf16 v[44:47], v[60:63], v[202:205], v[44:47]
	s_setprio 0
	s_barrier
	s_add_i32 s61, 0, 0x18000
	s_add_i32 s63, 0, 0x1c000
	v_add_u32_e32 v60, s61, v197
	v_add_u32_e32 v64, s63, v197
	ds_read_b128 v[48:51], v60
	ds_read_b128 v[52:55], v60 offset:1024
	ds_read_b128 v[56:59], v60 offset:2048
	ds_read_b128 v[60:63], v60 offset:3072
	ds_read_b128 v[168:171], v64
	ds_read_b128 v[178:181], v64 offset:1024
	ds_read_b128 v[182:185], v64 offset:2048
	ds_read_b128 v[202:205], v64 offset:3072
	s_add_u32 s14, s14, 0x40000
	s_addc_u32 s15, s15, 0
	s_mov_b32 m0, s95
	ds_read_b128 v[64:67], v201 offset:32768
	ds_read_b128 v[68:71], v201 offset:33792
	ds_read_b128 v[80:83], v201 offset:34816
	ds_read_b128 v[84:87], v201 offset:35840
	ds_read_b128 v[206:209], v201 offset:36864
	ds_read_b128 v[210:213], v201 offset:37888
	ds_read_b128 v[214:217], v201 offset:38912
	ds_read_b128 v[218:221], v201 offset:39936
	global_load_lds_dwordx4 v160, s[14:15]
	v_lshl_add_u64 v[194:195], s[14:15], 0, v[162:163]
	s_mov_b32 m0, s96
	s_nop 0
	global_load_lds_dwordx4 v[194:195], off
	s_waitcnt vmcnt(8)
	s_waitcnt lgkmcnt(0)
	s_barrier
	s_setprio 1
	s_waitcnt lgkmcnt(0)
	v_mfma_f32_16x16x32_bf16 v[156:159], v[48:51], v[64:67], v[156:159]
	v_mfma_f32_16x16x32_bf16 v[152:155], v[56:59], v[64:67], v[152:155]
	v_mfma_f32_16x16x32_bf16 v[140:143], v[48:51], v[80:83], v[140:143]
	v_mfma_f32_16x16x32_bf16 v[136:139], v[56:59], v[80:83], v[136:139]
	v_mfma_f32_16x16x32_bf16 v[124:127], v[48:51], v[206:209], v[124:127]
	v_mfma_f32_16x16x32_bf16 v[120:123], v[56:59], v[206:209], v[120:123]
	v_mfma_f32_16x16x32_bf16 v[108:111], v[48:51], v[214:217], v[108:111]
	v_mfma_f32_16x16x32_bf16 v[104:107], v[56:59], v[214:217], v[104:107]
	v_mfma_f32_16x16x32_bf16 v[156:159], v[52:55], v[68:71], v[156:159]
	v_mfma_f32_16x16x32_bf16 v[152:155], v[60:63], v[68:71], v[152:155]
	v_mfma_f32_16x16x32_bf16 v[140:143], v[52:55], v[84:87], v[140:143]
	v_mfma_f32_16x16x32_bf16 v[136:139], v[60:63], v[84:87], v[136:139]
	v_mfma_f32_16x16x32_bf16 v[124:127], v[52:55], v[210:213], v[124:127]
	v_mfma_f32_16x16x32_bf16 v[120:123], v[60:63], v[210:213], v[120:123]
	v_mfma_f32_16x16x32_bf16 v[108:111], v[52:55], v[218:221], v[108:111]
	v_mfma_f32_16x16x32_bf16 v[104:107], v[60:63], v[218:221], v[104:107]
	s_setprio 0
	s_setprio 1
	v_mfma_f32_16x16x32_bf16 v[148:151], v[168:171], v[64:67], v[148:151]
	v_mfma_f32_16x16x32_bf16 v[64:67], v[182:185], v[64:67], v[144:147]
	v_mfma_f32_16x16x32_bf16 v[144:147], v[202:205], v[68:71], v[64:67]
	v_mfma_f32_16x16x32_bf16 v[64:67], v[168:171], v[80:83], v[132:135]
	v_mfma_f32_16x16x32_bf16 v[132:135], v[178:181], v[84:87], v[64:67]
	v_mfma_f32_16x16x32_bf16 v[64:67], v[182:185], v[80:83], v[128:131]
	v_mfma_f32_16x16x32_bf16 v[128:131], v[202:205], v[84:87], v[64:67]
	v_mfma_f32_16x16x32_bf16 v[64:67], v[168:171], v[206:209], v[116:119]
	v_mfma_f32_16x16x32_bf16 v[116:119], v[178:181], v[210:213], v[64:67]
	v_mfma_f32_16x16x32_bf16 v[64:67], v[182:185], v[206:209], v[112:115]
	v_mfma_f32_16x16x32_bf16 v[112:115], v[202:205], v[210:213], v[64:67]
	v_mfma_f32_16x16x32_bf16 v[64:67], v[168:171], v[214:217], v[100:103]
	v_mfma_f32_16x16x32_bf16 v[100:103], v[178:181], v[218:221], v[64:67]
	v_mfma_f32_16x16x32_bf16 v[64:67], v[182:185], v[214:217], v[96:99]
	v_mfma_f32_16x16x32_bf16 v[148:151], v[178:181], v[68:71], v[148:151]
	v_mfma_f32_16x16x32_bf16 v[96:99], v[202:205], v[218:221], v[64:67]
	s_setprio 0
	s_barrier
; #define PG8_STAGE(bufoff, gbase, voff) do { _Pragma("unroll") for (int _i = 0; _i < 2; ++_i) \
;         __builtin_amdgcn_global_load_lds((const unsigned*)((const char*)(gbase) + (voff)[_i]), (PG8_LAS unsigned*)(lds + (bufoff) + ldsw + _i * 8192), 16, 0, 0); } while (0)
; #define PG8_LDA(dst, b, h) do { _Pragma("unroll") for (int m = 0; m < 4; ++m) _Pragma("unroll") for (int k = 0; k < 2; ++k) dst[m][k] = *(const PG8_LAS bf16x8*)(lds + PG8_SA(b, h) + aoff + m * 2048 + k * 1024); } while (0)
; #define PG8_LDB(dst, b, h) do { _Pragma("unroll") for (int n = 0; n < 2; ++n) _Pragma("unroll") for (int k = 0; k < 2; ++k) dst[n][k] = *(const PG8_LAS bf16x8*)(lds + PG8_SB(b, h) + boff + n * 2048 + k * 1024); } while (0)
; #define PG8_MMA(ai, bj, At, Bt) do { __builtin_amdgcn_s_setprio(1); _Pragma("unroll") for (int m = 0; m < 4; ++m) _Pragma("unroll") for (int n = 0; n < 2; ++n) _Pragma("unroll") for (int k = 0; k < 2; ++k) \
;         acc[ai][bj][m][n] = __builtin_amdgcn_mfma_f32_16x16x32_bf16(Bt[n][k], At[m][k], acc[ai][bj][m][n], 0, 0, 0); __builtin_amdgcn_s_setprio(0); } while (0)
; template <class Epi, class Sched, bool ALIGN_EPI = false, bool SP2 = false>
; __device__ __forceinline__ void gemm_phase(PG8_LAS unsigned char* lds, const Gemm g, const Sched& S, const Epi& E) {
;     ...
;             if constexpr (SP2) {
;             PG8_LDB(B0, 0, 0); PG8_LDB(B1, 0, 1); PG8_SCHED; PG8_LDA(At, 0, 0); PG8_STAGE(PG8_SA(1, 1), a1 + hstepA, voffA);
;             PG8_WAIT_V(8); PG8_WAIT_L(0); PG8_BAR; PG8_MMA(0, 0, At, B0); PG8_MMA(0, 1, At, B1); PG8_BAR; PG8_SCHED;
;             PG8_LDA(At, 0, 1); PG8_STAGE(PG8_SB(0, 0), b2, voffB); PG8_STAGE(PG8_SB(0, 1), b2 + hstepB, voffB); PG8_STAGE(PG8_SA(0, 0), a2, voffA);
;             PG8_WAIT_V(8); PG8_WAIT_L(0); PG8_BAR; PG8_MMA(1, 0, At, B0); PG8_MMA(1, 1, At, B1); PG8_BAR; PG8_SCHED;
;             PG8_LDB(B0, 1, 0); PG8_LDB(B1, 1, 1); PG8_SCHED; PG8_LDA(At, 1, 0); PG8_STAGE(PG8_SA(0, 1), a2 + hstepA, voffA);
;             PG8_WAIT_V(8); PG8_WAIT_L(0); PG8_BAR; PG8_MMA(0, 0, At, B0); PG8_MMA(0, 1, At, B1); PG8_BAR; PG8_SCHED;
;             PG8_LDA(At, 1, 1); PG8_STAGE(PG8_SB(1, 0), b3, voffB); PG8_STAGE(PG8_SB(1, 1), b3 + hstepB, voffB); PG8_STAGE(PG8_SA(1, 0), a3, voffA);
;             PG8_WAIT_V(8); PG8_WAIT_L(0); PG8_BAR; PG8_MMA(1, 0, At, B0); PG8_MMA(1, 1, At, B1); PG8_BAR; PG8_SCHED;
	s_add_i32 s14, s61, s91
	v_lshl_add_u64 v[80:81], v[174:175], 0, s[80:81]
	s_mov_b32 m0, s14
	s_nop 0
	ds_read_b128 v[64:67], v201 offset:49152
	ds_read_b128 v[68:71], v201 offset:50176
	ds_read_b128 v[206:209], v201 offset:51200
	ds_read_b128 v[210:213], v201 offset:52224
	ds_read_b128 v[214:217], v201 offset:53248
	ds_read_b128 v[218:221], v201 offset:54272
	ds_read_b128 v[222:225], v201 offset:55296
	ds_read_b128 v[226:229], v201 offset:56320
	global_load_lds_dwordx4 v[80:81], off
	s_add_i32 m0, s14, 0x2000
	s_add_u32 s12, s12, 0x40080
	v_lshl_add_u64 v[80:81], v[176:177], 0, s[80:81]
	s_addc_u32 s13, s13, 0
	s_add_i32 s14, s63, s91
	global_load_lds_dwordx4 v[80:81], off
	s_mov_b32 m0, s14
	s_nop 0
	global_load_lds_dwordx4 v160, s[12:13]
	s_add_i32 m0, s14, 0x2000
	s_nop 0
	global_load_lds_dwordx4 v162, s[12:13]
	v_lshl_add_u64 v[80:81], v[186:187], 0, s[80:81]
	s_mov_b32 m0, s77
	s_nop 0
	global_load_lds_dwordx4 v[80:81], off
	v_lshl_add_u64 v[80:81], v[192:193], 0, s[80:81]
	s_mov_b32 m0, s1
	s_nop 0
	global_load_lds_dwordx4 v[80:81], off
	s_waitcnt vmcnt(8)
	s_waitcnt lgkmcnt(0)
	s_barrier
	s_setprio 1
	s_waitcnt lgkmcnt(0)
	v_mfma_f32_16x16x32_bf16 v[80:83], v[48:51], v[64:67], v[92:95]
	v_mfma_f32_16x16x32_bf16 v[92:95], v[52:55], v[68:71], v[80:83]
	v_mfma_f32_16x16x32_bf16 v[80:83], v[56:59], v[64:67], v[88:91]
	v_mfma_f32_16x16x32_bf16 v[76:79], v[48:51], v[206:209], v[76:79]
	v_mfma_f32_16x16x32_bf16 v[72:75], v[56:59], v[206:209], v[72:75]
	v_mfma_f32_16x16x32_bf16 v[28:31], v[48:51], v[214:217], v[28:31]
	v_mfma_f32_16x16x32_bf16 v[24:27], v[56:59], v[214:217], v[24:27]
	v_mfma_f32_16x16x32_bf16 v[12:15], v[48:51], v[222:225], v[12:15]
	v_mfma_f32_16x16x32_bf16 v[8:11], v[56:59], v[222:225], v[8:11]
	v_mfma_f32_16x16x32_bf16 v[88:91], v[60:63], v[68:71], v[80:83]
	v_mfma_f32_16x16x32_bf16 v[76:79], v[52:55], v[210:213], v[76:79]
	v_mfma_f32_16x16x32_bf16 v[72:75], v[60:63], v[210:213], v[72:75]
	v_mfma_f32_16x16x32_bf16 v[28:31], v[52:55], v[218:221], v[28:31]
	v_mfma_f32_16x16x32_bf16 v[24:27], v[60:63], v[218:221], v[24:27]
	v_mfma_f32_16x16x32_bf16 v[12:15], v[52:55], v[226:229], v[12:15]
	v_mfma_f32_16x16x32_bf16 v[8:11], v[60:63], v[226:229], v[8:11]
	s_setprio 0
	s_setprio 1
	v_mfma_f32_16x16x32_bf16 v[32:35], v[168:171], v[64:67], v[32:35]
	v_mfma_f32_16x16x32_bf16 v[84:87], v[178:181], v[68:71], v[32:35]
	v_mfma_f32_16x16x32_bf16 v[32:35], v[182:185], v[64:67], v[36:39]
	v_mfma_f32_16x16x32_bf16 v[80:83], v[202:205], v[68:71], v[32:35]
	v_mfma_f32_16x16x32_bf16 v[32:35], v[168:171], v[206:209], v[40:43]
	v_mfma_f32_16x16x32_bf16 v[68:71], v[178:181], v[210:213], v[32:35]
	v_mfma_f32_16x16x32_bf16 v[32:35], v[182:185], v[206:209], v[44:47]
	v_mfma_f32_16x16x32_bf16 v[20:23], v[168:171], v[214:217], v[20:23]
	v_mfma_f32_16x16x32_bf16 v[16:19], v[182:185], v[214:217], v[16:19]
	v_mfma_f32_16x16x32_bf16 v[4:7], v[168:171], v[222:225], v[4:7]
	v_mfma_f32_16x16x32_bf16 v[0:3], v[182:185], v[222:225], v[0:3]
	v_mfma_f32_16x16x32_bf16 v[64:67], v[202:205], v[210:213], v[32:35]
	v_mfma_f32_16x16x32_bf16 v[20:23], v[178:181], v[218:221], v[20:23]
	v_mfma_f32_16x16x32_bf16 v[16:19], v[202:205], v[218:221], v[16:19]
	v_mfma_f32_16x16x32_bf16 v[4:7], v[178:181], v[226:229], v[4:7]
	v_mfma_f32_16x16x32_bf16 v[0:3], v[202:205], v[226:229], v[0:3]
	s_setprio 0
	s_barrier
	s_add_i32 s21, s21, 2
	s_add_u32 s10, s10, 0x100
	s_addc_u32 s11, s11, 0
	s_add_u32 s19, s19, 0x100
	s_addc_u32 s20, s20, 0
	s_cmp_gt_u32 s21, 13
	s_cbranch_scc0 .LBB0_780
	s_and_b64 vcc, exec, s[56:57]
	s_cbranch_vccz .LBB0_783
	s_barrier

; #define PG8_STAGE(bufoff, gbase, voff) do { _Pragma("unroll") for (int _i = 0; _i < 2; ++_i) \
;         __builtin_amdgcn_global_load_lds((const unsigned*)((const char*)(gbase) + (voff)[_i]), (PG8_LAS unsigned*)(lds + (bufoff) + ldsw + _i * 8192), 16, 0, 0); } while (0)
; #define PG8_LDA(dst, b, h) do { _Pragma("unroll") for (int m = 0; m < 4; ++m) _Pragma("unroll") for (int k = 0; k < 2; ++k) dst[m][k] = *(const PG8_LAS bf16x8*)(lds + PG8_SA(b, h) + aoff + m * 2048 + k * 1024); } while (0)
; #define PG8_LDB(dst, b, h) do { _Pragma("unroll") for (int n = 0; n < 2; ++n) _Pragma("unroll") for (int k = 0; k < 2; ++k) dst[n][k] = *(const PG8_LAS bf16x8*)(lds + PG8_SB(b, h) + boff + n * 2048 + k * 1024); } while (0)
; template <class Epi, class Sched, bool ALIGN_EPI = false, bool SP2 = false>
; __device__ __forceinline__ void gemm_phase(PG8_LAS unsigned char* lds, const Gemm g, const Sched& S, const Epi& E) {
;     ...
;         for (int t = 0; t < nt; t += 2) {
;             const bool last = (t == nt - 2);
;             const char* a1 = cA + (size_t)(t + 1) * kstep;
;             const char* a2 = last ? nA : cA + (size_t)(t + 2) * kstep; const char* b2 = last ? nB : cB + (size_t)(t + 2) * kstep;
;             const char* a3 = a2 + kstep; const char* b3 = b2 + kstep;
;             if (last && has_next) S.a_ready(nxt);
;             if constexpr (SP2) {
;             PG8_LDB(B0, 0, 0); PG8_LDB(B1, 0, 1); PG8_SCHED; PG8_LDA(At, 0, 0); PG8_STAGE(PG8_SA(1, 1), a1 + hstepA, voffA);
;             PG8_WAIT_V(8); PG8_WAIT_L(0); PG8_BAR; PG8_MMA(0, 0, At, B0); PG8_MMA(0, 1, At, B1); PG8_BAR; PG8_SCHED;
;             PG8_LDA(At, 0, 1); PG8_STAGE(PG8_SB(0, 0), b2, voffB); PG8_STAGE(PG8_SB(0, 1), b2 + hstepB, voffB); PG8_STAGE(PG8_SA(0, 0), a2, voffA);
;             PG8_WAIT_V(8); PG8_WAIT_L(0); PG8_BAR; PG8_MMA(1, 0, At, B0); PG8_MMA(1, 1, At, B1); PG8_BAR; PG8_SCHED;
;             PG8_LDB(B0, 1, 0); PG8_LDB(B1, 1, 1); PG8_SCHED; PG8_LDA(At, 1, 0); PG8_STAGE(PG8_SA(0, 1), a2 + hstepA, voffA);
;             PG8_WAIT_V(8); PG8_WAIT_L(0); PG8_BAR; PG8_MMA(0, 0, At, B0); PG8_MMA(0, 1, At, B1); PG8_BAR; PG8_SCHED;
;             PG8_LDA(At, 1, 1); PG8_STAGE(PG8_SB(1, 0), b3, voffB); PG8_STAGE(PG8_SB(1, 1), b3 + hstepB, voffB); PG8_STAGE(PG8_SA(1, 0), a3, voffA);
;             PG8_WAIT_V(8); PG8_WAIT_L(0); PG8_BAR; PG8_MMA(1, 0, At, B0); PG8_MMA(1, 1, At, B1); PG8_BAR; PG8_SCHED;
.LBB0_1303:
	s_add_u32 s8, s28, 0x100
	s_addc_u32 s9, s29, 0
	s_add_i32 s63, 0, 0x10000
	s_cmp_eq_u32 s62, 2
	s_cselect_b32 s35, s25, s9
	s_cselect_b32 s34, s24, s8
	v_add_u32_e32 v142, s63, v147
	s_cselect_b32 s31, s27, s61
	s_cselect_b32 s30, s26, s59
	s_add_i32 s64, 0, 0x14000
	ds_read_b128 v[138:141], v142
	ds_read_b128 v[150:153], v142 offset:1024
	ds_read_b128 v[154:157], v142 offset:2048
	ds_read_b128 v[158:161], v142 offset:3072
	v_add_u32_e32 v142, s64, v147
	ds_read_b128 v[162:165], v142
	ds_read_b128 v[166:169], v142 offset:1024
	ds_read_b128 v[178:181], v142 offset:2048
	ds_read_b128 v[182:185], v142 offset:3072
	v_lshl_add_u64 v[142:143], s[28:29], 0, v[134:135]
	s_add_i32 m0, s46, 0xc000
	ds_read_b128 v[196:199], v149
	ds_read_b128 v[200:203], v149 offset:1024
	ds_read_b128 v[204:207], v149 offset:2048
	ds_read_b128 v[208:211], v149 offset:3072
	ds_read_b128 v[212:215], v149 offset:4096
	ds_read_b128 v[216:219], v149 offset:5120
	ds_read_b128 v[220:223], v149 offset:6144
	ds_read_b128 v[224:227], v149 offset:7168
	global_load_lds_dwordx4 v[142:143], off
	v_lshl_add_u64 v[142:143], s[28:29], 0, v[136:137]
	s_add_i32 m0, s46, 0xe000
	s_nop 0
	global_load_lds_dwordx4 v[142:143], off
	s_waitcnt vmcnt(8)
	s_waitcnt lgkmcnt(0)
	s_barrier
	s_setprio 1
	s_waitcnt lgkmcnt(0)
	v_mfma_f32_16x16x32_bf16 v[124:127], v[138:141], v[196:199], v[124:127]
	v_mfma_f32_16x16x32_bf16 v[120:123], v[154:157], v[196:199], v[120:123]
	v_mfma_f32_16x16x32_bf16 v[108:111], v[138:141], v[204:207], v[108:111]
	v_mfma_f32_16x16x32_bf16 v[104:107], v[154:157], v[204:207], v[104:107]
	v_mfma_f32_16x16x32_bf16 v[92:95], v[138:141], v[212:215], v[92:95]
	v_mfma_f32_16x16x32_bf16 v[88:91], v[154:157], v[212:215], v[88:91]
	v_mfma_f32_16x16x32_bf16 v[76:79], v[138:141], v[220:223], v[76:79]
	v_mfma_f32_16x16x32_bf16 v[72:75], v[154:157], v[220:223], v[72:75]
	v_mfma_f32_16x16x32_bf16 v[124:127], v[150:153], v[200:203], v[124:127]
	v_mfma_f32_16x16x32_bf16 v[120:123], v[158:161], v[200:203], v[120:123]
	v_mfma_f32_16x16x32_bf16 v[108:111], v[150:153], v[208:211], v[108:111]
	v_mfma_f32_16x16x32_bf16 v[104:107], v[158:161], v[208:211], v[104:107]
	v_mfma_f32_16x16x32_bf16 v[92:95], v[150:153], v[216:219], v[92:95]
	v_mfma_f32_16x16x32_bf16 v[88:91], v[158:161], v[216:219], v[88:91]
	v_mfma_f32_16x16x32_bf16 v[76:79], v[150:153], v[224:227], v[76:79]
	v_mfma_f32_16x16x32_bf16 v[72:75], v[158:161], v[224:227], v[72:75]
	s_setprio 0
	s_setprio 1
	v_mfma_f32_16x16x32_bf16 v[116:119], v[162:165], v[196:199], v[116:119]
	v_mfma_f32_16x16x32_bf16 v[112:115], v[178:181], v[196:199], v[112:115]
	v_mfma_f32_16x16x32_bf16 v[100:103], v[162:165], v[204:207], v[100:103]
	v_mfma_f32_16x16x32_bf16 v[96:99], v[178:181], v[204:207], v[96:99]
	v_mfma_f32_16x16x32_bf16 v[84:87], v[162:165], v[212:215], v[84:87]
	v_mfma_f32_16x16x32_bf16 v[80:83], v[178:181], v[212:215], v[80:83]
	v_mfma_f32_16x16x32_bf16 v[68:71], v[162:165], v[220:223], v[68:71]
	v_mfma_f32_16x16x32_bf16 v[64:67], v[178:181], v[220:223], v[64:67]
	v_mfma_f32_16x16x32_bf16 v[116:119], v[166:169], v[200:203], v[116:119]
	v_mfma_f32_16x16x32_bf16 v[112:115], v[182:185], v[200:203], v[112:115]
	v_mfma_f32_16x16x32_bf16 v[100:103], v[166:169], v[208:211], v[100:103]
	v_mfma_f32_16x16x32_bf16 v[96:99], v[182:185], v[208:211], v[96:99]
	v_mfma_f32_16x16x32_bf16 v[84:87], v[166:169], v[216:219], v[84:87]
	v_mfma_f32_16x16x32_bf16 v[80:83], v[182:185], v[216:219], v[80:83]
	v_mfma_f32_16x16x32_bf16 v[68:71], v[166:169], v[224:227], v[68:71]
	v_mfma_f32_16x16x32_bf16 v[64:67], v[182:185], v[224:227], v[64:67]
	s_setprio 0
	s_barrier
	s_add_i32 s28, s63, s43
	v_lshl_add_u64 v[142:143], s[30:31], 0, v[172:173]
	s_mov_b32 m0, s28
	ds_read_b128 v[196:199], v149 offset:16384
	ds_read_b128 v[200:203], v149 offset:17408
	ds_read_b128 v[204:207], v149 offset:18432
	ds_read_b128 v[208:211], v149 offset:19456
	ds_read_b128 v[212:215], v149 offset:20480
	ds_read_b128 v[216:219], v149 offset:21504
	ds_read_b128 v[220:223], v149 offset:22528
	ds_read_b128 v[224:227], v149 offset:23552
	global_load_lds_dwordx4 v[142:143], off
	s_add_i32 m0, s28, 0x2000
	s_add_u32 s28, s30, 0x6000
	v_lshl_add_u64 v[170:171], s[30:31], 0, v[132:133]
	s_addc_u32 s29, s31, 0
	s_add_i32 s63, s64, s43
	global_load_lds_dwordx4 v[170:171], off
	s_mov_b32 m0, s63
	v_lshl_add_u64 v[176:177], s[34:35], 0, v[130:131]
	global_load_lds_dwordx4 v172, s[28:29]
	s_add_i32 m0, s63, 0x2000
	s_nop 0
	global_load_lds_dwordx4 v132, s[28:29]
	v_lshl_add_u64 v[174:175], s[34:35], 0, v[128:129]
	s_mov_b32 m0, s46
	s_nop 0
	global_load_lds_dwordx4 v[174:175], off
	s_mov_b32 m0, s47
	s_nop 0
	global_load_lds_dwordx4 v[176:177], off
	s_waitcnt vmcnt(8)
	s_waitcnt lgkmcnt(0)
	s_barrier
; #define PG8_STAGE(bufoff, gbase, voff) do { _Pragma("unroll") for (int _i = 0; _i < 2; ++_i) \
;         __builtin_amdgcn_global_load_lds((const unsigned*)((const char*)(gbase) + (voff)[_i]), (PG8_LAS unsigned*)(lds + (bufoff) + ldsw + _i * 8192), 16, 0, 0); } while (0)
; #define PG8_LDA(dst, b, h) do { _Pragma("unroll") for (int m = 0; m < 4; ++m) _Pragma("unroll") for (int k = 0; k < 2; ++k) dst[m][k] = *(const PG8_LAS bf16x8*)(lds + PG8_SA(b, h) + aoff + m * 2048 + k * 1024); } while (0)
; #define PG8_LDB(dst, b, h) do { _Pragma("unroll") for (int n = 0; n < 2; ++n) _Pragma("unroll") for (int k = 0; k < 2; ++k) dst[n][k] = *(const PG8_LAS bf16x8*)(lds + PG8_SB(b, h) + boff + n * 2048 + k * 1024); } while (0)
; #define PG8_MMA(ai, bj, At, Bt) do { __builtin_amdgcn_s_setprio(1); _Pragma("unroll") for (int m = 0; m < 4; ++m) _Pragma("unroll") for (int n = 0; n < 2; ++n) _Pragma("unroll") for (int k = 0; k < 2; ++k) \
;         acc[ai][bj][m][n] = __builtin_amdgcn_mfma_f32_16x16x32_bf16(Bt[n][k], At[m][k], acc[ai][bj][m][n], 0, 0, 0); __builtin_amdgcn_s_setprio(0); } while (0)
; template <class Epi, class Sched, bool ALIGN_EPI = false, bool SP2 = false>
; __device__ __forceinline__ void gemm_phase(PG8_LAS unsigned char* lds, const Gemm g, const Sched& S, const Epi& E) {
;     ...
;             if constexpr (SP2) {
;             PG8_LDB(B0, 0, 0); PG8_LDB(B1, 0, 1); PG8_SCHED; PG8_LDA(At, 0, 0); PG8_STAGE(PG8_SA(1, 1), a1 + hstepA, voffA);
;             PG8_WAIT_V(8); PG8_WAIT_L(0); PG8_BAR; PG8_MMA(0, 0, At, B0); PG8_MMA(0, 1, At, B1); PG8_BAR; PG8_SCHED;
;             PG8_LDA(At, 0, 1); PG8_STAGE(PG8_SB(0, 0), b2, voffB); PG8_STAGE(PG8_SB(0, 1), b2 + hstepB, voffB); PG8_STAGE(PG8_SA(0, 0), a2, voffA);
;             PG8_WAIT_V(8); PG8_WAIT_L(0); PG8_BAR; PG8_MMA(1, 0, At, B0); PG8_MMA(1, 1, At, B1); PG8_BAR; PG8_SCHED;
;             PG8_LDB(B0, 1, 0); PG8_LDB(B1, 1, 1); PG8_SCHED; PG8_LDA(At, 1, 0); PG8_STAGE(PG8_SA(0, 1), a2 + hstepA, voffA);
;             PG8_WAIT_V(8); PG8_WAIT_L(0); PG8_BAR; PG8_MMA(0, 0, At, B0); PG8_MMA(0, 1, At, B1); PG8_BAR; PG8_SCHED;
;             PG8_LDA(At, 1, 1); PG8_STAGE(PG8_SB(1, 0), b3, voffB); PG8_STAGE(PG8_SB(1, 1), b3 + hstepB, voffB); PG8_STAGE(PG8_SA(1, 0), a3, voffA);
;             PG8_WAIT_V(8); PG8_WAIT_L(0); PG8_BAR; PG8_MMA(1, 0, At, B0); PG8_MMA(1, 1, At, B1); PG8_BAR; PG8_SCHED;
	s_setprio 1
	s_waitcnt lgkmcnt(0)
	v_mfma_f32_16x16x32_bf16 v[60:63], v[138:141], v[196:199], v[60:63]
	v_mfma_f32_16x16x32_bf16 v[56:59], v[154:157], v[196:199], v[56:59]
	v_mfma_f32_16x16x32_bf16 v[44:47], v[138:141], v[204:207], v[44:47]
	v_mfma_f32_16x16x32_bf16 v[40:43], v[154:157], v[204:207], v[40:43]
	v_mfma_f32_16x16x32_bf16 v[28:31], v[138:141], v[212:215], v[28:31]
	v_mfma_f32_16x16x32_bf16 v[24:27], v[154:157], v[212:215], v[24:27]
	v_mfma_f32_16x16x32_bf16 v[12:15], v[138:141], v[220:223], v[12:15]
	v_mfma_f32_16x16x32_bf16 v[8:11], v[154:157], v[220:223], v[8:11]
	v_mfma_f32_16x16x32_bf16 v[60:63], v[150:153], v[200:203], v[60:63]
	v_mfma_f32_16x16x32_bf16 v[56:59], v[158:161], v[200:203], v[56:59]
	v_mfma_f32_16x16x32_bf16 v[44:47], v[150:153], v[208:211], v[44:47]
	v_mfma_f32_16x16x32_bf16 v[40:43], v[158:161], v[208:211], v[40:43]
	v_mfma_f32_16x16x32_bf16 v[28:31], v[150:153], v[216:219], v[28:31]
	v_mfma_f32_16x16x32_bf16 v[24:27], v[158:161], v[216:219], v[24:27]
	v_mfma_f32_16x16x32_bf16 v[12:15], v[150:153], v[224:227], v[12:15]
	v_mfma_f32_16x16x32_bf16 v[8:11], v[158:161], v[224:227], v[8:11]
	s_setprio 0
	s_setprio 1
	v_mfma_f32_16x16x32_bf16 v[52:55], v[162:165], v[196:199], v[52:55]
	v_mfma_f32_16x16x32_bf16 v[48:51], v[178:181], v[196:199], v[48:51]
	v_mfma_f32_16x16x32_bf16 v[36:39], v[162:165], v[204:207], v[36:39]
	v_mfma_f32_16x16x32_bf16 v[32:35], v[178:181], v[204:207], v[32:35]
	v_mfma_f32_16x16x32_bf16 v[20:23], v[162:165], v[212:215], v[20:23]
	v_mfma_f32_16x16x32_bf16 v[16:19], v[178:181], v[212:215], v[16:19]
	v_mfma_f32_16x16x32_bf16 v[4:7], v[162:165], v[220:223], v[4:7]
	v_mfma_f32_16x16x32_bf16 v[0:3], v[178:181], v[220:223], v[0:3]
	v_mfma_f32_16x16x32_bf16 v[52:55], v[166:169], v[200:203], v[52:55]
	v_mfma_f32_16x16x32_bf16 v[48:51], v[182:185], v[200:203], v[48:51]
	v_mfma_f32_16x16x32_bf16 v[36:39], v[166:169], v[208:211], v[36:39]
	v_mfma_f32_16x16x32_bf16 v[32:35], v[182:185], v[208:211], v[32:35]
	v_mfma_f32_16x16x32_bf16 v[20:23], v[166:169], v[216:219], v[20:23]
	v_mfma_f32_16x16x32_bf16 v[16:19], v[182:185], v[216:219], v[16:19]
	v_mfma_f32_16x16x32_bf16 v[4:7], v[166:169], v[224:227], v[4:7]
	v_mfma_f32_16x16x32_bf16 v[0:3], v[182:185], v[224:227], v[0:3]
	s_setprio 0
	s_barrier
	s_add_i32 s63, 0, 0x18000
	v_add_u32_e32 v144, s63, v147
	s_add_i32 s64, 0, 0x1c000
	ds_read_b128 v[138:141], v144
	ds_read_b128 v[150:153], v144 offset:1024
	ds_read_b128 v[154:157], v144 offset:2048
	ds_read_b128 v[158:161], v144 offset:3072
	v_add_u32_e32 v144, s64, v147
	ds_read_b128 v[162:165], v144
	ds_read_b128 v[166:169], v144 offset:1024
	ds_read_b128 v[178:181], v144 offset:2048
	ds_read_b128 v[182:185], v144 offset:3072
	s_add_u32 s28, s34, 0x18000
	s_addc_u32 s29, s35, 0
	s_mov_b32 m0, s50
	ds_read_b128 v[196:199], v149 offset:32768
	ds_read_b128 v[200:203], v149 offset:33792
	ds_read_b128 v[204:207], v149 offset:34816
	ds_read_b128 v[208:211], v149 offset:35840
	ds_read_b128 v[212:215], v149 offset:36864
	ds_read_b128 v[216:219], v149 offset:37888
	ds_read_b128 v[220:223], v149 offset:38912
	ds_read_b128 v[224:227], v149 offset:39936
	global_load_lds_dwordx4 v128, s[28:29]
	v_lshl_add_u64 v[186:187], s[28:29], 0, v[130:131]
	s_mov_b32 m0, s51
	s_nop 0
	global_load_lds_dwordx4 v[186:187], off
	s_waitcnt vmcnt(8)
	s_waitcnt lgkmcnt(0)
	s_barrier
	s_setprio 1
	s_waitcnt lgkmcnt(0)
	v_mfma_f32_16x16x32_bf16 v[124:127], v[138:141], v[196:199], v[124:127]
	v_mfma_f32_16x16x32_bf16 v[120:123], v[154:157], v[196:199], v[120:123]
	v_mfma_f32_16x16x32_bf16 v[108:111], v[138:141], v[204:207], v[108:111]
	v_mfma_f32_16x16x32_bf16 v[104:107], v[154:157], v[204:207], v[104:107]
	v_mfma_f32_16x16x32_bf16 v[92:95], v[138:141], v[212:215], v[92:95]
	v_mfma_f32_16x16x32_bf16 v[88:91], v[154:157], v[212:215], v[88:91]
	v_mfma_f32_16x16x32_bf16 v[76:79], v[138:141], v[220:223], v[76:79]
	v_mfma_f32_16x16x32_bf16 v[72:75], v[154:157], v[220:223], v[72:75]
	v_mfma_f32_16x16x32_bf16 v[124:127], v[150:153], v[200:203], v[124:127]
	v_mfma_f32_16x16x32_bf16 v[120:123], v[158:161], v[200:203], v[120:123]
	v_mfma_f32_16x16x32_bf16 v[108:111], v[150:153], v[208:211], v[108:111]
	v_mfma_f32_16x16x32_bf16 v[104:107], v[158:161], v[208:211], v[104:107]
	v_mfma_f32_16x16x32_bf16 v[92:95], v[150:153], v[216:219], v[92:95]
	v_mfma_f32_16x16x32_bf16 v[88:91], v[158:161], v[216:219], v[88:91]
	v_mfma_f32_16x16x32_bf16 v[76:79], v[150:153], v[224:227], v[76:79]
	v_mfma_f32_16x16x32_bf16 v[72:75], v[158:161], v[224:227], v[72:75]
	s_setprio 0
	s_setprio 1
	v_mfma_f32_16x16x32_bf16 v[116:119], v[162:165], v[196:199], v[116:119]
	v_mfma_f32_16x16x32_bf16 v[112:115], v[178:181], v[196:199], v[112:115]
	v_mfma_f32_16x16x32_bf16 v[100:103], v[162:165], v[204:207], v[100:103]
	v_mfma_f32_16x16x32_bf16 v[96:99], v[178:181], v[204:207], v[96:99]
	v_mfma_f32_16x16x32_bf16 v[84:87], v[162:165], v[212:215], v[84:87]
	v_mfma_f32_16x16x32_bf16 v[80:83], v[178:181], v[212:215], v[80:83]
	v_mfma_f32_16x16x32_bf16 v[68:71], v[162:165], v[220:223], v[68:71]
	v_mfma_f32_16x16x32_bf16 v[64:67], v[178:181], v[220:223], v[64:67]
	v_mfma_f32_16x16x32_bf16 v[116:119], v[166:169], v[200:203], v[116:119]
	v_mfma_f32_16x16x32_bf16 v[112:115], v[182:185], v[200:203], v[112:115]
	v_mfma_f32_16x16x32_bf16 v[100:103], v[166:169], v[208:211], v[100:103]
	v_mfma_f32_16x16x32_bf16 v[96:99], v[182:185], v[208:211], v[96:99]
	v_mfma_f32_16x16x32_bf16 v[84:87], v[166:169], v[216:219], v[84:87]
	v_mfma_f32_16x16x32_bf16 v[80:83], v[182:185], v[216:219], v[80:83]
	v_mfma_f32_16x16x32_bf16 v[68:71], v[166:169], v[224:227], v[68:71]
	v_mfma_f32_16x16x32_bf16 v[64:67], v[182:185], v[224:227], v[64:67]
	s_setprio 0
	s_barrier
; #define PG8_STAGE(bufoff, gbase, voff) do { _Pragma("unroll") for (int _i = 0; _i < 2; ++_i) \
;         __builtin_amdgcn_global_load_lds((const unsigned*)((const char*)(gbase) + (voff)[_i]), (PG8_LAS unsigned*)(lds + (bufoff) + ldsw + _i * 8192), 16, 0, 0); } while (0)
; #define PG8_LDA(dst, b, h) do { _Pragma("unroll") for (int m = 0; m < 4; ++m) _Pragma("unroll") for (int k = 0; k < 2; ++k) dst[m][k] = *(const PG8_LAS bf16x8*)(lds + PG8_SA(b, h) + aoff + m * 2048 + k * 1024); } while (0)
; #define PG8_LDB(dst, b, h) do { _Pragma("unroll") for (int n = 0; n < 2; ++n) _Pragma("unroll") for (int k = 0; k < 2; ++k) dst[n][k] = *(const PG8_LAS bf16x8*)(lds + PG8_SB(b, h) + boff + n * 2048 + k * 1024); } while (0)
; #define PG8_MMA(ai, bj, At, Bt) do { __builtin_amdgcn_s_setprio(1); _Pragma("unroll") for (int m = 0; m < 4; ++m) _Pragma("unroll") for (int n = 0; n < 2; ++n) _Pragma("unroll") for (int k = 0; k < 2; ++k) \
;         acc[ai][bj][m][n] = __builtin_amdgcn_mfma_f32_16x16x32_bf16(Bt[n][k], At[m][k], acc[ai][bj][m][n], 0, 0, 0); __builtin_amdgcn_s_setprio(0); } while (0)
; template <class Epi, class Sched, bool ALIGN_EPI = false, bool SP2 = false>
; __device__ __forceinline__ void gemm_phase(PG8_LAS unsigned char* lds, const Gemm g, const Sched& S, const Epi& E) {
;     ...
;             if constexpr (SP2) {
;             PG8_LDB(B0, 0, 0); PG8_LDB(B1, 0, 1); PG8_SCHED; PG8_LDA(At, 0, 0); PG8_STAGE(PG8_SA(1, 1), a1 + hstepA, voffA);
;             PG8_WAIT_V(8); PG8_WAIT_L(0); PG8_BAR; PG8_MMA(0, 0, At, B0); PG8_MMA(0, 1, At, B1); PG8_BAR; PG8_SCHED;
;             PG8_LDA(At, 0, 1); PG8_STAGE(PG8_SB(0, 0), b2, voffB); PG8_STAGE(PG8_SB(0, 1), b2 + hstepB, voffB); PG8_STAGE(PG8_SA(0, 0), a2, voffA);
;             PG8_WAIT_V(8); PG8_WAIT_L(0); PG8_BAR; PG8_MMA(1, 0, At, B0); PG8_MMA(1, 1, At, B1); PG8_BAR; PG8_SCHED;
;             PG8_LDB(B0, 1, 0); PG8_LDB(B1, 1, 1); PG8_SCHED; PG8_LDA(At, 1, 0); PG8_STAGE(PG8_SA(0, 1), a2 + hstepA, voffA);
;             PG8_WAIT_V(8); PG8_WAIT_L(0); PG8_BAR; PG8_MMA(0, 0, At, B0); PG8_MMA(0, 1, At, B1); PG8_BAR; PG8_SCHED;
;             PG8_LDA(At, 1, 1); PG8_STAGE(PG8_SB(1, 0), b3, voffB); PG8_STAGE(PG8_SB(1, 1), b3 + hstepB, voffB); PG8_STAGE(PG8_SA(1, 0), a3, voffA);
;             PG8_WAIT_V(8); PG8_WAIT_L(0); PG8_BAR; PG8_MMA(1, 0, At, B0); PG8_MMA(1, 1, At, B1); PG8_BAR; PG8_SCHED;
	s_add_i32 s28, s63, s43
	v_lshl_add_u64 v[142:143], v[142:143], 0, s[80:81]
	s_mov_b32 m0, s28
	ds_read_b128 v[196:199], v149 offset:49152
	ds_read_b128 v[200:203], v149 offset:50176
	ds_read_b128 v[204:207], v149 offset:51200
	ds_read_b128 v[208:211], v149 offset:52224
	ds_read_b128 v[212:215], v149 offset:53248
	ds_read_b128 v[216:219], v149 offset:54272
	ds_read_b128 v[220:223], v149 offset:55296
	ds_read_b128 v[224:227], v149 offset:56320
	global_load_lds_dwordx4 v[142:143], off
	s_add_i32 m0, s28, 0x2000
	s_add_u32 s28, s30, 0x6080
	v_lshl_add_u64 v[142:143], v[170:171], 0, s[80:81]
	s_addc_u32 s29, s31, 0
	s_add_i32 s30, s64, s43
	global_load_lds_dwordx4 v[142:143], off
	s_mov_b32 m0, s30
	s_nop 0
	global_load_lds_dwordx4 v172, s[28:29]
	s_add_i32 m0, s30, 0x2000
	s_nop 0
	global_load_lds_dwordx4 v132, s[28:29]
	v_lshl_add_u64 v[142:143], v[174:175], 0, s[80:81]
	s_mov_b32 m0, s52
	s_nop 0
	global_load_lds_dwordx4 v[142:143], off
	v_lshl_add_u64 v[142:143], v[176:177], 0, s[80:81]
	s_mov_b32 m0, s53
	s_nop 0
	global_load_lds_dwordx4 v[142:143], off
	s_waitcnt vmcnt(8)
	s_waitcnt lgkmcnt(0)
	s_barrier
	s_setprio 1
	s_waitcnt lgkmcnt(0)
	v_mfma_f32_16x16x32_bf16 v[60:63], v[138:141], v[196:199], v[60:63]
	v_mfma_f32_16x16x32_bf16 v[56:59], v[154:157], v[196:199], v[56:59]
	v_mfma_f32_16x16x32_bf16 v[44:47], v[138:141], v[204:207], v[44:47]
	v_mfma_f32_16x16x32_bf16 v[40:43], v[154:157], v[204:207], v[40:43]
	v_mfma_f32_16x16x32_bf16 v[28:31], v[138:141], v[212:215], v[28:31]
	v_mfma_f32_16x16x32_bf16 v[24:27], v[154:157], v[212:215], v[24:27]
	v_mfma_f32_16x16x32_bf16 v[12:15], v[138:141], v[220:223], v[12:15]
	v_mfma_f32_16x16x32_bf16 v[8:11], v[154:157], v[220:223], v[8:11]
	v_mfma_f32_16x16x32_bf16 v[60:63], v[150:153], v[200:203], v[60:63]
	v_mfma_f32_16x16x32_bf16 v[56:59], v[158:161], v[200:203], v[56:59]
	v_mfma_f32_16x16x32_bf16 v[44:47], v[150:153], v[208:211], v[44:47]
	v_mfma_f32_16x16x32_bf16 v[40:43], v[158:161], v[208:211], v[40:43]
	v_mfma_f32_16x16x32_bf16 v[28:31], v[150:153], v[216:219], v[28:31]
	v_mfma_f32_16x16x32_bf16 v[24:27], v[158:161], v[216:219], v[24:27]
	v_mfma_f32_16x16x32_bf16 v[12:15], v[150:153], v[224:227], v[12:15]
	v_mfma_f32_16x16x32_bf16 v[8:11], v[158:161], v[224:227], v[8:11]
	s_setprio 0
	s_setprio 1
	v_mfma_f32_16x16x32_bf16 v[52:55], v[162:165], v[196:199], v[52:55]
	v_mfma_f32_16x16x32_bf16 v[48:51], v[178:181], v[196:199], v[48:51]
	v_mfma_f32_16x16x32_bf16 v[36:39], v[162:165], v[204:207], v[36:39]
	v_mfma_f32_16x16x32_bf16 v[32:35], v[178:181], v[204:207], v[32:35]
	v_mfma_f32_16x16x32_bf16 v[20:23], v[162:165], v[212:215], v[20:23]
	v_mfma_f32_16x16x32_bf16 v[16:19], v[178:181], v[212:215], v[16:19]
	v_mfma_f32_16x16x32_bf16 v[4:7], v[162:165], v[220:223], v[4:7]
	v_mfma_f32_16x16x32_bf16 v[0:3], v[178:181], v[220:223], v[0:3]
	v_mfma_f32_16x16x32_bf16 v[52:55], v[166:169], v[200:203], v[52:55]
	v_mfma_f32_16x16x32_bf16 v[48:51], v[182:185], v[200:203], v[48:51]
	v_mfma_f32_16x16x32_bf16 v[36:39], v[166:169], v[208:211], v[36:39]
	v_mfma_f32_16x16x32_bf16 v[32:35], v[182:185], v[208:211], v[32:35]
	v_mfma_f32_16x16x32_bf16 v[20:23], v[166:169], v[216:219], v[20:23]
	v_mfma_f32_16x16x32_bf16 v[16:19], v[182:185], v[216:219], v[16:19]
	v_mfma_f32_16x16x32_bf16 v[4:7], v[166:169], v[224:227], v[4:7]
	v_mfma_f32_16x16x32_bf16 v[0:3], v[182:185], v[224:227], v[0:3]
	s_setprio 0
	s_barrier
	s_add_i32 s62, s62, 2
	s_add_u32 s59, s59, 0x100
	s_addc_u32 s61, s61, 0
	s_cmp_gt_u32 s62, 3
	s_mov_b64 s[28:29], s[8:9]
	s_cbranch_scc0 .LBB0_1303
	s_and_b64 vcc, exec, s[20:21]
	s_cbranch_vccz .LBB0_1306
	s_barrier

; #define PG8_STAGE(bufoff, gbase, voff) do { _Pragma("unroll") for (int _i = 0; _i < 2; ++_i) \
;         __builtin_amdgcn_global_load_lds((const unsigned*)((const char*)(gbase) + (voff)[_i]), (PG8_LAS unsigned*)(lds + (bufoff) + ldsw + _i * 8192), 16, 0, 0); } while (0)
; #define PG8_LDA(dst, b, h) do { _Pragma("unroll") for (int m = 0; m < 4; ++m) _Pragma("unroll") for (int k = 0; k < 2; ++k) dst[m][k] = *(const PG8_LAS bf16x8*)(lds + PG8_SA(b, h) + aoff + m * 2048 + k * 1024); } while (0)
; #define PG8_LDB(dst, b, h) do { _Pragma("unroll") for (int n = 0; n < 2; ++n) _Pragma("unroll") for (int k = 0; k < 2; ++k) dst[n][k] = *(const PG8_LAS bf16x8*)(lds + PG8_SB(b, h) + boff + n * 2048 + k * 1024); } while (0)
; template <class Epi, class Sched, bool ALIGN_EPI = false, bool SP2 = false>
; __device__ __forceinline__ void gemm_phase(PG8_LAS unsigned char* lds, const Gemm g, const Sched& S, const Epi& E) {
;     ...
;         for (int t = 0; t < nt; t += 2) {
;             const bool last = (t == nt - 2);
;             const char* a1 = cA + (size_t)(t + 1) * kstep;
;             const char* a2 = last ? nA : cA + (size_t)(t + 2) * kstep; const char* b2 = last ? nB : cB + (size_t)(t + 2) * kstep;
;             const char* a3 = a2 + kstep; const char* b3 = b2 + kstep;
;             if (last && has_next) S.a_ready(nxt);
;             if constexpr (SP2) {
;             PG8_LDB(B0, 0, 0); PG8_LDB(B1, 0, 1); PG8_SCHED; PG8_LDA(At, 0, 0); PG8_STAGE(PG8_SA(1, 1), a1 + hstepA, voffA);
;             PG8_WAIT_V(8); PG8_WAIT_L(0); PG8_BAR; PG8_MMA(0, 0, At, B0); PG8_MMA(0, 1, At, B1); PG8_BAR; PG8_SCHED;
;             PG8_LDA(At, 0, 1); PG8_STAGE(PG8_SB(0, 0), b2, voffB); PG8_STAGE(PG8_SB(0, 1), b2 + hstepB, voffB); PG8_STAGE(PG8_SA(0, 0), a2, voffA);
;             PG8_WAIT_V(8); PG8_WAIT_L(0); PG8_BAR; PG8_MMA(1, 0, At, B0); PG8_MMA(1, 1, At, B1); PG8_BAR; PG8_SCHED;
;             PG8_LDB(B0, 1, 0); PG8_LDB(B1, 1, 1); PG8_SCHED; PG8_LDA(At, 1, 0); PG8_STAGE(PG8_SA(0, 1), a2 + hstepA, voffA);
;             PG8_WAIT_V(8); PG8_WAIT_L(0); PG8_BAR; PG8_MMA(0, 0, At, B0); PG8_MMA(0, 1, At, B1); PG8_BAR; PG8_SCHED;
;             PG8_LDA(At, 1, 1); PG8_STAGE(PG8_SB(1, 0), b3, voffB); PG8_STAGE(PG8_SB(1, 1), b3 + hstepB, voffB); PG8_STAGE(PG8_SA(1, 0), a3, voffA);
;             PG8_WAIT_V(8); PG8_WAIT_L(0); PG8_BAR; PG8_MMA(1, 0, At, B0); PG8_MMA(1, 1, At, B1); PG8_BAR; PG8_SCHED;
.LBB0_1575:
	s_add_u32 s40, s38, 0xfffc0080
	s_addc_u32 s41, s39, -1
	s_add_i32 s67, 0, 0x10000
	s_cmp_eq_u32 s66, 12
	s_cselect_b32 s43, s27, s41
	s_cselect_b32 s42, s35, s40
	s_cselect_b32 s41, s25, s65
	s_cselect_b32 s40, s37, s64
	s_add_i32 s68, 0, 0x14000
	v_add_u32_e32 v92, s67, v181
	v_add_u32_e32 v164, s68, v181
	ds_read_b128 v[72:75], v92
	ds_read_b128 v[76:79], v92 offset:1024
	ds_read_b128 v[88:91], v92 offset:2048
	ds_read_b128 v[92:95], v92 offset:3072
	ds_read_b128 v[152:155], v164
	ds_read_b128 v[156:159], v164 offset:1024
	ds_read_b128 v[160:163], v164 offset:2048
	ds_read_b128 v[164:167], v164 offset:3072
	s_add_i32 m0, s51, 0xc000
	ds_read_b128 v[168:171], v186
	ds_read_b128 v[174:177], v186 offset:1024
	ds_read_b128 v[192:195], v186 offset:2048
	ds_read_b128 v[196:199], v186 offset:3072
	ds_read_b128 v[200:203], v186 offset:4096
	ds_read_b128 v[204:207], v186 offset:5120
	ds_read_b128 v[208:211], v186 offset:6144
	ds_read_b128 v[212:215], v186 offset:7168
	global_load_lds_dwordx4 v148, s[38:39]
	s_add_i32 m0, s51, 0xe000
	s_nop 0
	global_load_lds_dwordx4 v150, s[38:39]
	s_waitcnt vmcnt(8)
	s_waitcnt lgkmcnt(0)
	s_barrier
	s_setprio 1
	s_waitcnt lgkmcnt(0)
	v_mfma_f32_16x16x32_bf16 v[140:143], v[72:75], v[168:171], v[140:143]
	v_mfma_f32_16x16x32_bf16 v[136:139], v[88:91], v[168:171], v[136:139]
	v_mfma_f32_16x16x32_bf16 v[124:127], v[72:75], v[192:195], v[124:127]
	v_mfma_f32_16x16x32_bf16 v[120:123], v[88:91], v[192:195], v[120:123]
	v_mfma_f32_16x16x32_bf16 v[108:111], v[72:75], v[200:203], v[108:111]
	v_mfma_f32_16x16x32_bf16 v[104:107], v[88:91], v[200:203], v[104:107]
	v_mfma_f32_16x16x32_bf16 v[84:87], v[72:75], v[208:211], v[84:87]
	v_mfma_f32_16x16x32_bf16 v[80:83], v[88:91], v[208:211], v[80:83]
	v_mfma_f32_16x16x32_bf16 v[140:143], v[76:79], v[174:177], v[140:143]
	v_mfma_f32_16x16x32_bf16 v[136:139], v[92:95], v[174:177], v[136:139]
	v_mfma_f32_16x16x32_bf16 v[124:127], v[76:79], v[196:199], v[124:127]
	v_mfma_f32_16x16x32_bf16 v[120:123], v[92:95], v[196:199], v[120:123]
	v_mfma_f32_16x16x32_bf16 v[108:111], v[76:79], v[204:207], v[108:111]
	v_mfma_f32_16x16x32_bf16 v[104:107], v[92:95], v[204:207], v[104:107]
	v_mfma_f32_16x16x32_bf16 v[84:87], v[76:79], v[212:215], v[84:87]
	v_mfma_f32_16x16x32_bf16 v[80:83], v[92:95], v[212:215], v[80:83]
	s_setprio 0
	s_setprio 1
	v_mfma_f32_16x16x32_bf16 v[132:135], v[152:155], v[168:171], v[132:135]
	v_mfma_f32_16x16x32_bf16 v[128:131], v[160:163], v[168:171], v[128:131]
	v_mfma_f32_16x16x32_bf16 v[116:119], v[152:155], v[192:195], v[116:119]
	v_mfma_f32_16x16x32_bf16 v[112:115], v[160:163], v[192:195], v[112:115]
	v_mfma_f32_16x16x32_bf16 v[100:103], v[152:155], v[200:203], v[100:103]
	v_mfma_f32_16x16x32_bf16 v[96:99], v[160:163], v[200:203], v[96:99]
	v_mfma_f32_16x16x32_bf16 v[68:71], v[152:155], v[208:211], v[68:71]
	v_mfma_f32_16x16x32_bf16 v[64:67], v[160:163], v[208:211], v[64:67]
	v_mfma_f32_16x16x32_bf16 v[132:135], v[156:159], v[174:177], v[132:135]
	v_mfma_f32_16x16x32_bf16 v[128:131], v[164:167], v[174:177], v[128:131]
	v_mfma_f32_16x16x32_bf16 v[116:119], v[156:159], v[196:199], v[116:119]
	v_mfma_f32_16x16x32_bf16 v[112:115], v[164:167], v[196:199], v[112:115]
	v_mfma_f32_16x16x32_bf16 v[100:103], v[156:159], v[204:207], v[100:103]
	v_mfma_f32_16x16x32_bf16 v[96:99], v[164:167], v[204:207], v[96:99]
	v_mfma_f32_16x16x32_bf16 v[68:71], v[156:159], v[212:215], v[68:71]
	v_mfma_f32_16x16x32_bf16 v[64:67], v[164:167], v[212:215], v[64:67]
	s_setprio 0
	s_barrier
	s_add_i32 s67, s67, s50
	v_lshl_add_u64 v[178:179], s[40:41], 0, v[172:173]
	s_mov_b32 m0, s67
	ds_read_b128 v[168:171], v186 offset:16384
	ds_read_b128 v[174:177], v186 offset:17408
	ds_read_b128 v[192:195], v186 offset:18432
	ds_read_b128 v[196:199], v186 offset:19456
	ds_read_b128 v[200:203], v186 offset:20480
	ds_read_b128 v[204:207], v186 offset:21504
	ds_read_b128 v[208:211], v186 offset:22528
	ds_read_b128 v[212:215], v186 offset:23552
	global_load_lds_dwordx4 v[178:179], off
	s_add_i32 m0, s67, 0x2000
	s_add_u32 s70, s40, 0x40000
	v_lshl_add_u64 v[216:217], s[40:41], 0, v[144:145]
	s_addc_u32 s71, s41, 0
	s_add_i32 s67, s68, s50
	global_load_lds_dwordx4 v[216:217], off
	s_mov_b32 m0, s67
	v_lshl_add_u64 v[220:221], s[42:43], 0, v[144:145]
	global_load_lds_dwordx4 v172, s[70:71]
	s_add_i32 m0, s67, 0x2000
	s_nop 0
	global_load_lds_dwordx4 v144, s[70:71]
	v_lshl_add_u64 v[218:219], s[42:43], 0, v[172:173]
	s_mov_b32 m0, s51
	s_nop 0
	global_load_lds_dwordx4 v[218:219], off
	s_mov_b32 m0, s52
	s_nop 0
	global_load_lds_dwordx4 v[220:221], off
	s_waitcnt vmcnt(8)
	s_waitcnt lgkmcnt(0)
	s_barrier
; #define PG8_STAGE(bufoff, gbase, voff) do { _Pragma("unroll") for (int _i = 0; _i < 2; ++_i) \
;         __builtin_amdgcn_global_load_lds((const unsigned*)((const char*)(gbase) + (voff)[_i]), (PG8_LAS unsigned*)(lds + (bufoff) + ldsw + _i * 8192), 16, 0, 0); } while (0)
; #define PG8_LDA(dst, b, h) do { _Pragma("unroll") for (int m = 0; m < 4; ++m) _Pragma("unroll") for (int k = 0; k < 2; ++k) dst[m][k] = *(const PG8_LAS bf16x8*)(lds + PG8_SA(b, h) + aoff + m * 2048 + k * 1024); } while (0)
; #define PG8_LDB(dst, b, h) do { _Pragma("unroll") for (int n = 0; n < 2; ++n) _Pragma("unroll") for (int k = 0; k < 2; ++k) dst[n][k] = *(const PG8_LAS bf16x8*)(lds + PG8_SB(b, h) + boff + n * 2048 + k * 1024); } while (0)
; #define PG8_MMA(ai, bj, At, Bt) do { __builtin_amdgcn_s_setprio(1); _Pragma("unroll") for (int m = 0; m < 4; ++m) _Pragma("unroll") for (int n = 0; n < 2; ++n) _Pragma("unroll") for (int k = 0; k < 2; ++k) \
;         acc[ai][bj][m][n] = __builtin_amdgcn_mfma_f32_16x16x32_bf16(Bt[n][k], At[m][k], acc[ai][bj][m][n], 0, 0, 0); __builtin_amdgcn_s_setprio(0); } while (0)
; template <class Epi, class Sched, bool ALIGN_EPI = false, bool SP2 = false>
; __device__ __forceinline__ void gemm_phase(PG8_LAS unsigned char* lds, const Gemm g, const Sched& S, const Epi& E) {
;     ...
;             if constexpr (SP2) {
;             PG8_LDB(B0, 0, 0); PG8_LDB(B1, 0, 1); PG8_SCHED; PG8_LDA(At, 0, 0); PG8_STAGE(PG8_SA(1, 1), a1 + hstepA, voffA);
;             PG8_WAIT_V(8); PG8_WAIT_L(0); PG8_BAR; PG8_MMA(0, 0, At, B0); PG8_MMA(0, 1, At, B1); PG8_BAR; PG8_SCHED;
;             PG8_LDA(At, 0, 1); PG8_STAGE(PG8_SB(0, 0), b2, voffB); PG8_STAGE(PG8_SB(0, 1), b2 + hstepB, voffB); PG8_STAGE(PG8_SA(0, 0), a2, voffA);
;             PG8_WAIT_V(8); PG8_WAIT_L(0); PG8_BAR; PG8_MMA(1, 0, At, B0); PG8_MMA(1, 1, At, B1); PG8_BAR; PG8_SCHED;
;             PG8_LDB(B0, 1, 0); PG8_LDB(B1, 1, 1); PG8_SCHED; PG8_LDA(At, 1, 0); PG8_STAGE(PG8_SA(0, 1), a2 + hstepA, voffA);
;             PG8_WAIT_V(8); PG8_WAIT_L(0); PG8_BAR; PG8_MMA(0, 0, At, B0); PG8_MMA(0, 1, At, B1); PG8_BAR; PG8_SCHED;
;             PG8_LDA(At, 1, 1); PG8_STAGE(PG8_SB(1, 0), b3, voffB); PG8_STAGE(PG8_SB(1, 1), b3 + hstepB, voffB); PG8_STAGE(PG8_SA(1, 0), a3, voffA);
;             PG8_WAIT_V(8); PG8_WAIT_L(0); PG8_BAR; PG8_MMA(1, 0, At, B0); PG8_MMA(1, 1, At, B1); PG8_BAR; PG8_SCHED;
	s_setprio 1
	s_waitcnt lgkmcnt(0)
	v_mfma_f32_16x16x32_bf16 v[60:63], v[72:75], v[168:171], v[60:63]
	v_mfma_f32_16x16x32_bf16 v[56:59], v[88:91], v[168:171], v[56:59]
	v_mfma_f32_16x16x32_bf16 v[44:47], v[72:75], v[192:195], v[44:47]
	v_mfma_f32_16x16x32_bf16 v[40:43], v[88:91], v[192:195], v[40:43]
	v_mfma_f32_16x16x32_bf16 v[28:31], v[72:75], v[200:203], v[28:31]
	v_mfma_f32_16x16x32_bf16 v[24:27], v[88:91], v[200:203], v[24:27]
	v_mfma_f32_16x16x32_bf16 v[12:15], v[72:75], v[208:211], v[12:15]
	v_mfma_f32_16x16x32_bf16 v[8:11], v[88:91], v[208:211], v[8:11]
	v_mfma_f32_16x16x32_bf16 v[60:63], v[76:79], v[174:177], v[60:63]
	v_mfma_f32_16x16x32_bf16 v[56:59], v[92:95], v[174:177], v[56:59]
	v_mfma_f32_16x16x32_bf16 v[44:47], v[76:79], v[196:199], v[44:47]
	v_mfma_f32_16x16x32_bf16 v[40:43], v[92:95], v[196:199], v[40:43]
	v_mfma_f32_16x16x32_bf16 v[28:31], v[76:79], v[204:207], v[28:31]
	v_mfma_f32_16x16x32_bf16 v[24:27], v[92:95], v[204:207], v[24:27]
	v_mfma_f32_16x16x32_bf16 v[12:15], v[76:79], v[212:215], v[12:15]
	v_mfma_f32_16x16x32_bf16 v[8:11], v[92:95], v[212:215], v[8:11]
	s_setprio 0
	s_setprio 1
	v_mfma_f32_16x16x32_bf16 v[52:55], v[152:155], v[168:171], v[52:55]
	v_mfma_f32_16x16x32_bf16 v[48:51], v[160:163], v[168:171], v[48:51]
	v_mfma_f32_16x16x32_bf16 v[36:39], v[152:155], v[192:195], v[36:39]
	v_mfma_f32_16x16x32_bf16 v[32:35], v[160:163], v[192:195], v[32:35]
	v_mfma_f32_16x16x32_bf16 v[20:23], v[152:155], v[200:203], v[20:23]
	v_mfma_f32_16x16x32_bf16 v[16:19], v[160:163], v[200:203], v[16:19]
	v_mfma_f32_16x16x32_bf16 v[4:7], v[152:155], v[208:211], v[4:7]
	v_mfma_f32_16x16x32_bf16 v[0:3], v[160:163], v[208:211], v[0:3]
	v_mfma_f32_16x16x32_bf16 v[52:55], v[156:159], v[174:177], v[52:55]
	v_mfma_f32_16x16x32_bf16 v[48:51], v[164:167], v[174:177], v[48:51]
	v_mfma_f32_16x16x32_bf16 v[36:39], v[156:159], v[196:199], v[36:39]
	v_mfma_f32_16x16x32_bf16 v[32:35], v[164:167], v[196:199], v[32:35]
	v_mfma_f32_16x16x32_bf16 v[20:23], v[156:159], v[204:207], v[20:23]
	v_mfma_f32_16x16x32_bf16 v[16:19], v[164:167], v[204:207], v[16:19]
	v_mfma_f32_16x16x32_bf16 v[4:7], v[156:159], v[212:215], v[4:7]
	v_mfma_f32_16x16x32_bf16 v[0:3], v[164:167], v[212:215], v[0:3]
	s_setprio 0
	s_barrier
	s_add_i32 s67, 0, 0x18000
	s_add_i32 s68, 0, 0x1c000
	v_add_u32_e32 v92, s67, v181
	v_add_u32_e32 v164, s68, v181
	ds_read_b128 v[72:75], v92
	ds_read_b128 v[76:79], v92 offset:1024
	ds_read_b128 v[88:91], v92 offset:2048
	ds_read_b128 v[92:95], v92 offset:3072
	ds_read_b128 v[152:155], v164
	ds_read_b128 v[156:159], v164 offset:1024
	ds_read_b128 v[160:163], v164 offset:2048
	ds_read_b128 v[164:167], v164 offset:3072
	s_add_u32 s42, s42, 0x40000
	s_addc_u32 s43, s43, 0
	s_mov_b32 m0, s53
	ds_read_b128 v[168:171], v186 offset:32768
	ds_read_b128 v[174:177], v186 offset:33792
	ds_read_b128 v[192:195], v186 offset:34816
	ds_read_b128 v[196:199], v186 offset:35840
	ds_read_b128 v[200:203], v186 offset:36864
	ds_read_b128 v[204:207], v186 offset:37888
	ds_read_b128 v[208:211], v186 offset:38912
	ds_read_b128 v[212:215], v186 offset:39936
	global_load_lds_dwordx4 v172, s[42:43]
	v_lshl_add_u64 v[222:223], s[42:43], 0, v[144:145]
	s_mov_b32 m0, s54
	s_nop 0
	global_load_lds_dwordx4 v[222:223], off
	s_waitcnt vmcnt(8)
	s_waitcnt lgkmcnt(0)
	s_barrier
	s_setprio 1
	s_waitcnt lgkmcnt(0)
	v_mfma_f32_16x16x32_bf16 v[140:143], v[72:75], v[168:171], v[140:143]
	v_mfma_f32_16x16x32_bf16 v[136:139], v[88:91], v[168:171], v[136:139]
	v_mfma_f32_16x16x32_bf16 v[124:127], v[72:75], v[192:195], v[124:127]
	v_mfma_f32_16x16x32_bf16 v[120:123], v[88:91], v[192:195], v[120:123]
	v_mfma_f32_16x16x32_bf16 v[108:111], v[72:75], v[200:203], v[108:111]
	v_mfma_f32_16x16x32_bf16 v[104:107], v[88:91], v[200:203], v[104:107]
	v_mfma_f32_16x16x32_bf16 v[84:87], v[72:75], v[208:211], v[84:87]
	v_mfma_f32_16x16x32_bf16 v[80:83], v[88:91], v[208:211], v[80:83]
	v_mfma_f32_16x16x32_bf16 v[140:143], v[76:79], v[174:177], v[140:143]
	v_mfma_f32_16x16x32_bf16 v[136:139], v[92:95], v[174:177], v[136:139]
	v_mfma_f32_16x16x32_bf16 v[124:127], v[76:79], v[196:199], v[124:127]
	v_mfma_f32_16x16x32_bf16 v[120:123], v[92:95], v[196:199], v[120:123]
	v_mfma_f32_16x16x32_bf16 v[108:111], v[76:79], v[204:207], v[108:111]
	v_mfma_f32_16x16x32_bf16 v[104:107], v[92:95], v[204:207], v[104:107]
	v_mfma_f32_16x16x32_bf16 v[84:87], v[76:79], v[212:215], v[84:87]
	v_mfma_f32_16x16x32_bf16 v[80:83], v[92:95], v[212:215], v[80:83]
	s_setprio 0
	s_setprio 1
	v_mfma_f32_16x16x32_bf16 v[132:135], v[152:155], v[168:171], v[132:135]
	v_mfma_f32_16x16x32_bf16 v[128:131], v[160:163], v[168:171], v[128:131]
	v_mfma_f32_16x16x32_bf16 v[116:119], v[152:155], v[192:195], v[116:119]
	v_mfma_f32_16x16x32_bf16 v[112:115], v[160:163], v[192:195], v[112:115]
	v_mfma_f32_16x16x32_bf16 v[100:103], v[152:155], v[200:203], v[100:103]
	v_mfma_f32_16x16x32_bf16 v[96:99], v[160:163], v[200:203], v[96:99]
	v_mfma_f32_16x16x32_bf16 v[68:71], v[152:155], v[208:211], v[68:71]
	v_mfma_f32_16x16x32_bf16 v[64:67], v[160:163], v[208:211], v[64:67]
	v_mfma_f32_16x16x32_bf16 v[132:135], v[156:159], v[174:177], v[132:135]
	v_mfma_f32_16x16x32_bf16 v[128:131], v[164:167], v[174:177], v[128:131]
	v_mfma_f32_16x16x32_bf16 v[116:119], v[156:159], v[196:199], v[116:119]
	v_mfma_f32_16x16x32_bf16 v[112:115], v[164:167], v[196:199], v[112:115]
	v_mfma_f32_16x16x32_bf16 v[100:103], v[156:159], v[204:207], v[100:103]
	v_mfma_f32_16x16x32_bf16 v[96:99], v[164:167], v[204:207], v[96:99]
	v_mfma_f32_16x16x32_bf16 v[68:71], v[156:159], v[212:215], v[68:71]
	v_mfma_f32_16x16x32_bf16 v[64:67], v[164:167], v[212:215], v[64:67]
	s_setprio 0
	s_barrier
; #define PG8_STAGE(bufoff, gbase, voff) do { _Pragma("unroll") for (int _i = 0; _i < 2; ++_i) \
;         __builtin_amdgcn_global_load_lds((const unsigned*)((const char*)(gbase) + (voff)[_i]), (PG8_LAS unsigned*)(lds + (bufoff) + ldsw + _i * 8192), 16, 0, 0); } while (0)
; #define PG8_LDA(dst, b, h) do { _Pragma("unroll") for (int m = 0; m < 4; ++m) _Pragma("unroll") for (int k = 0; k < 2; ++k) dst[m][k] = *(const PG8_LAS bf16x8*)(lds + PG8_SA(b, h) + aoff + m * 2048 + k * 1024); } while (0)
; #define PG8_LDB(dst, b, h) do { _Pragma("unroll") for (int n = 0; n < 2; ++n) _Pragma("unroll") for (int k = 0; k < 2; ++k) dst[n][k] = *(const PG8_LAS bf16x8*)(lds + PG8_SB(b, h) + boff + n * 2048 + k * 1024); } while (0)
; #define PG8_MMA(ai, bj, At, Bt) do { __builtin_amdgcn_s_setprio(1); _Pragma("unroll") for (int m = 0; m < 4; ++m) _Pragma("unroll") for (int n = 0; n < 2; ++n) _Pragma("unroll") for (int k = 0; k < 2; ++k) \
;         acc[ai][bj][m][n] = __builtin_amdgcn_mfma_f32_16x16x32_bf16(Bt[n][k], At[m][k], acc[ai][bj][m][n], 0, 0, 0); __builtin_amdgcn_s_setprio(0); } while (0)
; template <class Epi, class Sched, bool ALIGN_EPI = false, bool SP2 = false>
; __device__ __forceinline__ void gemm_phase(PG8_LAS unsigned char* lds, const Gemm g, const Sched& S, const Epi& E) {
;     ...
;             if constexpr (SP2) {
;             PG8_LDB(B0, 0, 0); PG8_LDB(B1, 0, 1); PG8_SCHED; PG8_LDA(At, 0, 0); PG8_STAGE(PG8_SA(1, 1), a1 + hstepA, voffA);
;             PG8_WAIT_V(8); PG8_WAIT_L(0); PG8_BAR; PG8_MMA(0, 0, At, B0); PG8_MMA(0, 1, At, B1); PG8_BAR; PG8_SCHED;
;             PG8_LDA(At, 0, 1); PG8_STAGE(PG8_SB(0, 0), b2, voffB); PG8_STAGE(PG8_SB(0, 1), b2 + hstepB, voffB); PG8_STAGE(PG8_SA(0, 0), a2, voffA);
;             PG8_WAIT_V(8); PG8_WAIT_L(0); PG8_BAR; PG8_MMA(1, 0, At, B0); PG8_MMA(1, 1, At, B1); PG8_BAR; PG8_SCHED;
;             PG8_LDB(B0, 1, 0); PG8_LDB(B1, 1, 1); PG8_SCHED; PG8_LDA(At, 1, 0); PG8_STAGE(PG8_SA(0, 1), a2 + hstepA, voffA);
;             PG8_WAIT_V(8); PG8_WAIT_L(0); PG8_BAR; PG8_MMA(0, 0, At, B0); PG8_MMA(0, 1, At, B1); PG8_BAR; PG8_SCHED;
;             PG8_LDA(At, 1, 1); PG8_STAGE(PG8_SB(1, 0), b3, voffB); PG8_STAGE(PG8_SB(1, 1), b3 + hstepB, voffB); PG8_STAGE(PG8_SA(1, 0), a3, voffA);
;             PG8_WAIT_V(8); PG8_WAIT_L(0); PG8_BAR; PG8_MMA(1, 0, At, B0); PG8_MMA(1, 1, At, B1); PG8_BAR; PG8_SCHED;
	s_add_i32 s42, s67, s50
	v_lshl_add_u64 v[178:179], v[178:179], 0, s[80:81]
	s_mov_b32 m0, s42
	ds_read_b128 v[168:171], v186 offset:49152
	ds_read_b128 v[174:177], v186 offset:50176
	ds_read_b128 v[192:195], v186 offset:51200
	ds_read_b128 v[196:199], v186 offset:52224
	ds_read_b128 v[200:203], v186 offset:53248
	ds_read_b128 v[204:207], v186 offset:54272
	ds_read_b128 v[208:211], v186 offset:55296
	ds_read_b128 v[212:215], v186 offset:56320
	global_load_lds_dwordx4 v[178:179], off
	s_add_i32 m0, s42, 0x2000
	s_add_u32 s40, s40, 0x40080
	v_lshl_add_u64 v[178:179], v[216:217], 0, s[80:81]
	s_addc_u32 s41, s41, 0
	s_add_i32 s42, s68, s50
	global_load_lds_dwordx4 v[178:179], off
	s_mov_b32 m0, s42
	s_nop 0
	global_load_lds_dwordx4 v172, s[40:41]
	s_add_i32 m0, s42, 0x2000
	s_nop 0
	global_load_lds_dwordx4 v144, s[40:41]
	v_lshl_add_u64 v[178:179], v[218:219], 0, s[80:81]
	s_mov_b32 m0, s59
	s_nop 0
	global_load_lds_dwordx4 v[178:179], off
	v_lshl_add_u64 v[178:179], v[220:221], 0, s[80:81]
	s_mov_b32 m0, s60
	s_nop 0
	global_load_lds_dwordx4 v[178:179], off
	s_waitcnt vmcnt(8)
	s_waitcnt lgkmcnt(0)
	s_barrier
	s_setprio 1
	s_waitcnt lgkmcnt(0)
	v_mfma_f32_16x16x32_bf16 v[60:63], v[72:75], v[168:171], v[60:63]
	v_mfma_f32_16x16x32_bf16 v[56:59], v[88:91], v[168:171], v[56:59]
	v_mfma_f32_16x16x32_bf16 v[44:47], v[72:75], v[192:195], v[44:47]
	v_mfma_f32_16x16x32_bf16 v[40:43], v[88:91], v[192:195], v[40:43]
	v_mfma_f32_16x16x32_bf16 v[28:31], v[72:75], v[200:203], v[28:31]
	v_mfma_f32_16x16x32_bf16 v[24:27], v[88:91], v[200:203], v[24:27]
	v_mfma_f32_16x16x32_bf16 v[12:15], v[72:75], v[208:211], v[12:15]
	v_mfma_f32_16x16x32_bf16 v[8:11], v[88:91], v[208:211], v[8:11]
	v_mfma_f32_16x16x32_bf16 v[60:63], v[76:79], v[174:177], v[60:63]
	v_mfma_f32_16x16x32_bf16 v[56:59], v[92:95], v[174:177], v[56:59]
	v_mfma_f32_16x16x32_bf16 v[44:47], v[76:79], v[196:199], v[44:47]
	v_mfma_f32_16x16x32_bf16 v[40:43], v[92:95], v[196:199], v[40:43]
	v_mfma_f32_16x16x32_bf16 v[28:31], v[76:79], v[204:207], v[28:31]
	v_mfma_f32_16x16x32_bf16 v[24:27], v[92:95], v[204:207], v[24:27]
	v_mfma_f32_16x16x32_bf16 v[12:15], v[76:79], v[212:215], v[12:15]
	v_mfma_f32_16x16x32_bf16 v[8:11], v[92:95], v[212:215], v[8:11]
	s_setprio 0
	s_setprio 1
	v_mfma_f32_16x16x32_bf16 v[52:55], v[152:155], v[168:171], v[52:55]
	v_mfma_f32_16x16x32_bf16 v[48:51], v[160:163], v[168:171], v[48:51]
	v_mfma_f32_16x16x32_bf16 v[36:39], v[152:155], v[192:195], v[36:39]
	v_mfma_f32_16x16x32_bf16 v[32:35], v[160:163], v[192:195], v[32:35]
	v_mfma_f32_16x16x32_bf16 v[20:23], v[152:155], v[200:203], v[20:23]
	v_mfma_f32_16x16x32_bf16 v[16:19], v[160:163], v[200:203], v[16:19]
	v_mfma_f32_16x16x32_bf16 v[4:7], v[152:155], v[208:211], v[4:7]
	v_mfma_f32_16x16x32_bf16 v[0:3], v[160:163], v[208:211], v[0:3]
	v_mfma_f32_16x16x32_bf16 v[52:55], v[156:159], v[174:177], v[52:55]
	v_mfma_f32_16x16x32_bf16 v[48:51], v[164:167], v[174:177], v[48:51]
	v_mfma_f32_16x16x32_bf16 v[36:39], v[156:159], v[196:199], v[36:39]
	v_mfma_f32_16x16x32_bf16 v[32:35], v[164:167], v[196:199], v[32:35]
	v_mfma_f32_16x16x32_bf16 v[20:23], v[156:159], v[204:207], v[20:23]
	v_mfma_f32_16x16x32_bf16 v[16:19], v[164:167], v[204:207], v[16:19]
	v_mfma_f32_16x16x32_bf16 v[4:7], v[156:159], v[212:215], v[4:7]
	v_mfma_f32_16x16x32_bf16 v[0:3], v[164:167], v[212:215], v[0:3]
	s_setprio 0
	s_barrier
	s_add_i32 s66, s66, 2
	s_add_u32 s38, s38, 0x100
	s_addc_u32 s39, s39, 0
	s_add_u32 s64, s64, 0x100
	s_addc_u32 s65, s65, 0
	s_cmp_gt_u32 s66, 13
	s_cbranch_scc0 .LBB0_1575
	s_and_b64 vcc, exec, s[22:23]
	s_cbranch_vccz .LBB0_1578
	s_barrier

; #define PG8_STAGE(bufoff, gbase, voff) do { _Pragma("unroll") for (int _i = 0; _i < 2; ++_i) \
;         __builtin_amdgcn_global_load_lds((const unsigned*)((const char*)(gbase) + (voff)[_i]), (PG8_LAS unsigned*)(lds + (bufoff) + ldsw + _i * 8192), 16, 0, 0); } while (0)
; #define PG8_LDA(dst, b, h) do { _Pragma("unroll") for (int m = 0; m < 4; ++m) _Pragma("unroll") for (int k = 0; k < 2; ++k) dst[m][k] = *(const PG8_LAS bf16x8*)(lds + PG8_SA(b, h) + aoff + m * 2048 + k * 1024); } while (0)
; #define PG8_LDB(dst, b, h) do { _Pragma("unroll") for (int n = 0; n < 2; ++n) _Pragma("unroll") for (int k = 0; k < 2; ++k) dst[n][k] = *(const PG8_LAS bf16x8*)(lds + PG8_SB(b, h) + boff + n * 2048 + k * 1024); } while (0)
; template <class Epi, class Sched, bool ALIGN_EPI = false, bool SP2 = false>
; __device__ __forceinline__ void gemm_phase(PG8_LAS unsigned char* lds, const Gemm g, const Sched& S, const Epi& E) {
;     ...
;         for (int t = 0; t < nt; t += 2) {
;             const bool last = (t == nt - 2);
;             const char* a1 = cA + (size_t)(t + 1) * kstep;
;             const char* a2 = last ? nA : cA + (size_t)(t + 2) * kstep; const char* b2 = last ? nB : cB + (size_t)(t + 2) * kstep;
;             const char* a3 = a2 + kstep; const char* b3 = b2 + kstep;
;             if (last && has_next) S.a_ready(nxt);
;             if constexpr (SP2) {
;             PG8_LDB(B0, 0, 0); PG8_LDB(B1, 0, 1); PG8_SCHED; PG8_LDA(At, 0, 0); PG8_STAGE(PG8_SA(1, 1), a1 + hstepA, voffA);
;             PG8_WAIT_V(8); PG8_WAIT_L(0); PG8_BAR; PG8_MMA(0, 0, At, B0); PG8_MMA(0, 1, At, B1); PG8_BAR; PG8_SCHED;
;             PG8_LDA(At, 0, 1); PG8_STAGE(PG8_SB(0, 0), b2, voffB); PG8_STAGE(PG8_SB(0, 1), b2 + hstepB, voffB); PG8_STAGE(PG8_SA(0, 0), a2, voffA);
;             PG8_WAIT_V(8); PG8_WAIT_L(0); PG8_BAR; PG8_MMA(1, 0, At, B0); PG8_MMA(1, 1, At, B1); PG8_BAR; PG8_SCHED;
;             PG8_LDB(B0, 1, 0); PG8_LDB(B1, 1, 1); PG8_SCHED; PG8_LDA(At, 1, 0); PG8_STAGE(PG8_SA(0, 1), a2 + hstepA, voffA);
;             PG8_WAIT_V(8); PG8_WAIT_L(0); PG8_BAR; PG8_MMA(0, 0, At, B0); PG8_MMA(0, 1, At, B1); PG8_BAR; PG8_SCHED;
;             PG8_LDA(At, 1, 1); PG8_STAGE(PG8_SB(1, 0), b3, voffB); PG8_STAGE(PG8_SB(1, 1), b3 + hstepB, voffB); PG8_STAGE(PG8_SA(1, 0), a3, voffA);
;             PG8_WAIT_V(8); PG8_WAIT_L(0); PG8_BAR; PG8_MMA(1, 0, At, B0); PG8_MMA(1, 1, At, B1); PG8_BAR; PG8_SCHED;
.LBB0_1786:
	s_add_u32 s36, s34, 0xfffc0080
	s_addc_u32 s37, s35, -1
	s_add_i32 s64, 0, 0x10000
	s_cmp_eq_u32 s63, 12
	s_cselect_b32 s39, s11, s37
	s_cselect_b32 s38, s25, s36
	s_cselect_b32 s37, s23, s62
	s_cselect_b32 s36, s60, s61
	s_add_i32 s66, 0, 0x14000
	v_add_u32_e32 v140, s64, v163
	v_add_u32_e32 v158, s66, v163
	ds_read_b128 v[128:131], v140
	ds_read_b128 v[132:135], v140 offset:1024
	ds_read_b128 v[136:139], v140 offset:2048
	ds_read_b128 v[140:143], v140 offset:3072
	ds_read_b128 v[154:157], v158
	ds_read_b128 v[166:169], v158 offset:1024
	ds_read_b128 v[174:177], v158 offset:2048
	ds_read_b128 v[178:181], v158 offset:3072
	s_add_i32 m0, s31, 0xc000
	ds_read_b128 v[182:185], v165
	ds_read_b128 v[192:195], v165 offset:1024
	ds_read_b128 v[196:199], v165 offset:2048
	ds_read_b128 v[200:203], v165 offset:3072
	ds_read_b128 v[204:207], v165 offset:4096
	ds_read_b128 v[208:211], v165 offset:5120
	ds_read_b128 v[212:215], v165 offset:6144
	ds_read_b128 v[216:219], v165 offset:7168
	global_load_lds_dwordx4 v150, s[34:35]
	s_add_i32 m0, s31, 0xe000
	s_nop 0
	global_load_lds_dwordx4 v152, s[34:35]
	s_waitcnt vmcnt(8)
	s_waitcnt lgkmcnt(0)
	s_barrier
	s_setprio 1
	s_waitcnt lgkmcnt(0)
	v_mfma_f32_16x16x32_bf16 v[124:127], v[128:131], v[182:185], v[124:127]
	v_mfma_f32_16x16x32_bf16 v[120:123], v[136:139], v[182:185], v[120:123]
	v_mfma_f32_16x16x32_bf16 v[108:111], v[128:131], v[196:199], v[108:111]
	v_mfma_f32_16x16x32_bf16 v[104:107], v[136:139], v[196:199], v[104:107]
	v_mfma_f32_16x16x32_bf16 v[92:95], v[128:131], v[204:207], v[92:95]
	v_mfma_f32_16x16x32_bf16 v[88:91], v[136:139], v[204:207], v[88:91]
	v_mfma_f32_16x16x32_bf16 v[76:79], v[128:131], v[212:215], v[76:79]
	v_mfma_f32_16x16x32_bf16 v[72:75], v[136:139], v[212:215], v[72:75]
	v_mfma_f32_16x16x32_bf16 v[124:127], v[132:135], v[192:195], v[124:127]
	v_mfma_f32_16x16x32_bf16 v[120:123], v[140:143], v[192:195], v[120:123]
	v_mfma_f32_16x16x32_bf16 v[108:111], v[132:135], v[200:203], v[108:111]
	v_mfma_f32_16x16x32_bf16 v[104:107], v[140:143], v[200:203], v[104:107]
	v_mfma_f32_16x16x32_bf16 v[92:95], v[132:135], v[208:211], v[92:95]
	v_mfma_f32_16x16x32_bf16 v[88:91], v[140:143], v[208:211], v[88:91]
	v_mfma_f32_16x16x32_bf16 v[76:79], v[132:135], v[216:219], v[76:79]
	v_mfma_f32_16x16x32_bf16 v[72:75], v[140:143], v[216:219], v[72:75]
	s_setprio 0
	s_setprio 1
	v_mfma_f32_16x16x32_bf16 v[116:119], v[154:157], v[182:185], v[116:119]
	v_mfma_f32_16x16x32_bf16 v[112:115], v[174:177], v[182:185], v[112:115]
	v_mfma_f32_16x16x32_bf16 v[100:103], v[154:157], v[196:199], v[100:103]
	v_mfma_f32_16x16x32_bf16 v[96:99], v[174:177], v[196:199], v[96:99]
	v_mfma_f32_16x16x32_bf16 v[84:87], v[154:157], v[204:207], v[84:87]
	v_mfma_f32_16x16x32_bf16 v[80:83], v[174:177], v[204:207], v[80:83]
	v_mfma_f32_16x16x32_bf16 v[68:71], v[154:157], v[212:215], v[68:71]
	v_mfma_f32_16x16x32_bf16 v[64:67], v[174:177], v[212:215], v[64:67]
	v_mfma_f32_16x16x32_bf16 v[116:119], v[166:169], v[192:195], v[116:119]
	v_mfma_f32_16x16x32_bf16 v[112:115], v[178:181], v[192:195], v[112:115]
	v_mfma_f32_16x16x32_bf16 v[100:103], v[166:169], v[200:203], v[100:103]
	v_mfma_f32_16x16x32_bf16 v[96:99], v[178:181], v[200:203], v[96:99]
	v_mfma_f32_16x16x32_bf16 v[84:87], v[166:169], v[208:211], v[84:87]
	v_mfma_f32_16x16x32_bf16 v[80:83], v[178:181], v[208:211], v[80:83]
	v_mfma_f32_16x16x32_bf16 v[68:71], v[166:169], v[216:219], v[68:71]
	v_mfma_f32_16x16x32_bf16 v[64:67], v[178:181], v[216:219], v[64:67]
	s_setprio 0
	s_barrier
	s_add_i32 s64, s64, s46
	v_lshl_add_u64 v[158:159], s[36:37], 0, v[172:173]
	s_mov_b32 m0, s64
	ds_read_b128 v[182:185], v165 offset:16384
	ds_read_b128 v[192:195], v165 offset:17408
	ds_read_b128 v[196:199], v165 offset:18432
	ds_read_b128 v[200:203], v165 offset:19456
	ds_read_b128 v[204:207], v165 offset:20480
	ds_read_b128 v[208:211], v165 offset:21504
	ds_read_b128 v[212:215], v165 offset:22528
	ds_read_b128 v[216:219], v165 offset:23552
	global_load_lds_dwordx4 v[158:159], off
	s_add_i32 m0, s64, 0x2000
	s_add_u32 s64, s36, 0x10000
	v_lshl_add_u64 v[170:171], s[36:37], 0, v[148:149]
	s_addc_u32 s65, s37, 0
	s_add_i32 s66, s66, s46
	global_load_lds_dwordx4 v[170:171], off
	s_mov_b32 m0, s66
	v_lshl_add_u64 v[220:221], s[38:39], 0, v[146:147]
	global_load_lds_dwordx4 v172, s[64:65]
	s_add_i32 m0, s66, 0x2000
	s_nop 0
	global_load_lds_dwordx4 v148, s[64:65]
	v_lshl_add_u64 v[186:187], s[38:39], 0, v[144:145]
	s_mov_b32 m0, s31
	s_nop 0
	global_load_lds_dwordx4 v[186:187], off
	s_mov_b32 m0, s47
	s_nop 0
	global_load_lds_dwordx4 v[220:221], off
	s_waitcnt vmcnt(8)
	s_waitcnt lgkmcnt(0)
	s_barrier
; #define PG8_STAGE(bufoff, gbase, voff) do { _Pragma("unroll") for (int _i = 0; _i < 2; ++_i) \
;         __builtin_amdgcn_global_load_lds((const unsigned*)((const char*)(gbase) + (voff)[_i]), (PG8_LAS unsigned*)(lds + (bufoff) + ldsw + _i * 8192), 16, 0, 0); } while (0)
; #define PG8_LDA(dst, b, h) do { _Pragma("unroll") for (int m = 0; m < 4; ++m) _Pragma("unroll") for (int k = 0; k < 2; ++k) dst[m][k] = *(const PG8_LAS bf16x8*)(lds + PG8_SA(b, h) + aoff + m * 2048 + k * 1024); } while (0)
; #define PG8_LDB(dst, b, h) do { _Pragma("unroll") for (int n = 0; n < 2; ++n) _Pragma("unroll") for (int k = 0; k < 2; ++k) dst[n][k] = *(const PG8_LAS bf16x8*)(lds + PG8_SB(b, h) + boff + n * 2048 + k * 1024); } while (0)
; #define PG8_MMA(ai, bj, At, Bt) do { __builtin_amdgcn_s_setprio(1); _Pragma("unroll") for (int m = 0; m < 4; ++m) _Pragma("unroll") for (int n = 0; n < 2; ++n) _Pragma("unroll") for (int k = 0; k < 2; ++k) \
;         acc[ai][bj][m][n] = __builtin_amdgcn_mfma_f32_16x16x32_bf16(Bt[n][k], At[m][k], acc[ai][bj][m][n], 0, 0, 0); __builtin_amdgcn_s_setprio(0); } while (0)
; template <class Epi, class Sched, bool ALIGN_EPI = false, bool SP2 = false>
; __device__ __forceinline__ void gemm_phase(PG8_LAS unsigned char* lds, const Gemm g, const Sched& S, const Epi& E) {
;     ...
;             if constexpr (SP2) {
;             PG8_LDB(B0, 0, 0); PG8_LDB(B1, 0, 1); PG8_SCHED; PG8_LDA(At, 0, 0); PG8_STAGE(PG8_SA(1, 1), a1 + hstepA, voffA);
;             PG8_WAIT_V(8); PG8_WAIT_L(0); PG8_BAR; PG8_MMA(0, 0, At, B0); PG8_MMA(0, 1, At, B1); PG8_BAR; PG8_SCHED;
;             PG8_LDA(At, 0, 1); PG8_STAGE(PG8_SB(0, 0), b2, voffB); PG8_STAGE(PG8_SB(0, 1), b2 + hstepB, voffB); PG8_STAGE(PG8_SA(0, 0), a2, voffA);
;             PG8_WAIT_V(8); PG8_WAIT_L(0); PG8_BAR; PG8_MMA(1, 0, At, B0); PG8_MMA(1, 1, At, B1); PG8_BAR; PG8_SCHED;
;             PG8_LDB(B0, 1, 0); PG8_LDB(B1, 1, 1); PG8_SCHED; PG8_LDA(At, 1, 0); PG8_STAGE(PG8_SA(0, 1), a2 + hstepA, voffA);
;             PG8_WAIT_V(8); PG8_WAIT_L(0); PG8_BAR; PG8_MMA(0, 0, At, B0); PG8_MMA(0, 1, At, B1); PG8_BAR; PG8_SCHED;
;             PG8_LDA(At, 1, 1); PG8_STAGE(PG8_SB(1, 0), b3, voffB); PG8_STAGE(PG8_SB(1, 1), b3 + hstepB, voffB); PG8_STAGE(PG8_SA(1, 0), a3, voffA);
;             PG8_WAIT_V(8); PG8_WAIT_L(0); PG8_BAR; PG8_MMA(1, 0, At, B0); PG8_MMA(1, 1, At, B1); PG8_BAR; PG8_SCHED;
	s_setprio 1
	s_waitcnt lgkmcnt(0)
	v_mfma_f32_16x16x32_bf16 v[60:63], v[128:131], v[182:185], v[60:63]
	v_mfma_f32_16x16x32_bf16 v[56:59], v[136:139], v[182:185], v[56:59]
	v_mfma_f32_16x16x32_bf16 v[44:47], v[128:131], v[196:199], v[44:47]
	v_mfma_f32_16x16x32_bf16 v[40:43], v[136:139], v[196:199], v[40:43]
	v_mfma_f32_16x16x32_bf16 v[28:31], v[128:131], v[204:207], v[28:31]
	v_mfma_f32_16x16x32_bf16 v[24:27], v[136:139], v[204:207], v[24:27]
	v_mfma_f32_16x16x32_bf16 v[12:15], v[128:131], v[212:215], v[12:15]
	v_mfma_f32_16x16x32_bf16 v[8:11], v[136:139], v[212:215], v[8:11]
	v_mfma_f32_16x16x32_bf16 v[60:63], v[132:135], v[192:195], v[60:63]
	v_mfma_f32_16x16x32_bf16 v[56:59], v[140:143], v[192:195], v[56:59]
	v_mfma_f32_16x16x32_bf16 v[44:47], v[132:135], v[200:203], v[44:47]
	v_mfma_f32_16x16x32_bf16 v[40:43], v[140:143], v[200:203], v[40:43]
	v_mfma_f32_16x16x32_bf16 v[28:31], v[132:135], v[208:211], v[28:31]
	v_mfma_f32_16x16x32_bf16 v[24:27], v[140:143], v[208:211], v[24:27]
	v_mfma_f32_16x16x32_bf16 v[12:15], v[132:135], v[216:219], v[12:15]
	v_mfma_f32_16x16x32_bf16 v[8:11], v[140:143], v[216:219], v[8:11]
	s_setprio 0
	s_setprio 1
	v_mfma_f32_16x16x32_bf16 v[52:55], v[154:157], v[182:185], v[52:55]
	v_mfma_f32_16x16x32_bf16 v[48:51], v[174:177], v[182:185], v[48:51]
	v_mfma_f32_16x16x32_bf16 v[36:39], v[154:157], v[196:199], v[36:39]
	v_mfma_f32_16x16x32_bf16 v[32:35], v[174:177], v[196:199], v[32:35]
	v_mfma_f32_16x16x32_bf16 v[20:23], v[154:157], v[204:207], v[20:23]
	v_mfma_f32_16x16x32_bf16 v[16:19], v[174:177], v[204:207], v[16:19]
	v_mfma_f32_16x16x32_bf16 v[4:7], v[154:157], v[212:215], v[4:7]
	v_mfma_f32_16x16x32_bf16 v[0:3], v[174:177], v[212:215], v[0:3]
	v_mfma_f32_16x16x32_bf16 v[52:55], v[166:169], v[192:195], v[52:55]
	v_mfma_f32_16x16x32_bf16 v[48:51], v[178:181], v[192:195], v[48:51]
	v_mfma_f32_16x16x32_bf16 v[36:39], v[166:169], v[200:203], v[36:39]
	v_mfma_f32_16x16x32_bf16 v[32:35], v[178:181], v[200:203], v[32:35]
	v_mfma_f32_16x16x32_bf16 v[20:23], v[166:169], v[208:211], v[20:23]
	v_mfma_f32_16x16x32_bf16 v[16:19], v[178:181], v[208:211], v[16:19]
	v_mfma_f32_16x16x32_bf16 v[4:7], v[166:169], v[216:219], v[4:7]
	v_mfma_f32_16x16x32_bf16 v[0:3], v[178:181], v[216:219], v[0:3]
	s_setprio 0
	s_barrier
	s_add_i32 s64, 0, 0x18000
	s_add_i32 s65, 0, 0x1c000
	v_add_u32_e32 v140, s64, v163
	v_add_u32_e32 v160, s65, v163
	ds_read_b128 v[128:131], v140
	ds_read_b128 v[132:135], v140 offset:1024
	ds_read_b128 v[136:139], v140 offset:2048
	ds_read_b128 v[140:143], v140 offset:3072
	ds_read_b128 v[154:157], v160
	ds_read_b128 v[166:169], v160 offset:1024
	ds_read_b128 v[174:177], v160 offset:2048
	ds_read_b128 v[178:181], v160 offset:3072
	s_add_u32 s38, s38, 0x40000
	s_addc_u32 s39, s39, 0
	s_mov_b32 m0, s49
	ds_read_b128 v[182:185], v165 offset:32768
	ds_read_b128 v[192:195], v165 offset:33792
	ds_read_b128 v[196:199], v165 offset:34816
	ds_read_b128 v[200:203], v165 offset:35840
	ds_read_b128 v[204:207], v165 offset:36864
	ds_read_b128 v[208:211], v165 offset:37888
	ds_read_b128 v[212:215], v165 offset:38912
	ds_read_b128 v[216:219], v165 offset:39936
	global_load_lds_dwordx4 v144, s[38:39]
	v_lshl_add_u64 v[222:223], s[38:39], 0, v[146:147]
	s_mov_b32 m0, s50
	s_nop 0
	global_load_lds_dwordx4 v[222:223], off
	s_waitcnt vmcnt(8)
	s_waitcnt lgkmcnt(0)
	s_barrier
	s_setprio 1
	s_waitcnt lgkmcnt(0)
	v_mfma_f32_16x16x32_bf16 v[124:127], v[128:131], v[182:185], v[124:127]
	v_mfma_f32_16x16x32_bf16 v[120:123], v[136:139], v[182:185], v[120:123]
	v_mfma_f32_16x16x32_bf16 v[108:111], v[128:131], v[196:199], v[108:111]
	v_mfma_f32_16x16x32_bf16 v[104:107], v[136:139], v[196:199], v[104:107]
	v_mfma_f32_16x16x32_bf16 v[92:95], v[128:131], v[204:207], v[92:95]
	v_mfma_f32_16x16x32_bf16 v[88:91], v[136:139], v[204:207], v[88:91]
	v_mfma_f32_16x16x32_bf16 v[76:79], v[128:131], v[212:215], v[76:79]
	v_mfma_f32_16x16x32_bf16 v[72:75], v[136:139], v[212:215], v[72:75]
	v_mfma_f32_16x16x32_bf16 v[124:127], v[132:135], v[192:195], v[124:127]
	v_mfma_f32_16x16x32_bf16 v[120:123], v[140:143], v[192:195], v[120:123]
	v_mfma_f32_16x16x32_bf16 v[108:111], v[132:135], v[200:203], v[108:111]
	v_mfma_f32_16x16x32_bf16 v[104:107], v[140:143], v[200:203], v[104:107]
	v_mfma_f32_16x16x32_bf16 v[92:95], v[132:135], v[208:211], v[92:95]
	v_mfma_f32_16x16x32_bf16 v[88:91], v[140:143], v[208:211], v[88:91]
	v_mfma_f32_16x16x32_bf16 v[76:79], v[132:135], v[216:219], v[76:79]
	v_mfma_f32_16x16x32_bf16 v[72:75], v[140:143], v[216:219], v[72:75]
	s_setprio 0
	s_setprio 1
	v_mfma_f32_16x16x32_bf16 v[116:119], v[154:157], v[182:185], v[116:119]
	v_mfma_f32_16x16x32_bf16 v[112:115], v[174:177], v[182:185], v[112:115]
	v_mfma_f32_16x16x32_bf16 v[100:103], v[154:157], v[196:199], v[100:103]
	v_mfma_f32_16x16x32_bf16 v[96:99], v[174:177], v[196:199], v[96:99]
	v_mfma_f32_16x16x32_bf16 v[84:87], v[154:157], v[204:207], v[84:87]
	v_mfma_f32_16x16x32_bf16 v[80:83], v[174:177], v[204:207], v[80:83]
	v_mfma_f32_16x16x32_bf16 v[68:71], v[154:157], v[212:215], v[68:71]
	v_mfma_f32_16x16x32_bf16 v[64:67], v[174:177], v[212:215], v[64:67]
	v_mfma_f32_16x16x32_bf16 v[116:119], v[166:169], v[192:195], v[116:119]
	v_mfma_f32_16x16x32_bf16 v[112:115], v[178:181], v[192:195], v[112:115]
	v_mfma_f32_16x16x32_bf16 v[100:103], v[166:169], v[200:203], v[100:103]
	v_mfma_f32_16x16x32_bf16 v[96:99], v[178:181], v[200:203], v[96:99]
	v_mfma_f32_16x16x32_bf16 v[84:87], v[166:169], v[208:211], v[84:87]
	v_mfma_f32_16x16x32_bf16 v[80:83], v[178:181], v[208:211], v[80:83]
	v_mfma_f32_16x16x32_bf16 v[68:71], v[166:169], v[216:219], v[68:71]
	v_mfma_f32_16x16x32_bf16 v[64:67], v[178:181], v[216:219], v[64:67]
	s_setprio 0
	s_barrier
; #define PG8_STAGE(bufoff, gbase, voff) do { _Pragma("unroll") for (int _i = 0; _i < 2; ++_i) \
;         __builtin_amdgcn_global_load_lds((const unsigned*)((const char*)(gbase) + (voff)[_i]), (PG8_LAS unsigned*)(lds + (bufoff) + ldsw + _i * 8192), 16, 0, 0); } while (0)
; #define PG8_LDA(dst, b, h) do { _Pragma("unroll") for (int m = 0; m < 4; ++m) _Pragma("unroll") for (int k = 0; k < 2; ++k) dst[m][k] = *(const PG8_LAS bf16x8*)(lds + PG8_SA(b, h) + aoff + m * 2048 + k * 1024); } while (0)
; #define PG8_LDB(dst, b, h) do { _Pragma("unroll") for (int n = 0; n < 2; ++n) _Pragma("unroll") for (int k = 0; k < 2; ++k) dst[n][k] = *(const PG8_LAS bf16x8*)(lds + PG8_SB(b, h) + boff + n * 2048 + k * 1024); } while (0)
; #define PG8_MMA(ai, bj, At, Bt) do { __builtin_amdgcn_s_setprio(1); _Pragma("unroll") for (int m = 0; m < 4; ++m) _Pragma("unroll") for (int n = 0; n < 2; ++n) _Pragma("unroll") for (int k = 0; k < 2; ++k) \
;         acc[ai][bj][m][n] = __builtin_amdgcn_mfma_f32_16x16x32_bf16(Bt[n][k], At[m][k], acc[ai][bj][m][n], 0, 0, 0); __builtin_amdgcn_s_setprio(0); } while (0)
; template <class Epi, class Sched, bool ALIGN_EPI = false, bool SP2 = false>
; __device__ __forceinline__ void gemm_phase(PG8_LAS unsigned char* lds, const Gemm g, const Sched& S, const Epi& E) {
;     ...
;             if constexpr (SP2) {
;             PG8_LDB(B0, 0, 0); PG8_LDB(B1, 0, 1); PG8_SCHED; PG8_LDA(At, 0, 0); PG8_STAGE(PG8_SA(1, 1), a1 + hstepA, voffA);
;             PG8_WAIT_V(8); PG8_WAIT_L(0); PG8_BAR; PG8_MMA(0, 0, At, B0); PG8_MMA(0, 1, At, B1); PG8_BAR; PG8_SCHED;
;             PG8_LDA(At, 0, 1); PG8_STAGE(PG8_SB(0, 0), b2, voffB); PG8_STAGE(PG8_SB(0, 1), b2 + hstepB, voffB); PG8_STAGE(PG8_SA(0, 0), a2, voffA);
;             PG8_WAIT_V(8); PG8_WAIT_L(0); PG8_BAR; PG8_MMA(1, 0, At, B0); PG8_MMA(1, 1, At, B1); PG8_BAR; PG8_SCHED;
;             PG8_LDB(B0, 1, 0); PG8_LDB(B1, 1, 1); PG8_SCHED; PG8_LDA(At, 1, 0); PG8_STAGE(PG8_SA(0, 1), a2 + hstepA, voffA);
;             PG8_WAIT_V(8); PG8_WAIT_L(0); PG8_BAR; PG8_MMA(0, 0, At, B0); PG8_MMA(0, 1, At, B1); PG8_BAR; PG8_SCHED;
;             PG8_LDA(At, 1, 1); PG8_STAGE(PG8_SB(1, 0), b3, voffB); PG8_STAGE(PG8_SB(1, 1), b3 + hstepB, voffB); PG8_STAGE(PG8_SA(1, 0), a3, voffA);
;             PG8_WAIT_V(8); PG8_WAIT_L(0); PG8_BAR; PG8_MMA(1, 0, At, B0); PG8_MMA(1, 1, At, B1); PG8_BAR; PG8_SCHED;
	s_add_i32 s38, s64, s46
	v_lshl_add_u64 v[158:159], v[158:159], 0, s[80:81]
	s_mov_b32 m0, s38
	ds_read_b128 v[182:185], v165 offset:49152
	ds_read_b128 v[192:195], v165 offset:50176
	ds_read_b128 v[196:199], v165 offset:51200
	ds_read_b128 v[200:203], v165 offset:52224
	ds_read_b128 v[204:207], v165 offset:53248
	ds_read_b128 v[208:211], v165 offset:54272
	ds_read_b128 v[212:215], v165 offset:55296
	ds_read_b128 v[216:219], v165 offset:56320
	global_load_lds_dwordx4 v[158:159], off
	s_add_i32 m0, s38, 0x2000
	s_add_u32 s36, s36, 0x10080
	v_lshl_add_u64 v[158:159], v[170:171], 0, s[80:81]
	s_addc_u32 s37, s37, 0
	s_add_i32 s38, s65, s46
	global_load_lds_dwordx4 v[158:159], off
	s_mov_b32 m0, s38
	s_nop 0
	global_load_lds_dwordx4 v172, s[36:37]
	s_add_i32 m0, s38, 0x2000
	s_nop 0
	global_load_lds_dwordx4 v148, s[36:37]
	v_lshl_add_u64 v[158:159], v[186:187], 0, s[80:81]
	s_mov_b32 m0, s57
	s_nop 0
	global_load_lds_dwordx4 v[158:159], off
	v_lshl_add_u64 v[158:159], v[220:221], 0, s[80:81]
	s_mov_b32 m0, s58
	s_nop 0
	global_load_lds_dwordx4 v[158:159], off
	s_waitcnt vmcnt(8)
	s_waitcnt lgkmcnt(0)
	s_barrier
	s_setprio 1
	s_waitcnt lgkmcnt(0)
	v_mfma_f32_16x16x32_bf16 v[60:63], v[128:131], v[182:185], v[60:63]
	v_mfma_f32_16x16x32_bf16 v[56:59], v[136:139], v[182:185], v[56:59]
	v_mfma_f32_16x16x32_bf16 v[44:47], v[128:131], v[196:199], v[44:47]
	v_mfma_f32_16x16x32_bf16 v[40:43], v[136:139], v[196:199], v[40:43]
	v_mfma_f32_16x16x32_bf16 v[28:31], v[128:131], v[204:207], v[28:31]
	v_mfma_f32_16x16x32_bf16 v[24:27], v[136:139], v[204:207], v[24:27]
	v_mfma_f32_16x16x32_bf16 v[12:15], v[128:131], v[212:215], v[12:15]
	v_mfma_f32_16x16x32_bf16 v[8:11], v[136:139], v[212:215], v[8:11]
	v_mfma_f32_16x16x32_bf16 v[60:63], v[132:135], v[192:195], v[60:63]
	v_mfma_f32_16x16x32_bf16 v[56:59], v[140:143], v[192:195], v[56:59]
	v_mfma_f32_16x16x32_bf16 v[44:47], v[132:135], v[200:203], v[44:47]
	v_mfma_f32_16x16x32_bf16 v[40:43], v[140:143], v[200:203], v[40:43]
	v_mfma_f32_16x16x32_bf16 v[28:31], v[132:135], v[208:211], v[28:31]
	v_mfma_f32_16x16x32_bf16 v[24:27], v[140:143], v[208:211], v[24:27]
	v_mfma_f32_16x16x32_bf16 v[12:15], v[132:135], v[216:219], v[12:15]
	v_mfma_f32_16x16x32_bf16 v[8:11], v[140:143], v[216:219], v[8:11]
	s_setprio 0
	s_setprio 1
	v_mfma_f32_16x16x32_bf16 v[52:55], v[154:157], v[182:185], v[52:55]
	v_mfma_f32_16x16x32_bf16 v[48:51], v[174:177], v[182:185], v[48:51]
	v_mfma_f32_16x16x32_bf16 v[36:39], v[154:157], v[196:199], v[36:39]
	v_mfma_f32_16x16x32_bf16 v[32:35], v[174:177], v[196:199], v[32:35]
	v_mfma_f32_16x16x32_bf16 v[20:23], v[154:157], v[204:207], v[20:23]
	v_mfma_f32_16x16x32_bf16 v[16:19], v[174:177], v[204:207], v[16:19]
	v_mfma_f32_16x16x32_bf16 v[4:7], v[154:157], v[212:215], v[4:7]
	v_mfma_f32_16x16x32_bf16 v[0:3], v[174:177], v[212:215], v[0:3]
	v_mfma_f32_16x16x32_bf16 v[52:55], v[166:169], v[192:195], v[52:55]
	v_mfma_f32_16x16x32_bf16 v[48:51], v[178:181], v[192:195], v[48:51]
	v_mfma_f32_16x16x32_bf16 v[36:39], v[166:169], v[200:203], v[36:39]
	v_mfma_f32_16x16x32_bf16 v[32:35], v[178:181], v[200:203], v[32:35]
	v_mfma_f32_16x16x32_bf16 v[20:23], v[166:169], v[208:211], v[20:23]
	v_mfma_f32_16x16x32_bf16 v[16:19], v[178:181], v[208:211], v[16:19]
	v_mfma_f32_16x16x32_bf16 v[4:7], v[166:169], v[216:219], v[4:7]
	v_mfma_f32_16x16x32_bf16 v[0:3], v[178:181], v[216:219], v[0:3]
	s_setprio 0
	s_barrier
	s_add_i32 s63, s63, 2
	s_add_u32 s34, s34, 0x100
	s_addc_u32 s35, s35, 0
	s_add_u32 s61, s61, 0x100
	s_addc_u32 s62, s62, 0
	s_cmp_gt_u32 s63, 13
	s_cbranch_scc0 .LBB0_1786
	s_and_b64 vcc, exec, s[20:21]
	s_cbranch_vccz .LBB0_1789
	s_barrier

; #define PG8_STAGE(bufoff, gbase, voff) do { _Pragma("unroll") for (int _i = 0; _i < 2; ++_i) \
;         __builtin_amdgcn_global_load_lds((const unsigned*)((const char*)(gbase) + (voff)[_i]), (PG8_LAS unsigned*)(lds + (bufoff) + ldsw + _i * 8192), 16, 0, 0); } while (0)
; #define PG8_LDA(dst, b, h) do { _Pragma("unroll") for (int m = 0; m < 4; ++m) _Pragma("unroll") for (int k = 0; k < 2; ++k) dst[m][k] = *(const PG8_LAS bf16x8*)(lds + PG8_SA(b, h) + aoff + m * 2048 + k * 1024); } while (0)
; #define PG8_LDB(dst, b, h) do { _Pragma("unroll") for (int n = 0; n < 2; ++n) _Pragma("unroll") for (int k = 0; k < 2; ++k) dst[n][k] = *(const PG8_LAS bf16x8*)(lds + PG8_SB(b, h) + boff + n * 2048 + k * 1024); } while (0)
; #define PG8_MMA(ai, bj, At, Bt) do { __builtin_amdgcn_s_setprio(1); _Pragma("unroll") for (int m = 0; m < 4; ++m) _Pragma("unroll") for (int n = 0; n < 2; ++n) _Pragma("unroll") for (int k = 0; k < 2; ++k) \
;         acc[ai][bj][m][n] = __builtin_amdgcn_mfma_f32_16x16x32_bf16(Bt[n][k], At[m][k], acc[ai][bj][m][n], 0, 0, 0); __builtin_amdgcn_s_setprio(0); } while (0)
; #define PG8_WAIT_V(n) asm volatile("s_waitcnt vmcnt(" #n ")" ::: "memory")
; #define PG8_WAIT_L(n) asm volatile("s_waitcnt lgkmcnt(" #n ")" ::: "memory")
; template <class Epi, class Sched, bool ALIGN_EPI = false, bool SP2 = false>
; __device__ __forceinline__ void gemm_phase(PG8_LAS unsigned char* lds, const Gemm g, const Sched& S, const Epi& E) {
;     ...
;             const bool last = (t == nt - 2);
;             const char* a1 = cA + (size_t)(t + 1) * kstep;
;             const char* a2 = last ? nA : cA + (size_t)(t + 2) * kstep; const char* b2 = last ? nB : cB + (size_t)(t + 2) * kstep;
;             const char* a3 = a2 + kstep; const char* b3 = b2 + kstep;
;             if (last && has_next) S.a_ready(nxt);
;             if constexpr (SP2) {
;             PG8_LDB(B0, 0, 0); PG8_LDB(B1, 0, 1); PG8_SCHED; PG8_LDA(At, 0, 0); PG8_STAGE(PG8_SA(1, 1), a1 + hstepA, voffA);
;             PG8_WAIT_V(8); PG8_WAIT_L(0); PG8_BAR; PG8_MMA(0, 0, At, B0); PG8_MMA(0, 1, At, B1); PG8_BAR; PG8_SCHED;
;             PG8_LDA(At, 0, 1); PG8_STAGE(PG8_SB(0, 0), b2, voffB); PG8_STAGE(PG8_SB(0, 1), b2 + hstepB, voffB); PG8_STAGE(PG8_SA(0, 0), a2, voffA);
;             PG8_WAIT_V(8); PG8_WAIT_L(0); PG8_BAR; PG8_MMA(1, 0, At, B0); PG8_MMA(1, 1, At, B1); PG8_BAR; PG8_SCHED;
.LBB0_1906:
	s_add_u32 s40, s38, 0xfff00080
	s_addc_u32 s41, s39, -1
	s_add_i32 s71, 0, 0x10000
	s_cmp_eq_u32 s70, 60
	s_cselect_b32 s43, s27, s41
	s_cselect_b32 s42, s35, s40
	s_cselect_b32 s41, s25, s68
	s_cselect_b32 s40, s37, s67
	s_add_i32 s74, 0, 0x14000
	v_add_u32_e32 v92, s71, v181
	v_add_u32_e32 v164, s74, v181
	ds_read_b128 v[72:75], v92
	ds_read_b128 v[80:83], v92 offset:1024
	ds_read_b128 v[88:91], v92 offset:2048
	ds_read_b128 v[92:95], v92 offset:3072
	ds_read_b128 v[152:155], v164
	ds_read_b128 v[156:159], v164 offset:1024
	ds_read_b128 v[160:163], v164 offset:2048
	ds_read_b128 v[164:167], v164 offset:3072
	s_add_i32 m0, s51, 0xc000
	ds_read_b128 v[168:171], v186
	ds_read_b128 v[174:177], v186 offset:1024
	ds_read_b128 v[192:195], v186 offset:2048
	ds_read_b128 v[196:199], v186 offset:3072
	ds_read_b128 v[200:203], v186 offset:4096
	ds_read_b128 v[204:207], v186 offset:5120
	ds_read_b128 v[208:211], v186 offset:6144
	ds_read_b128 v[212:215], v186 offset:7168
	global_load_lds_dwordx4 v148, s[38:39]
	s_add_i32 m0, s51, 0xe000
	s_nop 0
	global_load_lds_dwordx4 v150, s[38:39]
	s_waitcnt vmcnt(8)
	s_waitcnt lgkmcnt(0)
	s_barrier
	s_setprio 1
	s_waitcnt lgkmcnt(0)
	v_mfma_f32_16x16x32_bf16 v[140:143], v[72:75], v[168:171], v[140:143]
	v_mfma_f32_16x16x32_bf16 v[136:139], v[88:91], v[168:171], v[136:139]
	v_mfma_f32_16x16x32_bf16 v[124:127], v[72:75], v[192:195], v[124:127]
	v_mfma_f32_16x16x32_bf16 v[120:123], v[88:91], v[192:195], v[120:123]
	v_mfma_f32_16x16x32_bf16 v[108:111], v[72:75], v[200:203], v[108:111]
	v_mfma_f32_16x16x32_bf16 v[104:107], v[88:91], v[200:203], v[104:107]
	v_mfma_f32_16x16x32_bf16 v[84:87], v[72:75], v[208:211], v[84:87]
	v_mfma_f32_16x16x32_bf16 v[76:79], v[88:91], v[208:211], v[76:79]
	v_mfma_f32_16x16x32_bf16 v[140:143], v[80:83], v[174:177], v[140:143]
	v_mfma_f32_16x16x32_bf16 v[136:139], v[92:95], v[174:177], v[136:139]
	v_mfma_f32_16x16x32_bf16 v[124:127], v[80:83], v[196:199], v[124:127]
	v_mfma_f32_16x16x32_bf16 v[120:123], v[92:95], v[196:199], v[120:123]
	v_mfma_f32_16x16x32_bf16 v[108:111], v[80:83], v[204:207], v[108:111]
	v_mfma_f32_16x16x32_bf16 v[104:107], v[92:95], v[204:207], v[104:107]
	v_mfma_f32_16x16x32_bf16 v[84:87], v[80:83], v[212:215], v[84:87]
	v_mfma_f32_16x16x32_bf16 v[76:79], v[92:95], v[212:215], v[76:79]
	s_setprio 0
	s_setprio 1
	v_mfma_f32_16x16x32_bf16 v[132:135], v[152:155], v[168:171], v[132:135]
	v_mfma_f32_16x16x32_bf16 v[128:131], v[160:163], v[168:171], v[128:131]
	v_mfma_f32_16x16x32_bf16 v[116:119], v[152:155], v[192:195], v[116:119]
	v_mfma_f32_16x16x32_bf16 v[112:115], v[160:163], v[192:195], v[112:115]
	v_mfma_f32_16x16x32_bf16 v[100:103], v[152:155], v[200:203], v[100:103]
	v_mfma_f32_16x16x32_bf16 v[96:99], v[160:163], v[200:203], v[96:99]
	v_mfma_f32_16x16x32_bf16 v[68:71], v[152:155], v[208:211], v[68:71]
	v_mfma_f32_16x16x32_bf16 v[64:67], v[160:163], v[208:211], v[64:67]
	v_mfma_f32_16x16x32_bf16 v[132:135], v[156:159], v[174:177], v[132:135]
	v_mfma_f32_16x16x32_bf16 v[128:131], v[164:167], v[174:177], v[128:131]
	v_mfma_f32_16x16x32_bf16 v[116:119], v[156:159], v[196:199], v[116:119]
	v_mfma_f32_16x16x32_bf16 v[112:115], v[164:167], v[196:199], v[112:115]
	v_mfma_f32_16x16x32_bf16 v[100:103], v[156:159], v[204:207], v[100:103]
	v_mfma_f32_16x16x32_bf16 v[96:99], v[164:167], v[204:207], v[96:99]
	v_mfma_f32_16x16x32_bf16 v[68:71], v[156:159], v[212:215], v[68:71]
	v_mfma_f32_16x16x32_bf16 v[64:67], v[164:167], v[212:215], v[64:67]
	s_setprio 0
	s_barrier
	s_add_i32 s71, s71, s50
	v_lshl_add_u64 v[178:179], s[40:41], 0, v[172:173]
	s_mov_b32 m0, s71
	ds_read_b128 v[168:171], v186 offset:16384
	ds_read_b128 v[174:177], v186 offset:17408
	ds_read_b128 v[192:195], v186 offset:18432
	ds_read_b128 v[196:199], v186 offset:19456
	ds_read_b128 v[200:203], v186 offset:20480
	ds_read_b128 v[204:207], v186 offset:21504
	ds_read_b128 v[208:211], v186 offset:22528
	ds_read_b128 v[212:215], v186 offset:23552
	global_load_lds_dwordx4 v[178:179], off
	s_add_i32 m0, s71, 0x2000
	s_add_u32 s72, s40, 0x100000
	v_lshl_add_u64 v[216:217], s[40:41], 0, v[144:145]
	s_addc_u32 s73, s41, 0
	s_add_i32 s71, s74, s50
	global_load_lds_dwordx4 v[216:217], off
	s_mov_b32 m0, s71
	v_lshl_add_u64 v[220:221], s[42:43], 0, v[144:145]
	global_load_lds_dwordx4 v172, s[72:73]
	s_add_i32 m0, s71, 0x2000
	s_nop 0
	global_load_lds_dwordx4 v144, s[72:73]
	v_lshl_add_u64 v[218:219], s[42:43], 0, v[172:173]
	s_mov_b32 m0, s51
	s_nop 0
	global_load_lds_dwordx4 v[218:219], off
	s_mov_b32 m0, s52
	s_nop 0
	global_load_lds_dwordx4 v[220:221], off
	s_waitcnt vmcnt(8)
	s_waitcnt lgkmcnt(0)
	s_barrier
; #define PG8_STAGE(bufoff, gbase, voff) do { _Pragma("unroll") for (int _i = 0; _i < 2; ++_i) \
;         __builtin_amdgcn_global_load_lds((const unsigned*)((const char*)(gbase) + (voff)[_i]), (PG8_LAS unsigned*)(lds + (bufoff) + ldsw + _i * 8192), 16, 0, 0); } while (0)
; #define PG8_LDA(dst, b, h) do { _Pragma("unroll") for (int m = 0; m < 4; ++m) _Pragma("unroll") for (int k = 0; k < 2; ++k) dst[m][k] = *(const PG8_LAS bf16x8*)(lds + PG8_SA(b, h) + aoff + m * 2048 + k * 1024); } while (0)
; #define PG8_LDB(dst, b, h) do { _Pragma("unroll") for (int n = 0; n < 2; ++n) _Pragma("unroll") for (int k = 0; k < 2; ++k) dst[n][k] = *(const PG8_LAS bf16x8*)(lds + PG8_SB(b, h) + boff + n * 2048 + k * 1024); } while (0)
; #define PG8_MMA(ai, bj, At, Bt) do { __builtin_amdgcn_s_setprio(1); _Pragma("unroll") for (int m = 0; m < 4; ++m) _Pragma("unroll") for (int n = 0; n < 2; ++n) _Pragma("unroll") for (int k = 0; k < 2; ++k) \
;         acc[ai][bj][m][n] = __builtin_amdgcn_mfma_f32_16x16x32_bf16(Bt[n][k], At[m][k], acc[ai][bj][m][n], 0, 0, 0); __builtin_amdgcn_s_setprio(0); } while (0)
; #define PG8_WAIT_V(n) asm volatile("s_waitcnt vmcnt(" #n ")" ::: "memory")
; #define PG8_WAIT_L(n) asm volatile("s_waitcnt lgkmcnt(" #n ")" ::: "memory")
; #define PG8_BAR __builtin_amdgcn_s_barrier()
; #define PG8_SCHED __builtin_amdgcn_sched_barrier(0)
; template <class Epi, class Sched, bool ALIGN_EPI = false, bool SP2 = false>
; __device__ __forceinline__ void gemm_phase(PG8_LAS unsigned char* lds, const Gemm g, const Sched& S, const Epi& E) {
;     ...
;             PG8_WAIT_V(8); PG8_WAIT_L(0); PG8_BAR; PG8_MMA(1, 0, At, B0); PG8_MMA(1, 1, At, B1); PG8_BAR; PG8_SCHED;
;             PG8_LDB(B0, 1, 0); PG8_LDB(B1, 1, 1); PG8_SCHED; PG8_LDA(At, 1, 0); PG8_STAGE(PG8_SA(0, 1), a2 + hstepA, voffA);
;             PG8_WAIT_V(8); PG8_WAIT_L(0); PG8_BAR; PG8_MMA(0, 0, At, B0); PG8_MMA(0, 1, At, B1); PG8_BAR; PG8_SCHED;
	s_setprio 1
	s_waitcnt lgkmcnt(0)
	v_mfma_f32_16x16x32_bf16 v[60:63], v[72:75], v[168:171], v[60:63]
	v_mfma_f32_16x16x32_bf16 v[56:59], v[88:91], v[168:171], v[56:59]
	v_mfma_f32_16x16x32_bf16 v[44:47], v[72:75], v[192:195], v[44:47]
	v_mfma_f32_16x16x32_bf16 v[40:43], v[88:91], v[192:195], v[40:43]
	v_mfma_f32_16x16x32_bf16 v[28:31], v[72:75], v[200:203], v[28:31]
	v_mfma_f32_16x16x32_bf16 v[24:27], v[88:91], v[200:203], v[24:27]
	v_mfma_f32_16x16x32_bf16 v[12:15], v[72:75], v[208:211], v[12:15]
	v_mfma_f32_16x16x32_bf16 v[8:11], v[88:91], v[208:211], v[8:11]
	v_mfma_f32_16x16x32_bf16 v[60:63], v[80:83], v[174:177], v[60:63]
	v_mfma_f32_16x16x32_bf16 v[56:59], v[92:95], v[174:177], v[56:59]
	v_mfma_f32_16x16x32_bf16 v[44:47], v[80:83], v[196:199], v[44:47]
	v_mfma_f32_16x16x32_bf16 v[40:43], v[92:95], v[196:199], v[40:43]
	v_mfma_f32_16x16x32_bf16 v[28:31], v[80:83], v[204:207], v[28:31]
	v_mfma_f32_16x16x32_bf16 v[24:27], v[92:95], v[204:207], v[24:27]
	v_mfma_f32_16x16x32_bf16 v[12:15], v[80:83], v[212:215], v[12:15]
	v_mfma_f32_16x16x32_bf16 v[8:11], v[92:95], v[212:215], v[8:11]
	s_setprio 0
	s_setprio 1
	v_mfma_f32_16x16x32_bf16 v[52:55], v[152:155], v[168:171], v[52:55]
	v_mfma_f32_16x16x32_bf16 v[48:51], v[160:163], v[168:171], v[48:51]
	v_mfma_f32_16x16x32_bf16 v[36:39], v[152:155], v[192:195], v[36:39]
	v_mfma_f32_16x16x32_bf16 v[32:35], v[160:163], v[192:195], v[32:35]
	v_mfma_f32_16x16x32_bf16 v[20:23], v[152:155], v[200:203], v[20:23]
	v_mfma_f32_16x16x32_bf16 v[16:19], v[160:163], v[200:203], v[16:19]
	v_mfma_f32_16x16x32_bf16 v[4:7], v[152:155], v[208:211], v[4:7]
	v_mfma_f32_16x16x32_bf16 v[0:3], v[160:163], v[208:211], v[0:3]
	v_mfma_f32_16x16x32_bf16 v[52:55], v[156:159], v[174:177], v[52:55]
	v_mfma_f32_16x16x32_bf16 v[48:51], v[164:167], v[174:177], v[48:51]
	v_mfma_f32_16x16x32_bf16 v[36:39], v[156:159], v[196:199], v[36:39]
	v_mfma_f32_16x16x32_bf16 v[32:35], v[164:167], v[196:199], v[32:35]
	v_mfma_f32_16x16x32_bf16 v[20:23], v[156:159], v[204:207], v[20:23]
	v_mfma_f32_16x16x32_bf16 v[16:19], v[164:167], v[204:207], v[16:19]
	v_mfma_f32_16x16x32_bf16 v[4:7], v[156:159], v[212:215], v[4:7]
	v_mfma_f32_16x16x32_bf16 v[0:3], v[164:167], v[212:215], v[0:3]
	s_setprio 0
	s_barrier
	s_add_i32 s71, 0, 0x18000
	s_add_i32 s72, 0, 0x1c000
	v_add_u32_e32 v92, s71, v181
	v_add_u32_e32 v164, s72, v181
	ds_read_b128 v[72:75], v92
	ds_read_b128 v[80:83], v92 offset:1024
	ds_read_b128 v[88:91], v92 offset:2048
	ds_read_b128 v[92:95], v92 offset:3072
	ds_read_b128 v[152:155], v164
	ds_read_b128 v[156:159], v164 offset:1024
	ds_read_b128 v[160:163], v164 offset:2048
	ds_read_b128 v[164:167], v164 offset:3072
	s_add_u32 s42, s42, 0x100000
	s_addc_u32 s43, s43, 0
	s_mov_b32 m0, s53
	ds_read_b128 v[168:171], v186 offset:32768
	ds_read_b128 v[174:177], v186 offset:33792
	ds_read_b128 v[192:195], v186 offset:34816
	ds_read_b128 v[196:199], v186 offset:35840
	ds_read_b128 v[200:203], v186 offset:36864
	ds_read_b128 v[204:207], v186 offset:37888
	ds_read_b128 v[208:211], v186 offset:38912
	ds_read_b128 v[212:215], v186 offset:39936
	global_load_lds_dwordx4 v172, s[42:43]
	v_lshl_add_u64 v[222:223], s[42:43], 0, v[144:145]
	s_mov_b32 m0, s57
	s_nop 0
	global_load_lds_dwordx4 v[222:223], off
	s_waitcnt vmcnt(8)
	s_waitcnt lgkmcnt(0)
	s_barrier
	s_setprio 1
	s_waitcnt lgkmcnt(0)
	v_mfma_f32_16x16x32_bf16 v[140:143], v[72:75], v[168:171], v[140:143]
	v_mfma_f32_16x16x32_bf16 v[136:139], v[88:91], v[168:171], v[136:139]
	v_mfma_f32_16x16x32_bf16 v[124:127], v[72:75], v[192:195], v[124:127]
	v_mfma_f32_16x16x32_bf16 v[120:123], v[88:91], v[192:195], v[120:123]
	v_mfma_f32_16x16x32_bf16 v[108:111], v[72:75], v[200:203], v[108:111]
	v_mfma_f32_16x16x32_bf16 v[104:107], v[88:91], v[200:203], v[104:107]
	v_mfma_f32_16x16x32_bf16 v[84:87], v[72:75], v[208:211], v[84:87]
	v_mfma_f32_16x16x32_bf16 v[76:79], v[88:91], v[208:211], v[76:79]
	v_mfma_f32_16x16x32_bf16 v[140:143], v[80:83], v[174:177], v[140:143]
	v_mfma_f32_16x16x32_bf16 v[136:139], v[92:95], v[174:177], v[136:139]
	v_mfma_f32_16x16x32_bf16 v[124:127], v[80:83], v[196:199], v[124:127]
	v_mfma_f32_16x16x32_bf16 v[120:123], v[92:95], v[196:199], v[120:123]
	v_mfma_f32_16x16x32_bf16 v[108:111], v[80:83], v[204:207], v[108:111]
	v_mfma_f32_16x16x32_bf16 v[104:107], v[92:95], v[204:207], v[104:107]
	v_mfma_f32_16x16x32_bf16 v[84:87], v[80:83], v[212:215], v[84:87]
	v_mfma_f32_16x16x32_bf16 v[76:79], v[92:95], v[212:215], v[76:79]
	s_setprio 0
	s_setprio 1
	v_mfma_f32_16x16x32_bf16 v[132:135], v[152:155], v[168:171], v[132:135]
	v_mfma_f32_16x16x32_bf16 v[128:131], v[160:163], v[168:171], v[128:131]
	v_mfma_f32_16x16x32_bf16 v[116:119], v[152:155], v[192:195], v[116:119]
	v_mfma_f32_16x16x32_bf16 v[112:115], v[160:163], v[192:195], v[112:115]
	v_mfma_f32_16x16x32_bf16 v[100:103], v[152:155], v[200:203], v[100:103]
	v_mfma_f32_16x16x32_bf16 v[96:99], v[160:163], v[200:203], v[96:99]
	v_mfma_f32_16x16x32_bf16 v[68:71], v[152:155], v[208:211], v[68:71]
	v_mfma_f32_16x16x32_bf16 v[64:67], v[160:163], v[208:211], v[64:67]
	v_mfma_f32_16x16x32_bf16 v[132:135], v[156:159], v[174:177], v[132:135]
	v_mfma_f32_16x16x32_bf16 v[128:131], v[164:167], v[174:177], v[128:131]
	v_mfma_f32_16x16x32_bf16 v[116:119], v[156:159], v[196:199], v[116:119]
	v_mfma_f32_16x16x32_bf16 v[112:115], v[164:167], v[196:199], v[112:115]
	v_mfma_f32_16x16x32_bf16 v[100:103], v[156:159], v[204:207], v[100:103]
	v_mfma_f32_16x16x32_bf16 v[96:99], v[164:167], v[204:207], v[96:99]
	v_mfma_f32_16x16x32_bf16 v[68:71], v[156:159], v[212:215], v[68:71]
	v_mfma_f32_16x16x32_bf16 v[64:67], v[164:167], v[212:215], v[64:67]
	s_setprio 0
	s_barrier
; #define PG8_STAGE(bufoff, gbase, voff) do { _Pragma("unroll") for (int _i = 0; _i < 2; ++_i) \
;         __builtin_amdgcn_global_load_lds((const unsigned*)((const char*)(gbase) + (voff)[_i]), (PG8_LAS unsigned*)(lds + (bufoff) + ldsw + _i * 8192), 16, 0, 0); } while (0)
; #define PG8_LDA(dst, b, h) do { _Pragma("unroll") for (int m = 0; m < 4; ++m) _Pragma("unroll") for (int k = 0; k < 2; ++k) dst[m][k] = *(const PG8_LAS bf16x8*)(lds + PG8_SA(b, h) + aoff + m * 2048 + k * 1024); } while (0)
; #define PG8_MMA(ai, bj, At, Bt) do { __builtin_amdgcn_s_setprio(1); _Pragma("unroll") for (int m = 0; m < 4; ++m) _Pragma("unroll") for (int n = 0; n < 2; ++n) _Pragma("unroll") for (int k = 0; k < 2; ++k) \
;         acc[ai][bj][m][n] = __builtin_amdgcn_mfma_f32_16x16x32_bf16(Bt[n][k], At[m][k], acc[ai][bj][m][n], 0, 0, 0); __builtin_amdgcn_s_setprio(0); } while (0)
; #define PG8_WAIT_V(n) asm volatile("s_waitcnt vmcnt(" #n ")" ::: "memory")
; #define PG8_WAIT_L(n) asm volatile("s_waitcnt lgkmcnt(" #n ")" ::: "memory")
; #define PG8_BAR __builtin_amdgcn_s_barrier()
; #define PG8_SCHED __builtin_amdgcn_sched_barrier(0)
; template <class Epi, class Sched, bool ALIGN_EPI = false, bool SP2 = false>
; __device__ __forceinline__ void gemm_phase(PG8_LAS unsigned char* lds, const Gemm g, const Sched& S, const Epi& E) {
;     ...
;             PG8_LDA(At, 1, 1); PG8_STAGE(PG8_SB(1, 0), b3, voffB); PG8_STAGE(PG8_SB(1, 1), b3 + hstepB, voffB); PG8_STAGE(PG8_SA(1, 0), a3, voffA);
;             PG8_WAIT_V(8); PG8_WAIT_L(0); PG8_BAR; PG8_MMA(1, 0, At, B0); PG8_MMA(1, 1, At, B1); PG8_BAR; PG8_SCHED;
	s_add_i32 s42, s71, s50
	v_lshl_add_u64 v[178:179], v[178:179], 0, s[80:81]
	s_mov_b32 m0, s42
	ds_read_b128 v[168:171], v186 offset:49152
	ds_read_b128 v[174:177], v186 offset:50176
	ds_read_b128 v[192:195], v186 offset:51200
	ds_read_b128 v[196:199], v186 offset:52224
	ds_read_b128 v[200:203], v186 offset:53248
	ds_read_b128 v[204:207], v186 offset:54272
	ds_read_b128 v[208:211], v186 offset:55296
	ds_read_b128 v[212:215], v186 offset:56320
	global_load_lds_dwordx4 v[178:179], off
	s_add_i32 m0, s42, 0x2000
	s_add_u32 s40, s40, 0x100080
	v_lshl_add_u64 v[178:179], v[216:217], 0, s[80:81]
	s_addc_u32 s41, s41, 0
	s_add_i32 s42, s72, s50
	global_load_lds_dwordx4 v[178:179], off
	s_mov_b32 m0, s42
	s_nop 0
	global_load_lds_dwordx4 v172, s[40:41]
	s_add_i32 m0, s42, 0x2000
	s_nop 0
	global_load_lds_dwordx4 v144, s[40:41]
	v_lshl_add_u64 v[178:179], v[218:219], 0, s[80:81]
	s_mov_b32 m0, s62
	s_nop 0
	global_load_lds_dwordx4 v[178:179], off
	v_lshl_add_u64 v[178:179], v[220:221], 0, s[80:81]
	s_mov_b32 m0, s63
	s_nop 0
	global_load_lds_dwordx4 v[178:179], off
	s_waitcnt vmcnt(8)
	s_waitcnt lgkmcnt(0)
	s_barrier
	s_setprio 1
	s_waitcnt lgkmcnt(0)
	v_mfma_f32_16x16x32_bf16 v[60:63], v[72:75], v[168:171], v[60:63]
	v_mfma_f32_16x16x32_bf16 v[56:59], v[88:91], v[168:171], v[56:59]
	v_mfma_f32_16x16x32_bf16 v[44:47], v[72:75], v[192:195], v[44:47]
	v_mfma_f32_16x16x32_bf16 v[40:43], v[88:91], v[192:195], v[40:43]
	v_mfma_f32_16x16x32_bf16 v[28:31], v[72:75], v[200:203], v[28:31]
	v_mfma_f32_16x16x32_bf16 v[24:27], v[88:91], v[200:203], v[24:27]
	v_mfma_f32_16x16x32_bf16 v[12:15], v[72:75], v[208:211], v[12:15]
	v_mfma_f32_16x16x32_bf16 v[8:11], v[88:91], v[208:211], v[8:11]
	v_mfma_f32_16x16x32_bf16 v[60:63], v[80:83], v[174:177], v[60:63]
	v_mfma_f32_16x16x32_bf16 v[56:59], v[92:95], v[174:177], v[56:59]
	v_mfma_f32_16x16x32_bf16 v[44:47], v[80:83], v[196:199], v[44:47]
	v_mfma_f32_16x16x32_bf16 v[40:43], v[92:95], v[196:199], v[40:43]
	v_mfma_f32_16x16x32_bf16 v[28:31], v[80:83], v[204:207], v[28:31]
	v_mfma_f32_16x16x32_bf16 v[24:27], v[92:95], v[204:207], v[24:27]
	v_mfma_f32_16x16x32_bf16 v[12:15], v[80:83], v[212:215], v[12:15]
	v_mfma_f32_16x16x32_bf16 v[8:11], v[92:95], v[212:215], v[8:11]
	s_setprio 0
	s_setprio 1
	v_mfma_f32_16x16x32_bf16 v[52:55], v[152:155], v[168:171], v[52:55]
	v_mfma_f32_16x16x32_bf16 v[48:51], v[160:163], v[168:171], v[48:51]
	v_mfma_f32_16x16x32_bf16 v[36:39], v[152:155], v[192:195], v[36:39]
	v_mfma_f32_16x16x32_bf16 v[32:35], v[160:163], v[192:195], v[32:35]
	v_mfma_f32_16x16x32_bf16 v[20:23], v[152:155], v[200:203], v[20:23]
	v_mfma_f32_16x16x32_bf16 v[16:19], v[160:163], v[200:203], v[16:19]
	v_mfma_f32_16x16x32_bf16 v[4:7], v[152:155], v[208:211], v[4:7]
	v_mfma_f32_16x16x32_bf16 v[0:3], v[160:163], v[208:211], v[0:3]
	v_mfma_f32_16x16x32_bf16 v[52:55], v[156:159], v[174:177], v[52:55]
	v_mfma_f32_16x16x32_bf16 v[48:51], v[164:167], v[174:177], v[48:51]
	v_mfma_f32_16x16x32_bf16 v[36:39], v[156:159], v[196:199], v[36:39]
	v_mfma_f32_16x16x32_bf16 v[32:35], v[164:167], v[196:199], v[32:35]
	v_mfma_f32_16x16x32_bf16 v[20:23], v[156:159], v[204:207], v[20:23]
	v_mfma_f32_16x16x32_bf16 v[16:19], v[164:167], v[204:207], v[16:19]
	v_mfma_f32_16x16x32_bf16 v[4:7], v[156:159], v[212:215], v[4:7]
	v_mfma_f32_16x16x32_bf16 v[0:3], v[164:167], v[212:215], v[0:3]
	s_setprio 0
	s_barrier
	s_add_i32 s70, s70, 2
	s_add_u32 s38, s38, 0x100
	s_addc_u32 s39, s39, 0
	s_add_u32 s67, s67, 0x100
	s_addc_u32 s68, s68, 0
	s_cmp_gt_u32 s70, 61
	s_cbranch_scc0 .LBB0_1906
	s_and_b64 vcc, exec, s[22:23]
	s_cbranch_vccz .LBB0_1909
	s_barrier

; #define PG8_STAGE(bufoff, gbase, voff) do { _Pragma("unroll") for (int _i = 0; _i < 2; ++_i) \
;         __builtin_amdgcn_global_load_lds((const unsigned*)((const char*)(gbase) + (voff)[_i]), (PG8_LAS unsigned*)(lds + (bufoff) + ldsw + _i * 8192), 16, 0, 0); } while (0)
; #define PG8_LDA(dst, b, h) do { _Pragma("unroll") for (int m = 0; m < 4; ++m) _Pragma("unroll") for (int k = 0; k < 2; ++k) dst[m][k] = *(const PG8_LAS bf16x8*)(lds + PG8_SA(b, h) + aoff + m * 2048 + k * 1024); } while (0)
; #define PG8_LDB(dst, b, h) do { _Pragma("unroll") for (int n = 0; n < 2; ++n) _Pragma("unroll") for (int k = 0; k < 2; ++k) dst[n][k] = *(const PG8_LAS bf16x8*)(lds + PG8_SB(b, h) + boff + n * 2048 + k * 1024); } while (0)
; #define PG8_MMA(ai, bj, At, Bt) do { __builtin_amdgcn_s_setprio(1); _Pragma("unroll") for (int m = 0; m < 4; ++m) _Pragma("unroll") for (int n = 0; n < 2; ++n) _Pragma("unroll") for (int k = 0; k < 2; ++k) \
;         acc[ai][bj][m][n] = __builtin_amdgcn_mfma_f32_16x16x32_bf16(Bt[n][k], At[m][k], acc[ai][bj][m][n], 0, 0, 0); __builtin_amdgcn_s_setprio(0); } while (0)
; #define PG8_WAIT_V(n) asm volatile("s_waitcnt vmcnt(" #n ")" ::: "memory")
; #define PG8_WAIT_L(n) asm volatile("s_waitcnt lgkmcnt(" #n ")" ::: "memory")
; template <class Epi, class Sched, bool ALIGN_EPI = false, bool SP2 = false>
; __device__ __forceinline__ void gemm_phase(PG8_LAS unsigned char* lds, const Gemm g, const Sched& S, const Epi& E) {
;     ...
;             const bool last = (t == nt - 2);
;             const char* a1 = cA + (size_t)(t + 1) * kstep;
;             const char* a2 = last ? nA : cA + (size_t)(t + 2) * kstep; const char* b2 = last ? nB : cB + (size_t)(t + 2) * kstep;
;             const char* a3 = a2 + kstep; const char* b3 = b2 + kstep;
;             if (last && has_next) S.a_ready(nxt);
;             if constexpr (SP2) {
;             PG8_LDB(B0, 0, 0); PG8_LDB(B1, 0, 1); PG8_SCHED; PG8_LDA(At, 0, 0); PG8_STAGE(PG8_SA(1, 1), a1 + hstepA, voffA);
;             PG8_WAIT_V(8); PG8_WAIT_L(0); PG8_BAR; PG8_MMA(0, 0, At, B0); PG8_MMA(0, 1, At, B1); PG8_BAR; PG8_SCHED;
;             PG8_LDA(At, 0, 1); PG8_STAGE(PG8_SB(0, 0), b2, voffB); PG8_STAGE(PG8_SB(0, 1), b2 + hstepB, voffB); PG8_STAGE(PG8_SA(0, 0), a2, voffA);
;             PG8_WAIT_V(8); PG8_WAIT_L(0); PG8_BAR; PG8_MMA(1, 0, At, B0); PG8_MMA(1, 1, At, B1); PG8_BAR; PG8_SCHED;
.LBB0_1950:
	s_add_u32 s30, s28, 0xfff00080
	s_addc_u32 s31, s29, -1
	s_add_i32 s62, 0, 0x10000
	s_cmp_eq_u32 s61, 60
	s_cselect_b32 s35, s21, s31
	s_cselect_b32 s34, s27, s30
	s_cselect_b32 s31, s15, s60
	s_cselect_b32 s30, s58, s59
	s_add_i32 s64, 0, 0x14000
	v_add_u32_e32 v108, s62, v153
	v_add_u32_e32 v150, s64, v153
	ds_read_b128 v[52:55], v108
	ds_read_b128 v[92:95], v108 offset:1024
	ds_read_b128 v[100:103], v108 offset:2048
	ds_read_b128 v[108:111], v108 offset:3072
	ds_read_b128 v[156:159], v150
	ds_read_b128 v[160:163], v150 offset:1024
	ds_read_b128 v[164:167], v150 offset:2048
	ds_read_b128 v[168:171], v150 offset:3072
	s_add_i32 m0, s38, 0xc000
	ds_read_b128 v[174:177], v155
	ds_read_b128 v[178:181], v155 offset:1024
	ds_read_b128 v[182:185], v155 offset:2048
	ds_read_b128 v[192:195], v155 offset:3072
	ds_read_b128 v[196:199], v155 offset:4096
	ds_read_b128 v[200:203], v155 offset:5120
	ds_read_b128 v[204:207], v155 offset:6144
	ds_read_b128 v[208:211], v155 offset:7168
	global_load_lds_dwordx4 v146, s[28:29]
	s_add_i32 m0, s38, 0xe000
	s_nop 0
	global_load_lds_dwordx4 v148, s[28:29]
	s_waitcnt vmcnt(8)
	s_waitcnt lgkmcnt(0)
	s_barrier
	s_setprio 1
	s_waitcnt lgkmcnt(0)
	v_mfma_f32_16x16x32_bf16 v[140:143], v[52:55], v[174:177], v[140:143]
	v_mfma_f32_16x16x32_bf16 v[136:139], v[100:103], v[174:177], v[136:139]
	v_mfma_f32_16x16x32_bf16 v[124:127], v[52:55], v[182:185], v[124:127]
	v_mfma_f32_16x16x32_bf16 v[120:123], v[100:103], v[182:185], v[120:123]
	v_mfma_f32_16x16x32_bf16 v[104:107], v[52:55], v[196:199], v[104:107]
	v_mfma_f32_16x16x32_bf16 v[96:99], v[100:103], v[196:199], v[96:99]
	v_mfma_f32_16x16x32_bf16 v[80:83], v[52:55], v[204:207], v[80:83]
	v_mfma_f32_16x16x32_bf16 v[76:79], v[100:103], v[204:207], v[76:79]
	v_mfma_f32_16x16x32_bf16 v[140:143], v[92:95], v[178:181], v[140:143]
	v_mfma_f32_16x16x32_bf16 v[136:139], v[108:111], v[178:181], v[136:139]
	v_mfma_f32_16x16x32_bf16 v[124:127], v[92:95], v[192:195], v[124:127]
	v_mfma_f32_16x16x32_bf16 v[120:123], v[108:111], v[192:195], v[120:123]
	v_mfma_f32_16x16x32_bf16 v[104:107], v[92:95], v[200:203], v[104:107]
	v_mfma_f32_16x16x32_bf16 v[96:99], v[108:111], v[200:203], v[96:99]
	v_mfma_f32_16x16x32_bf16 v[80:83], v[92:95], v[208:211], v[80:83]
	v_mfma_f32_16x16x32_bf16 v[76:79], v[108:111], v[208:211], v[76:79]
	s_setprio 0
	s_setprio 1
	v_mfma_f32_16x16x32_bf16 v[132:135], v[156:159], v[174:177], v[132:135]
	v_mfma_f32_16x16x32_bf16 v[128:131], v[164:167], v[174:177], v[128:131]
	v_mfma_f32_16x16x32_bf16 v[116:119], v[156:159], v[182:185], v[116:119]
	v_mfma_f32_16x16x32_bf16 v[112:115], v[164:167], v[182:185], v[112:115]
	v_mfma_f32_16x16x32_bf16 v[88:91], v[156:159], v[196:199], v[88:91]
	v_mfma_f32_16x16x32_bf16 v[84:87], v[164:167], v[196:199], v[84:87]
	v_mfma_f32_16x16x32_bf16 v[72:75], v[156:159], v[204:207], v[72:75]
	v_mfma_f32_16x16x32_bf16 v[68:71], v[164:167], v[204:207], v[68:71]
	v_mfma_f32_16x16x32_bf16 v[132:135], v[160:163], v[178:181], v[132:135]
	v_mfma_f32_16x16x32_bf16 v[128:131], v[168:171], v[178:181], v[128:131]
	v_mfma_f32_16x16x32_bf16 v[116:119], v[160:163], v[192:195], v[116:119]
	v_mfma_f32_16x16x32_bf16 v[112:115], v[168:171], v[192:195], v[112:115]
	v_mfma_f32_16x16x32_bf16 v[88:91], v[160:163], v[200:203], v[88:91]
	v_mfma_f32_16x16x32_bf16 v[84:87], v[168:171], v[200:203], v[84:87]
	v_mfma_f32_16x16x32_bf16 v[72:75], v[160:163], v[208:211], v[72:75]
	v_mfma_f32_16x16x32_bf16 v[68:71], v[168:171], v[208:211], v[68:71]
	s_setprio 0
	s_barrier
	s_add_i32 s62, s62, s37
	v_lshl_add_u64 v[150:151], s[30:31], 0, v[172:173]
	s_mov_b32 m0, s62
	ds_read_b128 v[174:177], v155 offset:16384
	ds_read_b128 v[178:181], v155 offset:17408
	ds_read_b128 v[182:185], v155 offset:18432
	ds_read_b128 v[192:195], v155 offset:19456
	ds_read_b128 v[196:199], v155 offset:20480
	ds_read_b128 v[200:203], v155 offset:21504
	ds_read_b128 v[204:207], v155 offset:22528
	ds_read_b128 v[208:211], v155 offset:23552
	global_load_lds_dwordx4 v[150:151], off
	s_add_i32 m0, s62, 0x2000
	s_add_u32 s62, s30, 0x100000
	v_lshl_add_u64 v[186:187], s[30:31], 0, v[144:145]
	s_addc_u32 s63, s31, 0
	s_add_i32 s64, s64, s37
	global_load_lds_dwordx4 v[186:187], off
	s_mov_b32 m0, s64
	v_lshl_add_u64 v[214:215], s[34:35], 0, v[144:145]
	global_load_lds_dwordx4 v172, s[62:63]
	s_add_i32 m0, s64, 0x2000
	s_nop 0
	global_load_lds_dwordx4 v144, s[62:63]
	v_lshl_add_u64 v[212:213], s[34:35], 0, v[172:173]
	s_mov_b32 m0, s38
	s_nop 0
	global_load_lds_dwordx4 v[212:213], off
	s_mov_b32 m0, s39
	s_nop 0
	global_load_lds_dwordx4 v[214:215], off
	s_waitcnt vmcnt(8)
	s_waitcnt lgkmcnt(0)
	s_barrier
; #define PG8_STAGE(bufoff, gbase, voff) do { _Pragma("unroll") for (int _i = 0; _i < 2; ++_i) \
;         __builtin_amdgcn_global_load_lds((const unsigned*)((const char*)(gbase) + (voff)[_i]), (PG8_LAS unsigned*)(lds + (bufoff) + ldsw + _i * 8192), 16, 0, 0); } while (0)
; #define PG8_LDA(dst, b, h) do { _Pragma("unroll") for (int m = 0; m < 4; ++m) _Pragma("unroll") for (int k = 0; k < 2; ++k) dst[m][k] = *(const PG8_LAS bf16x8*)(lds + PG8_SA(b, h) + aoff + m * 2048 + k * 1024); } while (0)
; #define PG8_LDB(dst, b, h) do { _Pragma("unroll") for (int n = 0; n < 2; ++n) _Pragma("unroll") for (int k = 0; k < 2; ++k) dst[n][k] = *(const PG8_LAS bf16x8*)(lds + PG8_SB(b, h) + boff + n * 2048 + k * 1024); } while (0)
; #define PG8_MMA(ai, bj, At, Bt) do { __builtin_amdgcn_s_setprio(1); _Pragma("unroll") for (int m = 0; m < 4; ++m) _Pragma("unroll") for (int n = 0; n < 2; ++n) _Pragma("unroll") for (int k = 0; k < 2; ++k) \
;         acc[ai][bj][m][n] = __builtin_amdgcn_mfma_f32_16x16x32_bf16(Bt[n][k], At[m][k], acc[ai][bj][m][n], 0, 0, 0); __builtin_amdgcn_s_setprio(0); } while (0)
; #define PG8_WAIT_V(n) asm volatile("s_waitcnt vmcnt(" #n ")" ::: "memory")
; #define PG8_WAIT_L(n) asm volatile("s_waitcnt lgkmcnt(" #n ")" ::: "memory")
; #define PG8_BAR __builtin_amdgcn_s_barrier()
; #define PG8_SCHED __builtin_amdgcn_sched_barrier(0)
; template <class Epi, class Sched, bool ALIGN_EPI = false, bool SP2 = false>
; __device__ __forceinline__ void gemm_phase(PG8_LAS unsigned char* lds, const Gemm g, const Sched& S, const Epi& E) {
;     ...
;             PG8_WAIT_V(8); PG8_WAIT_L(0); PG8_BAR; PG8_MMA(1, 0, At, B0); PG8_MMA(1, 1, At, B1); PG8_BAR; PG8_SCHED;
;             PG8_LDB(B0, 1, 0); PG8_LDB(B1, 1, 1); PG8_SCHED; PG8_LDA(At, 1, 0); PG8_STAGE(PG8_SA(0, 1), a2 + hstepA, voffA);
;             PG8_WAIT_V(8); PG8_WAIT_L(0); PG8_BAR; PG8_MMA(0, 0, At, B0); PG8_MMA(0, 1, At, B1); PG8_BAR; PG8_SCHED;
	s_setprio 1
	s_waitcnt lgkmcnt(0)
	v_mfma_f32_16x16x32_bf16 v[64:67], v[52:55], v[174:177], v[64:67]
	v_mfma_f32_16x16x32_bf16 v[60:63], v[100:103], v[174:177], v[60:63]
	v_mfma_f32_16x16x32_bf16 v[44:47], v[52:55], v[182:185], v[44:47]
	v_mfma_f32_16x16x32_bf16 v[40:43], v[100:103], v[182:185], v[40:43]
	v_mfma_f32_16x16x32_bf16 v[28:31], v[52:55], v[196:199], v[28:31]
	v_mfma_f32_16x16x32_bf16 v[24:27], v[100:103], v[196:199], v[24:27]
	v_mfma_f32_16x16x32_bf16 v[12:15], v[52:55], v[204:207], v[12:15]
	v_mfma_f32_16x16x32_bf16 v[8:11], v[100:103], v[204:207], v[8:11]
	v_mfma_f32_16x16x32_bf16 v[64:67], v[92:95], v[178:181], v[64:67]
	v_mfma_f32_16x16x32_bf16 v[60:63], v[108:111], v[178:181], v[60:63]
	v_mfma_f32_16x16x32_bf16 v[44:47], v[92:95], v[192:195], v[44:47]
	v_mfma_f32_16x16x32_bf16 v[40:43], v[108:111], v[192:195], v[40:43]
	v_mfma_f32_16x16x32_bf16 v[28:31], v[92:95], v[200:203], v[28:31]
	v_mfma_f32_16x16x32_bf16 v[24:27], v[108:111], v[200:203], v[24:27]
	v_mfma_f32_16x16x32_bf16 v[12:15], v[92:95], v[208:211], v[12:15]
	v_mfma_f32_16x16x32_bf16 v[8:11], v[108:111], v[208:211], v[8:11]
	s_setprio 0
	s_setprio 1
	v_mfma_f32_16x16x32_bf16 v[48:51], v[164:167], v[174:177], v[48:51]
	v_mfma_f32_16x16x32_bf16 v[36:39], v[156:159], v[182:185], v[36:39]
	v_mfma_f32_16x16x32_bf16 v[32:35], v[164:167], v[182:185], v[32:35]
	v_mfma_f32_16x16x32_bf16 v[20:23], v[156:159], v[196:199], v[20:23]
	v_mfma_f32_16x16x32_bf16 v[16:19], v[164:167], v[196:199], v[16:19]
	v_mfma_f32_16x16x32_bf16 v[4:7], v[156:159], v[204:207], v[4:7]
	v_mfma_f32_16x16x32_bf16 v[0:3], v[164:167], v[204:207], v[0:3]
	v_mfma_f32_16x16x32_bf16 v[52:55], v[156:159], v[174:177], v[56:59]
	v_mfma_f32_16x16x32_bf16 v[48:51], v[168:171], v[178:181], v[48:51]
	v_mfma_f32_16x16x32_bf16 v[36:39], v[160:163], v[192:195], v[36:39]
	v_mfma_f32_16x16x32_bf16 v[32:35], v[168:171], v[192:195], v[32:35]
	v_mfma_f32_16x16x32_bf16 v[20:23], v[160:163], v[200:203], v[20:23]
	v_mfma_f32_16x16x32_bf16 v[16:19], v[168:171], v[200:203], v[16:19]
	v_mfma_f32_16x16x32_bf16 v[4:7], v[160:163], v[208:211], v[4:7]
	v_mfma_f32_16x16x32_bf16 v[0:3], v[168:171], v[208:211], v[0:3]
	v_mfma_f32_16x16x32_bf16 v[52:55], v[160:163], v[178:181], v[52:55]
	s_setprio 0
	s_barrier
	s_add_i32 s62, 0, 0x18000
	s_add_i32 s63, 0, 0x1c000
	v_add_u32_e32 v108, s62, v153
	v_add_u32_e32 v168, s63, v153
	ds_read_b128 v[56:59], v108
	ds_read_b128 v[92:95], v108 offset:1024
	ds_read_b128 v[100:103], v108 offset:2048
	ds_read_b128 v[108:111], v108 offset:3072
	ds_read_b128 v[156:159], v168
	ds_read_b128 v[160:163], v168 offset:1024
	ds_read_b128 v[164:167], v168 offset:2048
	ds_read_b128 v[168:171], v168 offset:3072
	s_add_u32 s34, s34, 0x100000
	s_addc_u32 s35, s35, 0
	s_mov_b32 m0, s40
	ds_read_b128 v[174:177], v155 offset:32768
	ds_read_b128 v[178:181], v155 offset:33792
	ds_read_b128 v[182:185], v155 offset:34816
	ds_read_b128 v[192:195], v155 offset:35840
	ds_read_b128 v[196:199], v155 offset:36864
	ds_read_b128 v[200:203], v155 offset:37888
	ds_read_b128 v[204:207], v155 offset:38912
	ds_read_b128 v[208:211], v155 offset:39936
	global_load_lds_dwordx4 v172, s[34:35]
	v_lshl_add_u64 v[216:217], s[34:35], 0, v[144:145]
	s_mov_b32 m0, s41
	s_nop 0
	global_load_lds_dwordx4 v[216:217], off
	s_waitcnt vmcnt(8)
	s_waitcnt lgkmcnt(0)
	s_barrier
	s_setprio 1
	s_waitcnt lgkmcnt(0)
	v_mfma_f32_16x16x32_bf16 v[140:143], v[56:59], v[174:177], v[140:143]
	v_mfma_f32_16x16x32_bf16 v[136:139], v[100:103], v[174:177], v[136:139]
	v_mfma_f32_16x16x32_bf16 v[124:127], v[56:59], v[182:185], v[124:127]
	v_mfma_f32_16x16x32_bf16 v[120:123], v[100:103], v[182:185], v[120:123]
	v_mfma_f32_16x16x32_bf16 v[104:107], v[56:59], v[196:199], v[104:107]
	v_mfma_f32_16x16x32_bf16 v[96:99], v[100:103], v[196:199], v[96:99]
	v_mfma_f32_16x16x32_bf16 v[80:83], v[56:59], v[204:207], v[80:83]
	v_mfma_f32_16x16x32_bf16 v[76:79], v[100:103], v[204:207], v[76:79]
	v_mfma_f32_16x16x32_bf16 v[140:143], v[92:95], v[178:181], v[140:143]
	v_mfma_f32_16x16x32_bf16 v[136:139], v[108:111], v[178:181], v[136:139]
	v_mfma_f32_16x16x32_bf16 v[124:127], v[92:95], v[192:195], v[124:127]
	v_mfma_f32_16x16x32_bf16 v[120:123], v[108:111], v[192:195], v[120:123]
	v_mfma_f32_16x16x32_bf16 v[104:107], v[92:95], v[200:203], v[104:107]
	v_mfma_f32_16x16x32_bf16 v[96:99], v[108:111], v[200:203], v[96:99]
	v_mfma_f32_16x16x32_bf16 v[80:83], v[92:95], v[208:211], v[80:83]
	v_mfma_f32_16x16x32_bf16 v[76:79], v[108:111], v[208:211], v[76:79]
	s_setprio 0
	s_setprio 1
	v_mfma_f32_16x16x32_bf16 v[132:135], v[156:159], v[174:177], v[132:135]
	v_mfma_f32_16x16x32_bf16 v[128:131], v[164:167], v[174:177], v[128:131]
	v_mfma_f32_16x16x32_bf16 v[116:119], v[156:159], v[182:185], v[116:119]
	v_mfma_f32_16x16x32_bf16 v[112:115], v[164:167], v[182:185], v[112:115]
	v_mfma_f32_16x16x32_bf16 v[88:91], v[156:159], v[196:199], v[88:91]
	v_mfma_f32_16x16x32_bf16 v[84:87], v[164:167], v[196:199], v[84:87]
	v_mfma_f32_16x16x32_bf16 v[72:75], v[156:159], v[204:207], v[72:75]
	v_mfma_f32_16x16x32_bf16 v[68:71], v[164:167], v[204:207], v[68:71]
	v_mfma_f32_16x16x32_bf16 v[132:135], v[160:163], v[178:181], v[132:135]
	v_mfma_f32_16x16x32_bf16 v[128:131], v[168:171], v[178:181], v[128:131]
	v_mfma_f32_16x16x32_bf16 v[116:119], v[160:163], v[192:195], v[116:119]
	v_mfma_f32_16x16x32_bf16 v[112:115], v[168:171], v[192:195], v[112:115]
	v_mfma_f32_16x16x32_bf16 v[88:91], v[160:163], v[200:203], v[88:91]
	v_mfma_f32_16x16x32_bf16 v[84:87], v[168:171], v[200:203], v[84:87]
	v_mfma_f32_16x16x32_bf16 v[72:75], v[160:163], v[208:211], v[72:75]
	v_mfma_f32_16x16x32_bf16 v[68:71], v[168:171], v[208:211], v[68:71]
	s_setprio 0
	s_barrier
; #define PG8_STAGE(bufoff, gbase, voff) do { _Pragma("unroll") for (int _i = 0; _i < 2; ++_i) \
;         __builtin_amdgcn_global_load_lds((const unsigned*)((const char*)(gbase) + (voff)[_i]), (PG8_LAS unsigned*)(lds + (bufoff) + ldsw + _i * 8192), 16, 0, 0); } while (0)
; #define PG8_LDA(dst, b, h) do { _Pragma("unroll") for (int m = 0; m < 4; ++m) _Pragma("unroll") for (int k = 0; k < 2; ++k) dst[m][k] = *(const PG8_LAS bf16x8*)(lds + PG8_SA(b, h) + aoff + m * 2048 + k * 1024); } while (0)
; #define PG8_MMA(ai, bj, At, Bt) do { __builtin_amdgcn_s_setprio(1); _Pragma("unroll") for (int m = 0; m < 4; ++m) _Pragma("unroll") for (int n = 0; n < 2; ++n) _Pragma("unroll") for (int k = 0; k < 2; ++k) \
;         acc[ai][bj][m][n] = __builtin_amdgcn_mfma_f32_16x16x32_bf16(Bt[n][k], At[m][k], acc[ai][bj][m][n], 0, 0, 0); __builtin_amdgcn_s_setprio(0); } while (0)
; #define PG8_WAIT_V(n) asm volatile("s_waitcnt vmcnt(" #n ")" ::: "memory")
; #define PG8_WAIT_L(n) asm volatile("s_waitcnt lgkmcnt(" #n ")" ::: "memory")
; #define PG8_BAR __builtin_amdgcn_s_barrier()
; #define PG8_SCHED __builtin_amdgcn_sched_barrier(0)
; template <class Epi, class Sched, bool ALIGN_EPI = false, bool SP2 = false>
; __device__ __forceinline__ void gemm_phase(PG8_LAS unsigned char* lds, const Gemm g, const Sched& S, const Epi& E) {
;     ...
;             PG8_LDA(At, 1, 1); PG8_STAGE(PG8_SB(1, 0), b3, voffB); PG8_STAGE(PG8_SB(1, 1), b3 + hstepB, voffB); PG8_STAGE(PG8_SA(1, 0), a3, voffA);
;             PG8_WAIT_V(8); PG8_WAIT_L(0); PG8_BAR; PG8_MMA(1, 0, At, B0); PG8_MMA(1, 1, At, B1); PG8_BAR; PG8_SCHED;
	s_add_i32 s34, s62, s37
	v_lshl_add_u64 v[150:151], v[150:151], 0, s[80:81]
	s_mov_b32 m0, s34
	ds_read_b128 v[174:177], v155 offset:49152
	ds_read_b128 v[178:181], v155 offset:50176
	ds_read_b128 v[182:185], v155 offset:51200
	ds_read_b128 v[192:195], v155 offset:52224
	ds_read_b128 v[196:199], v155 offset:53248
	ds_read_b128 v[200:203], v155 offset:54272
	ds_read_b128 v[204:207], v155 offset:55296
	ds_read_b128 v[208:211], v155 offset:56320
	global_load_lds_dwordx4 v[150:151], off
	s_add_i32 m0, s34, 0x2000
	s_add_u32 s30, s30, 0x100080
	v_lshl_add_u64 v[150:151], v[186:187], 0, s[80:81]
	s_addc_u32 s31, s31, 0
	s_add_i32 s34, s63, s37
	global_load_lds_dwordx4 v[150:151], off
	s_mov_b32 m0, s34
	s_nop 0
	global_load_lds_dwordx4 v172, s[30:31]
	s_add_i32 m0, s34, 0x2000
	s_nop 0
	global_load_lds_dwordx4 v144, s[30:31]
	v_lshl_add_u64 v[150:151], v[212:213], 0, s[80:81]
	s_mov_b32 m0, s50
	s_nop 0
	global_load_lds_dwordx4 v[150:151], off
	v_lshl_add_u64 v[150:151], v[214:215], 0, s[80:81]
	s_mov_b32 m0, s51
	s_nop 0
	global_load_lds_dwordx4 v[150:151], off
	s_waitcnt vmcnt(8)
	s_waitcnt lgkmcnt(0)
	s_barrier
	s_setprio 1
	s_waitcnt lgkmcnt(0)
	v_mfma_f32_16x16x32_bf16 v[64:67], v[56:59], v[174:177], v[64:67]
	v_mfma_f32_16x16x32_bf16 v[60:63], v[100:103], v[174:177], v[60:63]
	v_mfma_f32_16x16x32_bf16 v[44:47], v[56:59], v[182:185], v[44:47]
	v_mfma_f32_16x16x32_bf16 v[40:43], v[100:103], v[182:185], v[40:43]
	v_mfma_f32_16x16x32_bf16 v[28:31], v[56:59], v[196:199], v[28:31]
	v_mfma_f32_16x16x32_bf16 v[24:27], v[100:103], v[196:199], v[24:27]
	v_mfma_f32_16x16x32_bf16 v[12:15], v[56:59], v[204:207], v[12:15]
	v_mfma_f32_16x16x32_bf16 v[8:11], v[100:103], v[204:207], v[8:11]
	v_mfma_f32_16x16x32_bf16 v[64:67], v[92:95], v[178:181], v[64:67]
	v_mfma_f32_16x16x32_bf16 v[60:63], v[108:111], v[178:181], v[60:63]
	v_mfma_f32_16x16x32_bf16 v[44:47], v[92:95], v[192:195], v[44:47]
	v_mfma_f32_16x16x32_bf16 v[40:43], v[108:111], v[192:195], v[40:43]
	v_mfma_f32_16x16x32_bf16 v[28:31], v[92:95], v[200:203], v[28:31]
	v_mfma_f32_16x16x32_bf16 v[24:27], v[108:111], v[200:203], v[24:27]
	v_mfma_f32_16x16x32_bf16 v[12:15], v[92:95], v[208:211], v[12:15]
	v_mfma_f32_16x16x32_bf16 v[8:11], v[108:111], v[208:211], v[8:11]
	s_setprio 0
	s_setprio 1
	v_mfma_f32_16x16x32_bf16 v[52:55], v[156:159], v[174:177], v[52:55]
	v_mfma_f32_16x16x32_bf16 v[48:51], v[164:167], v[174:177], v[48:51]
	v_mfma_f32_16x16x32_bf16 v[36:39], v[156:159], v[182:185], v[36:39]
	v_mfma_f32_16x16x32_bf16 v[32:35], v[164:167], v[182:185], v[32:35]
	v_mfma_f32_16x16x32_bf16 v[20:23], v[156:159], v[196:199], v[20:23]
	v_mfma_f32_16x16x32_bf16 v[16:19], v[164:167], v[196:199], v[16:19]
	v_mfma_f32_16x16x32_bf16 v[4:7], v[156:159], v[204:207], v[4:7]
	v_mfma_f32_16x16x32_bf16 v[0:3], v[164:167], v[204:207], v[0:3]
	v_mfma_f32_16x16x32_bf16 v[56:59], v[160:163], v[178:181], v[52:55]
	v_mfma_f32_16x16x32_bf16 v[48:51], v[168:171], v[178:181], v[48:51]
	v_mfma_f32_16x16x32_bf16 v[36:39], v[160:163], v[192:195], v[36:39]
	v_mfma_f32_16x16x32_bf16 v[32:35], v[168:171], v[192:195], v[32:35]
	v_mfma_f32_16x16x32_bf16 v[20:23], v[160:163], v[200:203], v[20:23]
	v_mfma_f32_16x16x32_bf16 v[16:19], v[168:171], v[200:203], v[16:19]
	v_mfma_f32_16x16x32_bf16 v[4:7], v[160:163], v[208:211], v[4:7]
	v_mfma_f32_16x16x32_bf16 v[0:3], v[168:171], v[208:211], v[0:3]
	s_setprio 0
	s_barrier
	s_add_i32 s61, s61, 2
	s_add_u32 s28, s28, 0x100
	s_addc_u32 s29, s29, 0
	s_add_u32 s59, s59, 0x100
	s_addc_u32 s60, s60, 0
	s_cmp_gt_u32 s61, 61
	s_cbranch_scc0 .LBB0_1950
	s_and_b64 vcc, exec, s[12:13]
	s_cbranch_vccz .LBB0_1953
	s_barrier

; #define PG8_STAGE(bufoff, gbase, voff) do { _Pragma("unroll") for (int _i = 0; _i < 2; ++_i) \
;         __builtin_amdgcn_global_load_lds((const unsigned*)((const char*)(gbase) + (voff)[_i]), (PG8_LAS unsigned*)(lds + (bufoff) + ldsw + _i * 8192), 16, 0, 0); } while (0)
; #define PG8_LDA(dst, b, h) do { _Pragma("unroll") for (int m = 0; m < 4; ++m) _Pragma("unroll") for (int k = 0; k < 2; ++k) dst[m][k] = *(const PG8_LAS bf16x8*)(lds + PG8_SA(b, h) + aoff + m * 2048 + k * 1024); } while (0)
; #define PG8_LDB(dst, b, h) do { _Pragma("unroll") for (int n = 0; n < 2; ++n) _Pragma("unroll") for (int k = 0; k < 2; ++k) dst[n][k] = *(const PG8_LAS bf16x8*)(lds + PG8_SB(b, h) + boff + n * 2048 + k * 1024); } while (0)
; #define PG8_MMA(ai, bj, At, Bt) do { __builtin_amdgcn_s_setprio(1); _Pragma("unroll") for (int m = 0; m < 4; ++m) _Pragma("unroll") for (int n = 0; n < 2; ++n) _Pragma("unroll") for (int k = 0; k < 2; ++k) \
;         acc[ai][bj][m][n] = __builtin_amdgcn_mfma_f32_16x16x32_bf16(Bt[n][k], At[m][k], acc[ai][bj][m][n], 0, 0, 0); __builtin_amdgcn_s_setprio(0); } while (0)
; #define PG8_WAIT_V(n) asm volatile("s_waitcnt vmcnt(" #n ")" ::: "memory")
; #define PG8_WAIT_L(n) asm volatile("s_waitcnt lgkmcnt(" #n ")" ::: "memory")
; template <class Epi, class Sched, bool ALIGN_EPI = false, bool SP2 = false>
; __device__ __forceinline__ void gemm_phase(PG8_LAS unsigned char* lds, const Gemm g, const Sched& S, const Epi& E) {
;     ...
;             const bool last = (t == nt - 2);
;             const char* a1 = cA + (size_t)(t + 1) * kstep;
;             const char* a2 = last ? nA : cA + (size_t)(t + 2) * kstep; const char* b2 = last ? nB : cB + (size_t)(t + 2) * kstep;
;             const char* a3 = a2 + kstep; const char* b3 = b2 + kstep;
;             if (last && has_next) S.a_ready(nxt);
;             if constexpr (SP2) {
;             PG8_LDB(B0, 0, 0); PG8_LDB(B1, 0, 1); PG8_SCHED; PG8_LDA(At, 0, 0); PG8_STAGE(PG8_SA(1, 1), a1 + hstepA, voffA);
;             PG8_WAIT_V(8); PG8_WAIT_L(0); PG8_BAR; PG8_MMA(0, 0, At, B0); PG8_MMA(0, 1, At, B1); PG8_BAR; PG8_SCHED;
;             PG8_LDA(At, 0, 1); PG8_STAGE(PG8_SB(0, 0), b2, voffB); PG8_STAGE(PG8_SB(0, 1), b2 + hstepB, voffB); PG8_STAGE(PG8_SA(0, 0), a2, voffA);
;             PG8_WAIT_V(8); PG8_WAIT_L(0); PG8_BAR; PG8_MMA(1, 0, At, B0); PG8_MMA(1, 1, At, B1); PG8_BAR; PG8_SCHED;
.LBB0_1972:
	s_add_u32 s26, s24, 0xfff00080
	s_addc_u32 s27, s25, -1
	s_add_i32 s49, 0, 0x10000
	s_cmp_eq_u32 s47, 4
	s_cselect_b32 s29, s15, s27
	s_cselect_b32 s28, s14, s26
	s_cselect_b32 s27, s21, s23
	s_cselect_b32 s26, s20, s17
	s_add_i32 s52, 0, 0x14000
	v_add_u32_e32 v124, s49, v158
	v_add_u32_e32 v156, s52, v158
	ds_read_b128 v[108:111], v124
	ds_read_b128 v[116:119], v124 offset:1024
	ds_read_b128 v[120:123], v124 offset:2048
	ds_read_b128 v[124:127], v124 offset:3072
	ds_read_b128 v[152:155], v156
	ds_read_b128 v[162:165], v156 offset:1024
	ds_read_b128 v[166:169], v156 offset:2048
	ds_read_b128 v[174:177], v156 offset:3072
	s_add_i32 m0, s34, 0xc000
	ds_read_b128 v[178:181], v161
	ds_read_b128 v[182:185], v161 offset:1024
	ds_read_b128 v[192:195], v161 offset:2048
	ds_read_b128 v[196:199], v161 offset:3072
	ds_read_b128 v[200:203], v161 offset:4096
	ds_read_b128 v[204:207], v161 offset:5120
	ds_read_b128 v[208:211], v161 offset:6144
	ds_read_b128 v[212:215], v161 offset:7168
	global_load_lds_dwordx4 v148, s[24:25]
	v_lshl_add_u64 v[156:157], s[24:25], 0, v[150:151]
	s_add_i32 m0, s34, 0xe000
	s_nop 0
	global_load_lds_dwordx4 v[156:157], off
	s_waitcnt vmcnt(8)
	s_waitcnt lgkmcnt(0)
	s_barrier
	s_setprio 1
	s_waitcnt lgkmcnt(0)
	v_mfma_f32_16x16x32_bf16 v[140:143], v[108:111], v[178:181], v[140:143]
	v_mfma_f32_16x16x32_bf16 v[136:139], v[120:123], v[178:181], v[136:139]
	v_mfma_f32_16x16x32_bf16 v[112:115], v[108:111], v[192:195], v[112:115]
	v_mfma_f32_16x16x32_bf16 v[104:107], v[120:123], v[192:195], v[104:107]
	v_mfma_f32_16x16x32_bf16 v[92:95], v[108:111], v[200:203], v[92:95]
	v_mfma_f32_16x16x32_bf16 v[88:91], v[120:123], v[200:203], v[88:91]
	v_mfma_f32_16x16x32_bf16 v[76:79], v[108:111], v[208:211], v[76:79]
	v_mfma_f32_16x16x32_bf16 v[72:75], v[120:123], v[208:211], v[72:75]
	v_mfma_f32_16x16x32_bf16 v[140:143], v[116:119], v[182:185], v[140:143]
	v_mfma_f32_16x16x32_bf16 v[136:139], v[124:127], v[182:185], v[136:139]
	v_mfma_f32_16x16x32_bf16 v[112:115], v[116:119], v[196:199], v[112:115]
	v_mfma_f32_16x16x32_bf16 v[104:107], v[124:127], v[196:199], v[104:107]
	v_mfma_f32_16x16x32_bf16 v[92:95], v[116:119], v[204:207], v[92:95]
	v_mfma_f32_16x16x32_bf16 v[88:91], v[124:127], v[204:207], v[88:91]
	v_mfma_f32_16x16x32_bf16 v[76:79], v[116:119], v[212:215], v[76:79]
	v_mfma_f32_16x16x32_bf16 v[72:75], v[124:127], v[212:215], v[72:75]
	s_setprio 0
	s_setprio 1
	v_mfma_f32_16x16x32_bf16 v[132:135], v[152:155], v[178:181], v[132:135]
	v_mfma_f32_16x16x32_bf16 v[128:131], v[166:169], v[178:181], v[128:131]
	v_mfma_f32_16x16x32_bf16 v[100:103], v[152:155], v[192:195], v[100:103]
	v_mfma_f32_16x16x32_bf16 v[96:99], v[166:169], v[192:195], v[96:99]
	v_mfma_f32_16x16x32_bf16 v[84:87], v[152:155], v[200:203], v[84:87]
	v_mfma_f32_16x16x32_bf16 v[80:83], v[166:169], v[200:203], v[80:83]
	v_mfma_f32_16x16x32_bf16 v[68:71], v[152:155], v[208:211], v[68:71]
	v_mfma_f32_16x16x32_bf16 v[64:67], v[166:169], v[208:211], v[64:67]
	v_mfma_f32_16x16x32_bf16 v[132:135], v[162:165], v[182:185], v[132:135]
	v_mfma_f32_16x16x32_bf16 v[128:131], v[174:177], v[182:185], v[128:131]
	v_mfma_f32_16x16x32_bf16 v[100:103], v[162:165], v[196:199], v[100:103]
	v_mfma_f32_16x16x32_bf16 v[96:99], v[174:177], v[196:199], v[96:99]
	v_mfma_f32_16x16x32_bf16 v[84:87], v[162:165], v[204:207], v[84:87]
	v_mfma_f32_16x16x32_bf16 v[80:83], v[174:177], v[204:207], v[80:83]
	v_mfma_f32_16x16x32_bf16 v[68:71], v[162:165], v[212:215], v[68:71]
	v_mfma_f32_16x16x32_bf16 v[64:67], v[174:177], v[212:215], v[64:67]
	s_setprio 0
	s_barrier
	s_add_i32 s49, s49, s31
	v_lshl_add_u64 v[156:157], s[26:27], 0, v[146:147]
	s_mov_b32 m0, s49
	ds_read_b128 v[178:181], v161 offset:16384
	ds_read_b128 v[182:185], v161 offset:17408
	ds_read_b128 v[192:195], v161 offset:18432
	ds_read_b128 v[196:199], v161 offset:19456
	ds_read_b128 v[200:203], v161 offset:20480
	ds_read_b128 v[204:207], v161 offset:21504
	ds_read_b128 v[208:211], v161 offset:22528
	ds_read_b128 v[212:215], v161 offset:23552
	global_load_lds_dwordx4 v[156:157], off
	s_add_i32 m0, s49, 0x2000
	s_add_u32 s50, s26, 0x100000
	v_lshl_add_u64 v[170:171], s[26:27], 0, v[144:145]
	s_addc_u32 s51, s27, 0
	s_add_i32 s49, s52, s31
	global_load_lds_dwordx4 v[170:171], off
	s_mov_b32 m0, s49
	v_lshl_add_u64 v[216:217], s[28:29], 0, v[144:145]
	global_load_lds_dwordx4 v146, s[50:51]
	s_add_i32 m0, s49, 0x2000
	s_nop 0
	global_load_lds_dwordx4 v144, s[50:51]
	v_lshl_add_u64 v[186:187], s[28:29], 0, v[146:147]
	s_mov_b32 m0, s34
	s_nop 0
	global_load_lds_dwordx4 v[186:187], off
	s_mov_b32 m0, s35
	s_nop 0
	global_load_lds_dwordx4 v[216:217], off
	s_waitcnt vmcnt(8)
	s_waitcnt lgkmcnt(0)
	s_barrier
; #define PG8_STAGE(bufoff, gbase, voff) do { _Pragma("unroll") for (int _i = 0; _i < 2; ++_i) \
;         __builtin_amdgcn_global_load_lds((const unsigned*)((const char*)(gbase) + (voff)[_i]), (PG8_LAS unsigned*)(lds + (bufoff) + ldsw + _i * 8192), 16, 0, 0); } while (0)
; #define PG8_LDA(dst, b, h) do { _Pragma("unroll") for (int m = 0; m < 4; ++m) _Pragma("unroll") for (int k = 0; k < 2; ++k) dst[m][k] = *(const PG8_LAS bf16x8*)(lds + PG8_SA(b, h) + aoff + m * 2048 + k * 1024); } while (0)
; #define PG8_LDB(dst, b, h) do { _Pragma("unroll") for (int n = 0; n < 2; ++n) _Pragma("unroll") for (int k = 0; k < 2; ++k) dst[n][k] = *(const PG8_LAS bf16x8*)(lds + PG8_SB(b, h) + boff + n * 2048 + k * 1024); } while (0)
; #define PG8_MMA(ai, bj, At, Bt) do { __builtin_amdgcn_s_setprio(1); _Pragma("unroll") for (int m = 0; m < 4; ++m) _Pragma("unroll") for (int n = 0; n < 2; ++n) _Pragma("unroll") for (int k = 0; k < 2; ++k) \
;         acc[ai][bj][m][n] = __builtin_amdgcn_mfma_f32_16x16x32_bf16(Bt[n][k], At[m][k], acc[ai][bj][m][n], 0, 0, 0); __builtin_amdgcn_s_setprio(0); } while (0)
; #define PG8_WAIT_V(n) asm volatile("s_waitcnt vmcnt(" #n ")" ::: "memory")
; #define PG8_WAIT_L(n) asm volatile("s_waitcnt lgkmcnt(" #n ")" ::: "memory")
; #define PG8_BAR __builtin_amdgcn_s_barrier()
; #define PG8_SCHED __builtin_amdgcn_sched_barrier(0)
; template <class Epi, class Sched, bool ALIGN_EPI = false, bool SP2 = false>
; __device__ __forceinline__ void gemm_phase(PG8_LAS unsigned char* lds, const Gemm g, const Sched& S, const Epi& E) {
;     ...
;             PG8_WAIT_V(8); PG8_WAIT_L(0); PG8_BAR; PG8_MMA(1, 0, At, B0); PG8_MMA(1, 1, At, B1); PG8_BAR; PG8_SCHED;
;             PG8_LDB(B0, 1, 0); PG8_LDB(B1, 1, 1); PG8_SCHED; PG8_LDA(At, 1, 0); PG8_STAGE(PG8_SA(0, 1), a2 + hstepA, voffA);
;             PG8_WAIT_V(8); PG8_WAIT_L(0); PG8_BAR; PG8_MMA(0, 0, At, B0); PG8_MMA(0, 1, At, B1); PG8_BAR; PG8_SCHED;
	s_setprio 1
	s_waitcnt lgkmcnt(0)
	v_mfma_f32_16x16x32_bf16 v[60:63], v[108:111], v[178:181], v[60:63]
	v_mfma_f32_16x16x32_bf16 v[56:59], v[120:123], v[178:181], v[56:59]
	v_mfma_f32_16x16x32_bf16 v[52:55], v[108:111], v[192:195], v[52:55]
	v_mfma_f32_16x16x32_bf16 v[40:43], v[120:123], v[192:195], v[40:43]
	v_mfma_f32_16x16x32_bf16 v[36:39], v[108:111], v[200:203], v[36:39]
	v_mfma_f32_16x16x32_bf16 v[24:27], v[120:123], v[200:203], v[24:27]
	v_mfma_f32_16x16x32_bf16 v[20:23], v[108:111], v[208:211], v[20:23]
	v_mfma_f32_16x16x32_bf16 v[8:11], v[120:123], v[208:211], v[8:11]
	v_mfma_f32_16x16x32_bf16 v[60:63], v[116:119], v[182:185], v[60:63]
	v_mfma_f32_16x16x32_bf16 v[56:59], v[124:127], v[182:185], v[56:59]
	v_mfma_f32_16x16x32_bf16 v[52:55], v[116:119], v[196:199], v[52:55]
	v_mfma_f32_16x16x32_bf16 v[40:43], v[124:127], v[196:199], v[40:43]
	v_mfma_f32_16x16x32_bf16 v[36:39], v[116:119], v[204:207], v[36:39]
	v_mfma_f32_16x16x32_bf16 v[24:27], v[124:127], v[204:207], v[24:27]
	v_mfma_f32_16x16x32_bf16 v[20:23], v[116:119], v[212:215], v[20:23]
	v_mfma_f32_16x16x32_bf16 v[8:11], v[124:127], v[212:215], v[8:11]
	s_setprio 0
	s_setprio 1
	v_mfma_f32_16x16x32_bf16 v[48:51], v[152:155], v[178:181], v[48:51]
	v_mfma_f32_16x16x32_bf16 v[44:47], v[166:169], v[178:181], v[44:47]
	v_mfma_f32_16x16x32_bf16 v[32:35], v[152:155], v[192:195], v[32:35]
	v_mfma_f32_16x16x32_bf16 v[28:31], v[166:169], v[192:195], v[28:31]
	v_mfma_f32_16x16x32_bf16 v[16:19], v[152:155], v[200:203], v[16:19]
	v_mfma_f32_16x16x32_bf16 v[12:15], v[166:169], v[200:203], v[12:15]
	v_mfma_f32_16x16x32_bf16 v[4:7], v[152:155], v[208:211], v[4:7]
	v_mfma_f32_16x16x32_bf16 v[0:3], v[166:169], v[208:211], v[0:3]
	v_mfma_f32_16x16x32_bf16 v[48:51], v[162:165], v[182:185], v[48:51]
	v_mfma_f32_16x16x32_bf16 v[44:47], v[174:177], v[182:185], v[44:47]
	v_mfma_f32_16x16x32_bf16 v[32:35], v[162:165], v[196:199], v[32:35]
	v_mfma_f32_16x16x32_bf16 v[28:31], v[174:177], v[196:199], v[28:31]
	v_mfma_f32_16x16x32_bf16 v[16:19], v[162:165], v[204:207], v[16:19]
	v_mfma_f32_16x16x32_bf16 v[12:15], v[174:177], v[204:207], v[12:15]
	v_mfma_f32_16x16x32_bf16 v[4:7], v[162:165], v[212:215], v[4:7]
	v_mfma_f32_16x16x32_bf16 v[0:3], v[174:177], v[212:215], v[0:3]
	s_setprio 0
	s_barrier
	s_add_i32 s49, 0, 0x18000
	s_add_i32 s50, 0, 0x1c000
	v_add_u32_e32 v124, s49, v158
	v_add_u32_e32 v172, s50, v158
	ds_read_b128 v[108:111], v124
	ds_read_b128 v[116:119], v124 offset:1024
	ds_read_b128 v[120:123], v124 offset:2048
	ds_read_b128 v[124:127], v124 offset:3072
	ds_read_b128 v[152:155], v172
	ds_read_b128 v[162:165], v172 offset:1024
	ds_read_b128 v[166:169], v172 offset:2048
	ds_read_b128 v[174:177], v172 offset:3072
	s_add_u32 s28, s28, 0x100000
	s_addc_u32 s29, s29, 0
	s_mov_b32 m0, s36
	ds_read_b128 v[178:181], v161 offset:32768
	ds_read_b128 v[182:185], v161 offset:33792
	ds_read_b128 v[192:195], v161 offset:34816
	ds_read_b128 v[196:199], v161 offset:35840
	ds_read_b128 v[200:203], v161 offset:36864
	ds_read_b128 v[204:207], v161 offset:37888
	ds_read_b128 v[208:211], v161 offset:38912
	ds_read_b128 v[212:215], v161 offset:39936
	global_load_lds_dwordx4 v146, s[28:29]
	v_lshl_add_u64 v[218:219], s[28:29], 0, v[144:145]
	s_mov_b32 m0, s37
	s_nop 0
	global_load_lds_dwordx4 v[218:219], off
	s_waitcnt vmcnt(8)
	s_waitcnt lgkmcnt(0)
	s_barrier
	s_setprio 1
	s_waitcnt lgkmcnt(0)
	v_mfma_f32_16x16x32_bf16 v[140:143], v[108:111], v[178:181], v[140:143]
	v_mfma_f32_16x16x32_bf16 v[136:139], v[120:123], v[178:181], v[136:139]
	v_mfma_f32_16x16x32_bf16 v[112:115], v[108:111], v[192:195], v[112:115]
	v_mfma_f32_16x16x32_bf16 v[104:107], v[120:123], v[192:195], v[104:107]
	v_mfma_f32_16x16x32_bf16 v[92:95], v[108:111], v[200:203], v[92:95]
	v_mfma_f32_16x16x32_bf16 v[88:91], v[120:123], v[200:203], v[88:91]
	v_mfma_f32_16x16x32_bf16 v[76:79], v[108:111], v[208:211], v[76:79]
	v_mfma_f32_16x16x32_bf16 v[72:75], v[120:123], v[208:211], v[72:75]
	v_mfma_f32_16x16x32_bf16 v[140:143], v[116:119], v[182:185], v[140:143]
	v_mfma_f32_16x16x32_bf16 v[136:139], v[124:127], v[182:185], v[136:139]
	v_mfma_f32_16x16x32_bf16 v[112:115], v[116:119], v[196:199], v[112:115]
	v_mfma_f32_16x16x32_bf16 v[104:107], v[124:127], v[196:199], v[104:107]
	v_mfma_f32_16x16x32_bf16 v[92:95], v[116:119], v[204:207], v[92:95]
	v_mfma_f32_16x16x32_bf16 v[88:91], v[124:127], v[204:207], v[88:91]
	v_mfma_f32_16x16x32_bf16 v[76:79], v[116:119], v[212:215], v[76:79]
	v_mfma_f32_16x16x32_bf16 v[72:75], v[124:127], v[212:215], v[72:75]
	s_setprio 0
	s_setprio 1
	v_mfma_f32_16x16x32_bf16 v[132:135], v[152:155], v[178:181], v[132:135]
	v_mfma_f32_16x16x32_bf16 v[128:131], v[166:169], v[178:181], v[128:131]
	v_mfma_f32_16x16x32_bf16 v[100:103], v[152:155], v[192:195], v[100:103]
	v_mfma_f32_16x16x32_bf16 v[96:99], v[166:169], v[192:195], v[96:99]
	v_mfma_f32_16x16x32_bf16 v[84:87], v[152:155], v[200:203], v[84:87]
	v_mfma_f32_16x16x32_bf16 v[80:83], v[166:169], v[200:203], v[80:83]
	v_mfma_f32_16x16x32_bf16 v[68:71], v[152:155], v[208:211], v[68:71]
	v_mfma_f32_16x16x32_bf16 v[64:67], v[166:169], v[208:211], v[64:67]
	v_mfma_f32_16x16x32_bf16 v[132:135], v[162:165], v[182:185], v[132:135]
	v_mfma_f32_16x16x32_bf16 v[128:131], v[174:177], v[182:185], v[128:131]
	v_mfma_f32_16x16x32_bf16 v[100:103], v[162:165], v[196:199], v[100:103]
	v_mfma_f32_16x16x32_bf16 v[96:99], v[174:177], v[196:199], v[96:99]
	v_mfma_f32_16x16x32_bf16 v[84:87], v[162:165], v[204:207], v[84:87]
	v_mfma_f32_16x16x32_bf16 v[80:83], v[174:177], v[204:207], v[80:83]
	v_mfma_f32_16x16x32_bf16 v[68:71], v[162:165], v[212:215], v[68:71]
	v_mfma_f32_16x16x32_bf16 v[64:67], v[174:177], v[212:215], v[64:67]
	s_setprio 0
	s_barrier
; #define PG8_STAGE(bufoff, gbase, voff) do { _Pragma("unroll") for (int _i = 0; _i < 2; ++_i) \
;         __builtin_amdgcn_global_load_lds((const unsigned*)((const char*)(gbase) + (voff)[_i]), (PG8_LAS unsigned*)(lds + (bufoff) + ldsw + _i * 8192), 16, 0, 0); } while (0)
; #define PG8_LDA(dst, b, h) do { _Pragma("unroll") for (int m = 0; m < 4; ++m) _Pragma("unroll") for (int k = 0; k < 2; ++k) dst[m][k] = *(const PG8_LAS bf16x8*)(lds + PG8_SA(b, h) + aoff + m * 2048 + k * 1024); } while (0)
; #define PG8_MMA(ai, bj, At, Bt) do { __builtin_amdgcn_s_setprio(1); _Pragma("unroll") for (int m = 0; m < 4; ++m) _Pragma("unroll") for (int n = 0; n < 2; ++n) _Pragma("unroll") for (int k = 0; k < 2; ++k) \
;         acc[ai][bj][m][n] = __builtin_amdgcn_mfma_f32_16x16x32_bf16(Bt[n][k], At[m][k], acc[ai][bj][m][n], 0, 0, 0); __builtin_amdgcn_s_setprio(0); } while (0)
; #define PG8_WAIT_V(n) asm volatile("s_waitcnt vmcnt(" #n ")" ::: "memory")
; #define PG8_WAIT_L(n) asm volatile("s_waitcnt lgkmcnt(" #n ")" ::: "memory")
; #define PG8_BAR __builtin_amdgcn_s_barrier()
; #define PG8_SCHED __builtin_amdgcn_sched_barrier(0)
; template <class Epi, class Sched, bool ALIGN_EPI = false, bool SP2 = false>
; __device__ __forceinline__ void gemm_phase(PG8_LAS unsigned char* lds, const Gemm g, const Sched& S, const Epi& E) {
;     ...
;             PG8_LDA(At, 1, 1); PG8_STAGE(PG8_SB(1, 0), b3, voffB); PG8_STAGE(PG8_SB(1, 1), b3 + hstepB, voffB); PG8_STAGE(PG8_SA(1, 0), a3, voffA);
;             PG8_WAIT_V(8); PG8_WAIT_L(0); PG8_BAR; PG8_MMA(1, 0, At, B0); PG8_MMA(1, 1, At, B1); PG8_BAR; PG8_SCHED;
	s_add_i32 s28, s49, s31
	v_lshl_add_u64 v[156:157], v[156:157], 0, s[80:81]
	s_mov_b32 m0, s28
	ds_read_b128 v[178:181], v161 offset:49152
	ds_read_b128 v[182:185], v161 offset:50176
	ds_read_b128 v[192:195], v161 offset:51200
	ds_read_b128 v[196:199], v161 offset:52224
	ds_read_b128 v[200:203], v161 offset:53248
	ds_read_b128 v[204:207], v161 offset:54272
	ds_read_b128 v[208:211], v161 offset:55296
	ds_read_b128 v[212:215], v161 offset:56320
	global_load_lds_dwordx4 v[156:157], off
	s_add_i32 m0, s28, 0x2000
	s_add_u32 s26, s26, 0x100080
	v_lshl_add_u64 v[156:157], v[170:171], 0, s[80:81]
	s_addc_u32 s27, s27, 0
	s_add_i32 s28, s50, s31
	global_load_lds_dwordx4 v[156:157], off
	s_mov_b32 m0, s28
	s_nop 0
	global_load_lds_dwordx4 v146, s[26:27]
	s_add_i32 m0, s28, 0x2000
	s_nop 0
	global_load_lds_dwordx4 v144, s[26:27]
	v_lshl_add_u64 v[156:157], v[186:187], 0, s[80:81]
	s_mov_b32 m0, s2
	s_nop 0
	global_load_lds_dwordx4 v[156:157], off
	v_lshl_add_u64 v[156:157], v[216:217], 0, s[80:81]
	s_mov_b32 m0, s38
	s_nop 0
	global_load_lds_dwordx4 v[156:157], off
	s_waitcnt vmcnt(8)
	s_waitcnt lgkmcnt(0)
	s_barrier
	s_setprio 1
	s_waitcnt lgkmcnt(0)
	v_mfma_f32_16x16x32_bf16 v[60:63], v[108:111], v[178:181], v[60:63]
	v_mfma_f32_16x16x32_bf16 v[56:59], v[120:123], v[178:181], v[56:59]
	v_mfma_f32_16x16x32_bf16 v[52:55], v[108:111], v[192:195], v[52:55]
	v_mfma_f32_16x16x32_bf16 v[40:43], v[120:123], v[192:195], v[40:43]
	v_mfma_f32_16x16x32_bf16 v[36:39], v[108:111], v[200:203], v[36:39]
	v_mfma_f32_16x16x32_bf16 v[24:27], v[120:123], v[200:203], v[24:27]
	v_mfma_f32_16x16x32_bf16 v[20:23], v[108:111], v[208:211], v[20:23]
	v_mfma_f32_16x16x32_bf16 v[8:11], v[120:123], v[208:211], v[8:11]
	v_mfma_f32_16x16x32_bf16 v[60:63], v[116:119], v[182:185], v[60:63]
	v_mfma_f32_16x16x32_bf16 v[56:59], v[124:127], v[182:185], v[56:59]
	v_mfma_f32_16x16x32_bf16 v[52:55], v[116:119], v[196:199], v[52:55]
	v_mfma_f32_16x16x32_bf16 v[40:43], v[124:127], v[196:199], v[40:43]
	v_mfma_f32_16x16x32_bf16 v[36:39], v[116:119], v[204:207], v[36:39]
	v_mfma_f32_16x16x32_bf16 v[24:27], v[124:127], v[204:207], v[24:27]
	v_mfma_f32_16x16x32_bf16 v[20:23], v[116:119], v[212:215], v[20:23]
	v_mfma_f32_16x16x32_bf16 v[8:11], v[124:127], v[212:215], v[8:11]
	s_setprio 0
	s_setprio 1
	v_mfma_f32_16x16x32_bf16 v[48:51], v[152:155], v[178:181], v[48:51]
	v_mfma_f32_16x16x32_bf16 v[44:47], v[166:169], v[178:181], v[44:47]
	v_mfma_f32_16x16x32_bf16 v[32:35], v[152:155], v[192:195], v[32:35]
	v_mfma_f32_16x16x32_bf16 v[28:31], v[166:169], v[192:195], v[28:31]
	v_mfma_f32_16x16x32_bf16 v[16:19], v[152:155], v[200:203], v[16:19]
	v_mfma_f32_16x16x32_bf16 v[12:15], v[166:169], v[200:203], v[12:15]
	v_mfma_f32_16x16x32_bf16 v[4:7], v[152:155], v[208:211], v[4:7]
	v_mfma_f32_16x16x32_bf16 v[0:3], v[166:169], v[208:211], v[0:3]
	v_mfma_f32_16x16x32_bf16 v[48:51], v[162:165], v[182:185], v[48:51]
	v_mfma_f32_16x16x32_bf16 v[44:47], v[174:177], v[182:185], v[44:47]
	v_mfma_f32_16x16x32_bf16 v[32:35], v[162:165], v[196:199], v[32:35]
	v_mfma_f32_16x16x32_bf16 v[28:31], v[174:177], v[196:199], v[28:31]
	v_mfma_f32_16x16x32_bf16 v[16:19], v[162:165], v[204:207], v[16:19]
	v_mfma_f32_16x16x32_bf16 v[12:15], v[174:177], v[204:207], v[12:15]
	v_mfma_f32_16x16x32_bf16 v[4:7], v[162:165], v[212:215], v[4:7]
	v_mfma_f32_16x16x32_bf16 v[0:3], v[174:177], v[212:215], v[0:3]
	s_setprio 0
	s_barrier
	s_add_i32 s47, s47, 2
	s_add_u32 s24, s24, 0x100
	s_addc_u32 s25, s25, 0
	s_add_u32 s17, s17, 0x100
	s_addc_u32 s23, s23, 0
	s_cmp_gt_u32 s47, 5
	s_cbranch_scc0 .LBB0_1972
	s_and_b64 vcc, exec, s[10:11]
	s_cbranch_vccz .LBB0_1975
	s_barrier
